# f32->bf16 RNE pairs: bit-trick sequences (lsb, add3, mask, pack) replaced by v_cvt_pk_bf16_f32 at 200 sites (GEMM SwiGLU/bf16 epilogues and others)
# speedup vs baseline: 1.0137x; 1.0127x over previous
.LBB0_358:
	s_or_b64 exec, exec, s[46:47]
	s_waitcnt vmcnt(15)
	v_add_u32_e32 v7, v18, v19
	s_waitcnt vmcnt(14)
	ds_write_b32 v7, v0 offset:2080
	s_waitcnt vmcnt(13)
	v_cndmask_b32_e64 v0, v4, 0, s[44:45]
	s_waitcnt vmcnt(12)
	v_cndmask_b32_e64 v4, v5, 0, s[44:45]
	ds_write_b32 v7, v0 offset:4160
	ds_write_b32 v7, v4 offset:6240
	s_waitcnt vmcnt(11)
	v_cndmask_b32_e64 v0, v6, 0, s[44:45]
	s_waitcnt vmcnt(10)
	v_cndmask_b32_e64 v4, v8, 0, s[44:45]
	ds_write_b32 v7, v0 offset:8320
	ds_write_b32 v7, v4 offset:10400
	s_waitcnt vmcnt(9)
	v_cndmask_b32_e64 v0, v9, 0, s[44:45]
	s_waitcnt vmcnt(8)
	v_cndmask_b32_e64 v4, v10, 0, s[44:45]
	ds_write_b32 v7, v0 offset:12480
	ds_write_b32 v7, v4 offset:14560
	v_ashrrev_i32_e32 v0, 3, v17
	v_lshlrev_b32_e32 v4, 3, v17
	v_and_b32_e32 v10, 56, v4
	v_lshlrev_b32_e32 v4, 2, v0
	v_mad_u32_u24 v8, v10, s24, v4
	s_waitcnt lgkmcnt(0)
	s_barrier
	v_add_u32_e32 v17, 0x400, v8
	v_add_u32_e32 v0, s6, v0
	ds_read2_b32 v[4:5], v8 offset1:65
	ds_read2_b32 v[6:7], v8 offset0:130 offset1:195
	ds_read2_b32 v[8:9], v17 offset0:4 offset1:69
	ds_read2_b32 v[18:19], v17 offset0:134 offset1:199
	v_ashrrev_i32_e32 v17, 31, v0
	v_mul_lo_u32 v17, s18, v17
	v_mul_lo_u32 v22, s19, v0
	v_mad_u64_u32 v[20:21], s[18:19], s18, v0, 0
	v_add3_u32 v21, v21, v17, v22
	s_lshl_b32 s10, s10, 6
	v_lshl_add_u64 v[20:21], v[20:21], 1, s[16:17]
	s_ashr_i32 s11, s10, 31
	v_lshl_add_u64 v[20:21], s[10:11], 1, v[20:21]
	v_lshlrev_b32_e32 v0, 1, v10
	v_lshl_add_u64 v[20:21], v[20:21], 0, v[0:1]
	s_waitcnt lgkmcnt(2)
	v_cvt_pk_bf16_f32 v0, v6, v7
	v_cvt_pk_bf16_f32 v4, v4, v5
	v_mov_b32_e32 v5, v0
	s_waitcnt lgkmcnt(1)
	v_cvt_pk_bf16_f32 v6, v8, v9
	s_waitcnt lgkmcnt(0)
	v_cvt_pk_bf16_f32 v7, v18, v19
	global_store_dwordx4 v[20:21], v[4:7], off
	s_waitcnt lgkmcnt(0)
	s_barrier
	s_andn2_b64 vcc, exec, s[12:13]
	s_mov_b32 s6, s7
	s_waitcnt vmcnt(8)
	v_mov_b32_e32 v7, v2
	s_waitcnt vmcnt(7)
	v_mov_b32_e32 v0, v3
	s_waitcnt vmcnt(6)
	v_mov_b32_e32 v4, v11
	s_waitcnt vmcnt(5)
	v_mov_b32_e32 v5, v12
	s_waitcnt vmcnt(4)
	v_mov_b32_e32 v6, v13
	s_waitcnt vmcnt(3)
	v_mov_b32_e32 v8, v14
	s_waitcnt vmcnt(2)
	v_mov_b32_e32 v9, v15
	s_waitcnt vmcnt(1)
	v_mov_b32_e32 v10, v16
	s_cbranch_vccz .LBB0_398

.LBB0_405:
	s_or_b64 exec, exec, s[48:49]
	v_lshl_add_u64 v[2:3], v[2:3], 0, v[12:13]
	global_load_dwordx4 v[30:33], v[2:3], off
	global_load_dwordx4 v[34:37], v[2:3], off offset:1024
	global_load_dwordx4 v[38:41], v[2:3], off offset:2048
	s_nop 0
	global_load_dwordx4 v[2:5], v[2:3], off offset:3072
	s_nop 0
	global_load_dwordx4 v[42:45], v[8:9], off
	v_min_i32_e32 v0, 0x4000, v6
	v_ashrrev_i32_e32 v0, 11, v0
	v_mul_hi_i32_i24_e32 v21, 0x9000, v0
	v_mul_i32_i24_e32 v20, 0x9000, v0
	v_lshl_add_u64 v[20:21], s[14:15], 0, v[20:21]
	v_lshl_add_u64 v[22:23], v[20:21], 0, s[38:39]
	v_lshl_add_u64 v[46:47], v[22:23], 0, v[12:13]
	global_load_dwordx4 v[46:49], v[46:47], off
	v_lshl_add_u64 v[54:55], v[20:21], 0, v[12:13]
	global_load_dwordx4 v[50:53], v[54:55], off
	s_mov_b32 s4, s42
	s_waitcnt vmcnt(6)
	v_mov_b32_e32 v56, v31
	s_waitcnt vmcnt(5)
	v_mov_b32_e32 v57, v35
	v_mov_b32_e32 v20, v30
	v_mov_b32_e32 v21, v34
	s_waitcnt vmcnt(4)
	v_mov_b32_e32 v64, v39
	s_waitcnt vmcnt(3)
	v_mov_b32_e32 v65, v3
	v_pk_mul_f32 v[56:57], v[56:57], v[56:57]
	v_mov_b32_e32 v58, v32
	v_mov_b32_e32 v59, v36
	v_mov_b32_e32 v62, v38
	v_mov_b32_e32 v63, v2
	v_pk_mul_f32 v[64:65], v[64:65], v[64:65]
	v_pk_fma_f32 v[20:21], v[20:21], v[20:21], v[56:57]
	v_mov_b32_e32 v60, v33
	v_mov_b32_e32 v61, v37
	v_mov_b32_e32 v66, v40
	v_mov_b32_e32 v67, v4
	v_pk_fma_f32 v[56:57], v[62:63], v[62:63], v[64:65]
	v_pk_fma_f32 v[20:21], v[58:59], v[58:59], v[20:21]
	v_mov_b32_e32 v68, v41
	v_mov_b32_e32 v69, v5
	v_pk_fma_f32 v[56:57], v[66:67], v[66:67], v[56:57]
	v_pk_fma_f32 v[20:21], v[60:61], v[60:61], v[20:21]
	v_pk_fma_f32 v[56:57], v[68:69], v[68:69], v[56:57]
	v_add_f32_e32 v0, v20, v21
	v_add_f32_e32 v0, v0, v56
	v_add_f32_e32 v0, v0, v57
	ds_bpermute_b32 v20, v24, v0
	s_waitcnt vmcnt(2)
	v_mov_b32_e32 v57, v44
	v_mov_b32_e32 v44, v43
	v_mov_b32_e32 v43, v32
	s_waitcnt vmcnt(1)
	v_mov_b32_e32 v32, v46
	s_waitcnt lgkmcnt(0)
	v_add_f32_e32 v0, v0, v20
	ds_bpermute_b32 v20, v25, v0
	s_waitcnt vmcnt(0)
	v_mov_b32_e32 v59, v52
	v_mov_b32_e32 v52, v51
	v_mov_b32_e32 v58, v50
	v_mov_b32_e32 v50, v34
	s_waitcnt lgkmcnt(0)
	v_add_f32_e32 v0, v0, v20
	ds_bpermute_b32 v56, v26, v0
	v_lshlrev_b64 v[20:21], 11, v[6:7]
	v_lshl_add_u64 v[20:21], v[10:11], 0, v[20:21]
	v_mov_b32_e32 v51, v36
	v_mov_b32_e32 v36, v35
	s_waitcnt lgkmcnt(0)
	v_add_f32_e32 v0, v0, v56
	ds_bpermute_b32 v7, v27, v0
	v_mov_b32_e32 v56, v42
	v_mov_b32_e32 v42, v30
	v_mov_b32_e32 v30, v31
	v_mov_b32_e32 v31, v33
	s_waitcnt lgkmcnt(0)
	v_add_f32_e32 v0, v0, v7
	ds_bpermute_b32 v7, v28, v0
	v_mov_b32_e32 v33, v48
	v_mov_b32_e32 v48, v47
	v_pk_add_f32 v[46:47], v[48:49], 1.0 op_sel_hi:[1,0]
	v_pk_add_f32 v[32:33], v[32:33], 1.0 op_sel_hi:[1,0]
	s_waitcnt lgkmcnt(0)
	v_add_f32_e32 v0, v0, v7
	ds_bpermute_b32 v7, v29, v0
	s_waitcnt lgkmcnt(0)
	v_add_f32_e32 v0, v0, v7
	v_fmamk_f32 v0, v0, 0x3a800000, v174
	v_mul_f32_e32 v7, 0x4b800000, v0
	v_cmp_gt_f32_e32 vcc, s27, v0
	s_nop 1
	v_cndmask_b32_e32 v0, v0, v7, vcc
	v_rsq_f32_e32 v0, v0
	s_nop 0
	v_mul_f32_e32 v7, 0x45800000, v0
	v_cndmask_b32_e32 v0, v0, v7, vcc
	v_pk_mul_f32 v[30:31], v[30:31], v[0:1] op_sel_hi:[1,0]
	v_pk_mul_f32 v[42:43], v[42:43], v[0:1] op_sel_hi:[1,0]
	v_pk_mul_f32 v[30:31], v[44:45], v[30:31]
	v_pk_mul_f32 v[42:43], v[56:57], v[42:43]
	v_pk_fma_f32 v[30:31], v[46:47], v[30:31], v[52:53]
	v_pk_fma_f32 v[32:33], v[32:33], v[42:43], v[58:59]
	v_cvt_pk_bf16_f32 v7, v33, v31
	v_cvt_pk_bf16_f32 v32, v32, v30
	v_mov_b32_e32 v31, v7
	v_mov_b32_e32 v30, v32
	global_store_dwordx2 v[20:21], v[30:31], off
	global_load_dwordx4 v[30:33], v[8:9], off offset:1024
	v_lshl_add_u64 v[42:43], v[22:23], 0, v[14:15]
	global_load_dwordx4 v[42:45], v[42:43], off
	s_nop 0
	global_load_dwordx4 v[46:49], v[54:55], off offset:1024
	v_pk_mul_f32 v[34:35], v[50:51], v[0:1] op_sel_hi:[1,0]
	v_pk_mul_f32 v[36:37], v[36:37], v[0:1] op_sel_hi:[1,0]
	s_waitcnt vmcnt(2)
	v_mov_b32_e32 v50, v30
	v_mov_b32_e32 v51, v32
	s_waitcnt vmcnt(1)
	v_mov_b32_e32 v52, v42
	v_mov_b32_e32 v53, v44
	v_mov_b32_e32 v32, v31
	v_mov_b32_e32 v44, v43
	s_waitcnt vmcnt(0)
	v_mov_b32_e32 v56, v46
	v_mov_b32_e32 v57, v48
	v_mov_b32_e32 v48, v47
	v_pk_mul_f32 v[30:31], v[34:35], v[50:51]
	v_pk_add_f32 v[34:35], v[52:53], 1.0 op_sel_hi:[1,0]
	v_pk_mul_f32 v[32:33], v[36:37], v[32:33]
	v_pk_add_f32 v[36:37], v[44:45], 1.0 op_sel_hi:[1,0]
	v_pk_fma_f32 v[30:31], v[30:31], v[34:35], v[56:57]
	v_pk_fma_f32 v[32:33], v[32:33], v[36:37], v[48:49]
	v_cvt_pk_bf16_f32 v7, v31, v33
	v_cvt_pk_bf16_f32 v30, v30, v32
	v_mov_b32_e32 v31, v7
	global_store_dwordx2 v[20:21], v[30:31], off offset:512
	global_load_dwordx4 v[30:33], v[8:9], off offset:2048
	v_lshl_add_u64 v[34:35], v[22:23], 0, v[16:17]
	global_load_dwordx4 v[34:37], v[34:35], off
	s_nop 0
	global_load_dwordx4 v[42:45], v[54:55], off offset:2048
	v_mov_b32_e32 v46, v38
	v_mov_b32_e32 v47, v40
	v_mov_b32_e32 v38, v39
	v_mov_b32_e32 v39, v41
	v_pk_mul_f32 v[40:41], v[46:47], v[0:1] op_sel_hi:[1,0]
	v_pk_mul_f32 v[38:39], v[38:39], v[0:1] op_sel_hi:[1,0]
	v_lshl_add_u64 v[22:23], v[22:23], 0, v[18:19]
	s_waitcnt vmcnt(2)
	v_mov_b32_e32 v46, v30
	v_mov_b32_e32 v47, v32
	s_waitcnt vmcnt(1)
	v_mov_b32_e32 v48, v34
	v_mov_b32_e32 v49, v36
	v_mov_b32_e32 v32, v31
	v_mov_b32_e32 v36, v35
	s_waitcnt vmcnt(0)
	v_mov_b32_e32 v50, v42
	v_mov_b32_e32 v51, v44
	v_mov_b32_e32 v44, v43
	v_pk_mul_f32 v[30:31], v[40:41], v[46:47]
	v_pk_add_f32 v[34:35], v[48:49], 1.0 op_sel_hi:[1,0]
	v_pk_mul_f32 v[32:33], v[38:39], v[32:33]
	v_pk_add_f32 v[36:37], v[36:37], 1.0 op_sel_hi:[1,0]
	v_pk_fma_f32 v[30:31], v[30:31], v[34:35], v[50:51]
	v_pk_fma_f32 v[32:33], v[32:33], v[36:37], v[44:45]
	v_cvt_pk_bf16_f32 v7, v31, v33
	v_cvt_pk_bf16_f32 v30, v30, v32
	v_mov_b32_e32 v31, v7
	global_store_dwordx2 v[20:21], v[30:31], off offset:1024
	global_load_dwordx4 v[30:33], v[8:9], off offset:3072
	s_nop 0
	global_load_dwordx4 v[34:37], v[22:23], off
	global_load_dwordx4 v[38:41], v[54:55], off offset:3072
	v_mov_b32_e32 v22, v2
	v_mov_b32_e32 v23, v4
	v_mov_b32_e32 v4, v3
	v_pk_mul_f32 v[2:3], v[22:23], v[0:1] op_sel_hi:[1,0]
	v_pk_mul_f32 v[4:5], v[4:5], v[0:1] op_sel_hi:[1,0]
	s_waitcnt vmcnt(1)
	v_mov_b32_e32 v42, v34
	v_mov_b32_e32 v22, v30
	v_mov_b32_e32 v23, v32
	v_mov_b32_e32 v43, v36
	v_mov_b32_e32 v32, v31
	v_mov_b32_e32 v36, v35
	s_waitcnt vmcnt(0)
	v_mov_b32_e32 v44, v38
	v_mov_b32_e32 v45, v40
	v_mov_b32_e32 v40, v39
	v_pk_mul_f32 v[2:3], v[2:3], v[22:23]
	v_pk_add_f32 v[22:23], v[42:43], 1.0 op_sel_hi:[1,0]
	v_pk_mul_f32 v[4:5], v[4:5], v[32:33]
	v_pk_add_f32 v[30:31], v[36:37], 1.0 op_sel_hi:[1,0]
	v_pk_fma_f32 v[2:3], v[2:3], v[22:23], v[44:45]
	v_pk_fma_f32 v[4:5], v[4:5], v[30:31], v[40:41]
	v_and_b32_sdwa v0, v3, v177 dst_sel:DWORD dst_unused:UNUSED_PAD src0_sel:WORD_1 src1_sel:DWORD
	v_and_b32_sdwa v22, v5, v177 dst_sel:DWORD dst_unused:UNUSED_PAD src0_sel:WORD_1 src1_sel:DWORD
	v_and_b32_sdwa v23, v4, v177 dst_sel:DWORD dst_unused:UNUSED_PAD src0_sel:WORD_1 src1_sel:DWORD
	v_and_b32_sdwa v7, v2, v177 dst_sel:DWORD dst_unused:UNUSED_PAD src0_sel:WORD_1 src1_sel:DWORD
	v_add3_u32 v0, v3, v0, s28
	v_add3_u32 v3, v5, v22, s28
	v_add3_u32 v4, v4, v23, s28
	v_add3_u32 v2, v2, v7, s28
	v_and_b32_e32 v3, 0xffff0000, v3
	v_and_b32_e32 v4, 0xffff0000, v4
	v_or_b32_sdwa v3, v3, v0 dst_sel:DWORD dst_unused:UNUSED_PAD src0_sel:DWORD src1_sel:WORD_1
	v_or_b32_sdwa v2, v4, v2 dst_sel:DWORD dst_unused:UNUSED_PAD src0_sel:DWORD src1_sel:WORD_1
	global_store_dwordx2 v[20:21], v[2:3], off offset:1536
	s_nop 0
	v_lshl_add_u32 v6, s4, 3, v6
	v_cmp_lt_i32_e32 vcc, s29, v6
	s_or_b64 s[46:47], vcc, s[46:47]
	s_andn2_b64 exec, exec, s[46:47]
	s_cbranch_execz .LBB0_410

.LBB0_466:
	s_bitcmp1_b32 s4, 0
	s_cselect_b32 s21, 0x12000, 0
	v_or_b32_e32 v184, s21, v206
	v_add_u32_e32 v185, v184, v0
	v_add_u32_e32 v184, v184, v167
	ds_read_b128 v[210:213], v185
	ds_read_b128 v[226:229], v184 offset:32768
	ds_read_b128 v[214:217], v185 offset:2048
	ds_read_b128 v[218:221], v185 offset:4096
	ds_read_b128 v[222:225], v185 offset:6144
	ds_read_b128 v[230:233], v184 offset:34816
	ds_read_b128 v[234:237], v184 offset:36864
	ds_read_b128 v[238:241], v184 offset:38912
	ds_read_b128 v[242:245], v184 offset:40960
	ds_read_b128 v[246:249], v184 offset:43008
	ds_read_b128 v[198:201], v184 offset:45056
	ds_read_b128 v[184:187], v184 offset:47104
	s_add_i32 s10, s4, 1
	s_bitcmp1_b32 s10, 0
	s_cselect_b32 s23, 0x12000, 0
	v_add_u32_e32 v171, s23, v166
	v_xor_b32_e32 v169, 64, v206
	v_add3_u32 v169, s21, v167, v169
	s_waitcnt lgkmcnt(10)
	v_mfma_f32_16x16x32_bf16 v[158:161], v[226:229], v[210:213], v[158:161]
	s_waitcnt lgkmcnt(9)
	v_mfma_f32_16x16x32_bf16 v[94:97], v[226:229], v[214:217], v[94:97]
	s_waitcnt lgkmcnt(8)
	v_mfma_f32_16x16x32_bf16 v[62:65], v[226:229], v[218:221], v[62:65]
	s_waitcnt lgkmcnt(7)
	v_mfma_f32_16x16x32_bf16 v[30:33], v[226:229], v[222:225], v[30:33]
	ds_read_b128 v[226:229], v169 offset:32768
	s_waitcnt lgkmcnt(7)
	v_mfma_f32_16x16x32_bf16 v[154:157], v[230:233], v[210:213], v[154:157]
	v_mfma_f32_16x16x32_bf16 v[90:93], v[230:233], v[214:217], v[90:93]
	v_mfma_f32_16x16x32_bf16 v[58:61], v[230:233], v[218:221], v[58:61]
	v_mfma_f32_16x16x32_bf16 v[26:29], v[230:233], v[222:225], v[26:29]
	ds_read_b128 v[230:233], v169 offset:34816
	s_waitcnt lgkmcnt(7)
	v_mfma_f32_16x16x32_bf16 v[150:153], v[234:237], v[210:213], v[150:153]
	v_mfma_f32_16x16x32_bf16 v[86:89], v[234:237], v[214:217], v[86:89]
	v_mfma_f32_16x16x32_bf16 v[54:57], v[234:237], v[218:221], v[54:57]
	v_mfma_f32_16x16x32_bf16 v[22:25], v[234:237], v[222:225], v[22:25]
	ds_read_b128 v[234:237], v169 offset:36864
	s_waitcnt lgkmcnt(7)
	v_mfma_f32_16x16x32_bf16 v[146:149], v[238:241], v[210:213], v[146:149]
	v_mfma_f32_16x16x32_bf16 v[82:85], v[238:241], v[214:217], v[82:85]
	v_mfma_f32_16x16x32_bf16 v[50:53], v[238:241], v[218:221], v[50:53]
	v_mfma_f32_16x16x32_bf16 v[18:21], v[238:241], v[222:225], v[18:21]
	ds_read_b128 v[238:241], v169 offset:38912
	s_waitcnt lgkmcnt(7)
	v_mfma_f32_16x16x32_bf16 v[142:145], v[242:245], v[210:213], v[142:145]
	v_mfma_f32_16x16x32_bf16 v[78:81], v[242:245], v[214:217], v[78:81]
	v_mfma_f32_16x16x32_bf16 v[46:49], v[242:245], v[218:221], v[46:49]
	v_mfma_f32_16x16x32_bf16 v[14:17], v[242:245], v[222:225], v[14:17]
	ds_read_b128 v[242:245], v169 offset:40960
	s_waitcnt lgkmcnt(7)
	v_mfma_f32_16x16x32_bf16 v[138:141], v[246:249], v[210:213], v[138:141]
	v_mfma_f32_16x16x32_bf16 v[74:77], v[246:249], v[214:217], v[74:77]
	v_mfma_f32_16x16x32_bf16 v[42:45], v[246:249], v[218:221], v[42:45]
	v_mfma_f32_16x16x32_bf16 v[10:13], v[246:249], v[222:225], v[10:13]
	ds_read_b128 v[246:249], v169 offset:43008
	s_waitcnt lgkmcnt(7)
	v_mfma_f32_16x16x32_bf16 v[102:105], v[198:201], v[210:213], v[102:105]
	v_mfma_f32_16x16x32_bf16 v[70:73], v[198:201], v[214:217], v[70:73]
	v_mfma_f32_16x16x32_bf16 v[38:41], v[198:201], v[218:221], v[38:41]
	v_mfma_f32_16x16x32_bf16 v[6:9], v[198:201], v[222:225], v[6:9]
	ds_read_b128 v[198:201], v169 offset:45056
	s_waitcnt lgkmcnt(7)
	v_mfma_f32_16x16x32_bf16 v[98:101], v[184:187], v[210:213], v[98:101]
	v_mfma_f32_16x16x32_bf16 v[66:69], v[184:187], v[214:217], v[66:69]
	v_xor_b32_e32 v169, 64, v206
	v_add3_u32 v169, s21, v0, v169
	ds_read_b128 v[210:213], v169
	ds_read_b128 v[214:217], v169 offset:2048
	v_mfma_f32_16x16x32_bf16 v[34:37], v[184:187], v[218:221], v[34:37]
	ds_read_b128 v[218:221], v169 offset:4096
	v_mfma_f32_16x16x32_bf16 v[2:5], v[184:187], v[222:225], v[2:5]
	ds_read_b128 v[222:225], v169 offset:6144
	v_xor_b32_e32 v169, 64, v206
	v_add3_u32 v169, s21, v167, v169
	ds_read_b128 v[184:187], v169 offset:47104
	s_waitcnt lgkmcnt(4)
	v_mfma_f32_16x16x32_bf16 v[158:161], v[226:229], v[210:213], v[158:161]
	s_waitcnt lgkmcnt(3)
	v_mfma_f32_16x16x32_bf16 v[94:97], v[226:229], v[214:217], v[94:97]
	s_waitcnt lgkmcnt(2)
	v_mfma_f32_16x16x32_bf16 v[62:65], v[226:229], v[218:221], v[62:65]
	s_waitcnt lgkmcnt(1)
	v_mfma_f32_16x16x32_bf16 v[30:33], v[226:229], v[222:225], v[30:33]
	s_waitcnt vmcnt(7)
	ds_write_b128 v171, v[114:117]
	v_mfma_f32_16x16x32_bf16 v[154:157], v[230:233], v[210:213], v[154:157]
	v_mfma_f32_16x16x32_bf16 v[90:93], v[230:233], v[214:217], v[90:93]
	global_load_dwordx4 v[114:117], v168, vcc offset:256
	v_mfma_f32_16x16x32_bf16 v[58:61], v[230:233], v[218:221], v[58:61]
	v_mfma_f32_16x16x32_bf16 v[26:29], v[230:233], v[222:225], v[26:29]
	s_waitcnt vmcnt(7)
	ds_write_b128 v171, v[106:109] offset:8192
	v_mfma_f32_16x16x32_bf16 v[150:153], v[234:237], v[210:213], v[150:153]
	v_mfma_f32_16x16x32_bf16 v[86:89], v[234:237], v[214:217], v[86:89]
	v_add_u32_e32 v106, s34, v168
	global_load_dwordx4 v[106:109], v106, vcc offset:256
	v_mfma_f32_16x16x32_bf16 v[54:57], v[234:237], v[218:221], v[54:57]
	v_mfma_f32_16x16x32_bf16 v[22:25], v[234:237], v[222:225], v[22:25]
	s_waitcnt vmcnt(7)
	ds_write_b128 v171, v[110:113] offset:16384
	v_mfma_f32_16x16x32_bf16 v[146:149], v[238:241], v[210:213], v[146:149]
	v_mfma_f32_16x16x32_bf16 v[82:85], v[238:241], v[214:217], v[82:85]
	v_add_u32_e32 v110, s35, v168
	global_load_dwordx4 v[110:113], v110, vcc offset:256
	v_mfma_f32_16x16x32_bf16 v[50:53], v[238:241], v[218:221], v[50:53]
	v_mfma_f32_16x16x32_bf16 v[18:21], v[238:241], v[222:225], v[18:21]
	s_waitcnt vmcnt(7)
	ds_write_b128 v171, v[126:129] offset:24576
	v_mfma_f32_16x16x32_bf16 v[142:145], v[242:245], v[210:213], v[142:145]
	v_mfma_f32_16x16x32_bf16 v[78:81], v[242:245], v[214:217], v[78:81]
	v_add_u32_e32 v126, s36, v168
	global_load_dwordx4 v[126:129], v126, vcc offset:256
	v_mfma_f32_16x16x32_bf16 v[46:49], v[242:245], v[218:221], v[46:49]
	v_mfma_f32_16x16x32_bf16 v[14:17], v[242:245], v[222:225], v[14:17]
	s_waitcnt vmcnt(7)
	ds_write_b128 v171, v[122:125] offset:32768
	v_mfma_f32_16x16x32_bf16 v[138:141], v[246:249], v[210:213], v[138:141]
	v_mfma_f32_16x16x32_bf16 v[74:77], v[246:249], v[214:217], v[74:77]
	global_load_dwordx4 v[122:125], v170, s[100:101] offset:256
	v_mfma_f32_16x16x32_bf16 v[42:45], v[246:249], v[218:221], v[42:45]
	v_mfma_f32_16x16x32_bf16 v[10:13], v[246:249], v[222:225], v[10:13]
	s_waitcnt vmcnt(7)
	ds_write_b128 v171, v[118:121] offset:40960
	v_mfma_f32_16x16x32_bf16 v[102:105], v[198:201], v[210:213], v[102:105]
	v_mfma_f32_16x16x32_bf16 v[70:73], v[198:201], v[214:217], v[70:73]
	v_add_u32_e32 v118, s34, v170
	global_load_dwordx4 v[118:121], v118, s[100:101] offset:256
	v_mfma_f32_16x16x32_bf16 v[38:41], v[198:201], v[218:221], v[38:41]
	v_mfma_f32_16x16x32_bf16 v[6:9], v[198:201], v[222:225], v[6:9]
	s_waitcnt vmcnt(7)
	ds_write_b128 v171, v[134:137] offset:49152
	s_waitcnt lgkmcnt(7)
	v_mfma_f32_16x16x32_bf16 v[98:101], v[184:187], v[210:213], v[98:101]
	v_mfma_f32_16x16x32_bf16 v[66:69], v[184:187], v[214:217], v[66:69]
	v_add_u32_e32 v134, s35, v170
	global_load_dwordx4 v[134:137], v134, s[100:101] offset:256
	v_mfma_f32_16x16x32_bf16 v[34:37], v[184:187], v[218:221], v[34:37]
	v_mfma_f32_16x16x32_bf16 v[2:5], v[184:187], v[222:225], v[2:5]
	s_waitcnt vmcnt(7)
	ds_write_b128 v171, v[130:133] offset:57344
	v_add_u32_e32 v130, s36, v170
	global_load_dwordx4 v[130:133], v130, s[100:101] offset:256
	v_add_u32_e32 v168, 0x80, v168
	v_add_u32_e32 v170, 0x80, v170
	s_waitcnt lgkmcnt(0)
	s_barrier
	s_cmp_eq_u32 s10, 16
	s_mov_b32 s4, s10
	s_cbranch_scc0 .LBB0_466
	s_waitcnt vmcnt(6)
	v_mul_f32_e32 v109, 0xbfb8aa3b, v158
	v_exp_f32_e32 v109, v109
	s_waitcnt vmcnt(5)
	v_mul_f32_e32 v111, 0xbfb8aa3b, v159
	v_exp_f32_e32 v111, v111
	v_mul_f32_e32 v115, 0xbfb8aa3b, v161
	v_add_f32_e32 v109, 1.0, v109
	v_rcp_f32_e32 v114, v109
	v_add_f32_e32 v109, 1.0, v111
	v_mul_f32_e32 v111, 0xbfb8aa3b, v160
	v_exp_f32_e32 v111, v111
	v_exp_f32_e32 v117, v115
	v_rcp_f32_e32 v116, v109
	s_waitcnt vmcnt(2)
	v_mov_b32_e32 v118, v158
	v_add_f32_e32 v109, 1.0, v111
	v_rcp_f32_e32 v115, v109
	v_add_f32_e32 v109, 1.0, v117
	v_rcp_f32_e32 v117, v109
	v_mov_b32_e32 v119, v160
	v_pk_mul_f32 v[114:115], v[118:119], v[114:115]
	v_mov_b32_e32 v118, v154
	v_mov_b32_e32 v119, v156
	v_mov_b32_e32 v160, v159
	v_pk_mul_f32 v[114:115], v[118:119], v[114:115]
	v_pk_mul_f32 v[116:117], v[160:161], v[116:117]
	v_mov_b32_e32 v156, v155
	v_pk_mul_f32 v[116:117], v[156:157], v[116:117]
	v_cvt_pk_bf16_f32 v111, v115, v117
	v_cvt_pk_bf16_f32 v114, v114, v116
	v_or_b32_e32 v106, s7, v207
	v_ashrrev_i32_e32 v106, 1, v106
	v_mov_b32_e32 v115, v111
	v_mul_f32_e32 v111, 0xbfb8aa3b, v150
	v_or_b32_e32 v108, v106, v208
	v_exp_f32_e32 v111, v111
	v_mul_f32_e32 v116, 0xbfb8aa3b, v151
	v_add_u32_e32 v110, s6, v205
	v_mov_b64_e32 v[106:107], s[14:15]
	v_ashrrev_i32_e32 v109, 31, v108
	v_exp_f32_e32 v116, v116
	v_mad_i64_i32 v[112:113], s[6:7], v110, s52, v[106:107]
	v_lshlrev_b64 v[108:109], 1, v[108:109]
	v_lshl_add_u64 v[112:113], v[112:113], 0, v[108:109]
	s_waitcnt vmcnt(0)
	global_store_dwordx2 v[112:113], v[114:115], off
	v_add_f32_e32 v111, 1.0, v111
	v_mul_f32_e32 v115, 0xbfb8aa3b, v152
	v_rcp_f32_e32 v114, v111
	v_add_f32_e32 v111, 1.0, v116
	v_exp_f32_e32 v115, v115
	v_mul_f32_e32 v116, 0xbfb8aa3b, v153
	v_exp_f32_e32 v117, v116
	v_rcp_f32_e32 v116, v111
	v_add_f32_e32 v111, 1.0, v115
	v_rcp_f32_e32 v115, v111
	v_add_f32_e32 v111, 1.0, v117
	v_rcp_f32_e32 v117, v111
	v_mov_b32_e32 v118, v150
	v_mov_b32_e32 v119, v152
	v_pk_mul_f32 v[114:115], v[118:119], v[114:115]
	v_mov_b32_e32 v118, v146
	v_mov_b32_e32 v119, v148
	v_mov_b32_e32 v152, v151
	v_pk_mul_f32 v[114:115], v[118:119], v[114:115]
	v_pk_mul_f32 v[116:117], v[152:153], v[116:117]
	v_mov_b32_e32 v148, v147
	v_pk_mul_f32 v[116:117], v[148:149], v[116:117]
	v_cvt_pk_bf16_f32 v111, v115, v117
	v_cvt_pk_bf16_f32 v114, v114, v116
	v_mov_b32_e32 v115, v111
	v_mul_f32_e32 v111, 0xbfb8aa3b, v142
	v_exp_f32_e32 v111, v111
	v_mul_f32_e32 v116, 0xbfb8aa3b, v143
	v_exp_f32_e32 v116, v116
	global_store_dwordx2 v[112:113], v[114:115], off offset:32
	v_add_f32_e32 v111, 1.0, v111
	v_mul_f32_e32 v115, 0xbfb8aa3b, v144
	v_rcp_f32_e32 v114, v111
	v_add_f32_e32 v111, 1.0, v116
	v_exp_f32_e32 v115, v115
	v_mul_f32_e32 v116, 0xbfb8aa3b, v145
	v_exp_f32_e32 v117, v116
	v_rcp_f32_e32 v116, v111
	v_add_f32_e32 v111, 1.0, v115
	v_rcp_f32_e32 v115, v111
	v_add_f32_e32 v111, 1.0, v117
	v_rcp_f32_e32 v117, v111
	v_mov_b32_e32 v118, v142
	v_mov_b32_e32 v119, v144
	v_pk_mul_f32 v[114:115], v[118:119], v[114:115]
	v_mov_b32_e32 v118, v138
	v_mov_b32_e32 v119, v140
	v_mov_b32_e32 v144, v143
	v_pk_mul_f32 v[114:115], v[118:119], v[114:115]
	v_pk_mul_f32 v[116:117], v[144:145], v[116:117]
	v_mov_b32_e32 v140, v139
	v_pk_mul_f32 v[116:117], v[140:141], v[116:117]
	v_cvt_pk_bf16_f32 v111, v115, v117
	v_cvt_pk_bf16_f32 v114, v114, v116
	v_mov_b32_e32 v115, v111
	v_mul_f32_e32 v111, 0xbfb8aa3b, v102
	v_exp_f32_e32 v111, v111
	v_mul_f32_e32 v116, 0xbfb8aa3b, v103
	v_exp_f32_e32 v116, v116
	global_store_dwordx2 v[112:113], v[114:115], off offset:64
	v_add_f32_e32 v111, 1.0, v111
	v_mul_f32_e32 v115, 0xbfb8aa3b, v104
	v_rcp_f32_e32 v114, v111
	v_add_f32_e32 v111, 1.0, v116
	v_exp_f32_e32 v115, v115
	v_mul_f32_e32 v116, 0xbfb8aa3b, v105
	v_exp_f32_e32 v117, v116
	v_rcp_f32_e32 v116, v111
	v_add_f32_e32 v111, 1.0, v115
	v_rcp_f32_e32 v115, v111
	v_add_f32_e32 v111, 1.0, v117
	v_rcp_f32_e32 v117, v111
	v_mov_b32_e32 v118, v102
	v_mov_b32_e32 v119, v104
	v_mov_b32_e32 v104, v103
	v_pk_mul_f32 v[114:115], v[118:119], v[114:115]
	v_mov_b32_e32 v119, v100
	v_pk_mul_f32 v[102:103], v[104:105], v[116:117]
	v_mov_b32_e32 v100, v99
	v_mov_b32_e32 v118, v98
	v_pk_mul_f32 v[98:99], v[100:101], v[102:103]
	v_pk_mul_f32 v[114:115], v[118:119], v[114:115]
	v_cvt_pk_bf16_f32 v100, v115, v99
	v_cvt_pk_bf16_f32 v101, v114, v98
	v_mov_b32_e32 v99, v100
	v_mov_b32_e32 v98, v101
	global_store_dwordx2 v[112:113], v[98:99], off offset:96
	v_mul_f32_e32 v99, 0xbfb8aa3b, v94
	v_exp_f32_e32 v100, v99
	v_mul_f32_e32 v99, 0xbfb8aa3b, v95
	v_mul_f32_e32 v102, 0xbfb8aa3b, v96
	v_exp_f32_e32 v101, v99
	v_exp_f32_e32 v103, v102
	v_mul_f32_e32 v102, 0xbfb8aa3b, v97
	v_exp_f32_e32 v104, v102
	v_add_f32_e32 v101, 1.0, v101
	v_add_f32_e32 v100, 1.0, v100
	v_rcp_f32_e32 v102, v101
	v_add_f32_e32 v101, 1.0, v103
	v_add_f32_e32 v103, 1.0, v104
	v_rcp_f32_e32 v100, v100
	v_rcp_f32_e32 v101, v101
	v_rcp_f32_e32 v103, v103
	v_mov_b32_e32 v104, v94
	v_mov_b32_e32 v105, v96
	v_mov_b32_e32 v96, v95
	v_pk_mul_f32 v[100:101], v[104:105], v[100:101]
	v_mov_b32_e32 v105, v92
	v_pk_mul_f32 v[94:95], v[96:97], v[102:103]
	v_mov_b32_e32 v92, v91
	v_mov_b32_e32 v104, v90
	v_pk_mul_f32 v[90:91], v[92:93], v[94:95]
	v_pk_mul_f32 v[100:101], v[104:105], v[100:101]
	v_cvt_pk_bf16_f32 v92, v101, v91
	v_cvt_pk_bf16_f32 v93, v100, v90
	v_mov_b32_e32 v91, v92
	v_mul_f32_e32 v92, 0xbfb8aa3b, v86
	v_mov_b32_e32 v90, v93
	v_exp_f32_e32 v92, v92
	v_mul_f32_e32 v93, 0xbfb8aa3b, v87
	v_or_b32_e32 v98, 16, v110
	v_exp_f32_e32 v93, v93
	v_mad_i64_i32 v[98:99], s[6:7], v98, s52, v[106:107]
	v_lshl_add_u64 v[98:99], v[98:99], 0, v[108:109]
	global_store_dwordx2 v[98:99], v[90:91], off
	v_add_f32_e32 v90, 1.0, v92
	v_mul_f32_e32 v92, 0xbfb8aa3b, v88
	v_add_f32_e32 v91, 1.0, v93
	v_exp_f32_e32 v93, v92
	v_mul_f32_e32 v92, 0xbfb8aa3b, v89
	v_exp_f32_e32 v94, v92
	v_rcp_f32_e32 v92, v91
	v_add_f32_e32 v91, 1.0, v93
	v_rcp_f32_e32 v90, v90
	v_add_f32_e32 v93, 1.0, v94
	v_rcp_f32_e32 v91, v91
	v_rcp_f32_e32 v93, v93
	v_mov_b32_e32 v94, v86
	v_mov_b32_e32 v95, v88
	v_mov_b32_e32 v88, v87
	v_pk_mul_f32 v[90:91], v[94:95], v[90:91]
	v_mov_b32_e32 v95, v84
	v_pk_mul_f32 v[86:87], v[88:89], v[92:93]
	v_mov_b32_e32 v84, v83
	v_mov_b32_e32 v94, v82
	v_pk_mul_f32 v[82:83], v[84:85], v[86:87]
	v_pk_mul_f32 v[90:91], v[94:95], v[90:91]
	v_cvt_pk_bf16_f32 v84, v91, v83
	v_cvt_pk_bf16_f32 v85, v90, v82
	v_mov_b32_e32 v83, v84
	v_mul_f32_e32 v84, 0xbfb8aa3b, v78
	v_mov_b32_e32 v82, v85
	v_exp_f32_e32 v84, v84
	v_mul_f32_e32 v85, 0xbfb8aa3b, v79
	v_exp_f32_e32 v85, v85
	global_store_dwordx2 v[98:99], v[82:83], off offset:32
	v_add_f32_e32 v82, 1.0, v84
	v_mul_f32_e32 v84, 0xbfb8aa3b, v80
	v_add_f32_e32 v83, 1.0, v85
	v_exp_f32_e32 v85, v84
	v_mul_f32_e32 v84, 0xbfb8aa3b, v81
	v_exp_f32_e32 v86, v84
	v_rcp_f32_e32 v84, v83
	v_add_f32_e32 v83, 1.0, v85
	v_rcp_f32_e32 v82, v82
	v_add_f32_e32 v85, 1.0, v86
	v_rcp_f32_e32 v83, v83
	v_rcp_f32_e32 v85, v85
	v_mov_b32_e32 v86, v78
	v_mov_b32_e32 v87, v80
	v_mov_b32_e32 v80, v79
	v_pk_mul_f32 v[82:83], v[86:87], v[82:83]
	v_mov_b32_e32 v87, v76
	v_pk_mul_f32 v[78:79], v[80:81], v[84:85]
	v_mov_b32_e32 v76, v75
	v_mov_b32_e32 v86, v74
	v_pk_mul_f32 v[74:75], v[76:77], v[78:79]
	v_pk_mul_f32 v[82:83], v[86:87], v[82:83]
	v_cvt_pk_bf16_f32 v76, v83, v75
	v_cvt_pk_bf16_f32 v77, v82, v74
	v_mov_b32_e32 v75, v76
	v_mul_f32_e32 v76, 0xbfb8aa3b, v70
	v_mov_b32_e32 v74, v77
	v_exp_f32_e32 v76, v76
	v_mul_f32_e32 v77, 0xbfb8aa3b, v71
	v_exp_f32_e32 v77, v77
	global_store_dwordx2 v[98:99], v[74:75], off offset:64
	v_add_f32_e32 v74, 1.0, v76
	v_mul_f32_e32 v76, 0xbfb8aa3b, v72
	v_add_f32_e32 v75, 1.0, v77
	v_exp_f32_e32 v77, v76
	v_mul_f32_e32 v76, 0xbfb8aa3b, v73
	v_exp_f32_e32 v78, v76
	v_rcp_f32_e32 v76, v75
	v_add_f32_e32 v75, 1.0, v77
	v_rcp_f32_e32 v74, v74
	v_add_f32_e32 v77, 1.0, v78
	v_rcp_f32_e32 v75, v75
	v_rcp_f32_e32 v77, v77
	v_mov_b32_e32 v78, v70
	v_mov_b32_e32 v79, v72
	v_mov_b32_e32 v72, v71
	v_pk_mul_f32 v[74:75], v[78:79], v[74:75]
	v_mov_b32_e32 v79, v68
	v_pk_mul_f32 v[70:71], v[72:73], v[76:77]
	v_mov_b32_e32 v68, v67
	v_mov_b32_e32 v78, v66
	v_pk_mul_f32 v[66:67], v[68:69], v[70:71]
	v_pk_mul_f32 v[74:75], v[78:79], v[74:75]
	v_cvt_pk_bf16_f32 v68, v75, v67
	v_cvt_pk_bf16_f32 v69, v74, v66
	v_mov_b32_e32 v67, v68
	v_mov_b32_e32 v66, v69
	global_store_dwordx2 v[98:99], v[66:67], off offset:96
	v_mul_f32_e32 v67, 0xbfb8aa3b, v62
	v_exp_f32_e32 v68, v67
	v_mul_f32_e32 v67, 0xbfb8aa3b, v63
	v_mul_f32_e32 v70, 0xbfb8aa3b, v64
	v_exp_f32_e32 v69, v67
	v_exp_f32_e32 v71, v70
	v_mul_f32_e32 v70, 0xbfb8aa3b, v65
	v_exp_f32_e32 v72, v70
	v_add_f32_e32 v69, 1.0, v69
	v_add_f32_e32 v68, 1.0, v68
	v_rcp_f32_e32 v70, v69
	v_add_f32_e32 v69, 1.0, v71
	v_add_f32_e32 v71, 1.0, v72
	v_rcp_f32_e32 v68, v68
	v_rcp_f32_e32 v69, v69
	v_rcp_f32_e32 v71, v71
	v_mov_b32_e32 v72, v62
	v_mov_b32_e32 v73, v64
	v_mov_b32_e32 v64, v63
	v_pk_mul_f32 v[68:69], v[72:73], v[68:69]
	v_mov_b32_e32 v73, v60
	v_pk_mul_f32 v[62:63], v[64:65], v[70:71]
	v_mov_b32_e32 v60, v59
	v_mov_b32_e32 v72, v58
	v_pk_mul_f32 v[58:59], v[60:61], v[62:63]
	v_pk_mul_f32 v[68:69], v[72:73], v[68:69]
	v_cvt_pk_bf16_f32 v60, v69, v59
	v_cvt_pk_bf16_f32 v61, v68, v58
	v_mov_b32_e32 v59, v60
	v_mul_f32_e32 v60, 0xbfb8aa3b, v54
	v_mov_b32_e32 v58, v61
	v_exp_f32_e32 v60, v60
	v_mul_f32_e32 v61, 0xbfb8aa3b, v55
	v_or_b32_e32 v66, 32, v110
	v_exp_f32_e32 v61, v61
	v_mad_i64_i32 v[66:67], s[6:7], v66, s52, v[106:107]
	v_lshl_add_u64 v[66:67], v[66:67], 0, v[108:109]
	global_store_dwordx2 v[66:67], v[58:59], off
	v_add_f32_e32 v58, 1.0, v60
	v_mul_f32_e32 v60, 0xbfb8aa3b, v56
	v_add_f32_e32 v59, 1.0, v61
	v_exp_f32_e32 v61, v60
	v_mul_f32_e32 v60, 0xbfb8aa3b, v57
	v_exp_f32_e32 v62, v60
	v_rcp_f32_e32 v60, v59
	v_add_f32_e32 v59, 1.0, v61
	v_rcp_f32_e32 v58, v58
	v_add_f32_e32 v61, 1.0, v62
	v_rcp_f32_e32 v59, v59
	v_rcp_f32_e32 v61, v61
	v_mov_b32_e32 v62, v54
	v_mov_b32_e32 v63, v56
	v_mov_b32_e32 v56, v55
	v_pk_mul_f32 v[58:59], v[62:63], v[58:59]
	v_mov_b32_e32 v63, v52
	v_pk_mul_f32 v[54:55], v[56:57], v[60:61]
	v_mov_b32_e32 v52, v51
	v_mov_b32_e32 v62, v50
	v_pk_mul_f32 v[50:51], v[52:53], v[54:55]
	v_pk_mul_f32 v[58:59], v[62:63], v[58:59]
	v_cvt_pk_bf16_f32 v52, v59, v51
	v_cvt_pk_bf16_f32 v53, v58, v50
	v_mov_b32_e32 v51, v52
	v_mul_f32_e32 v52, 0xbfb8aa3b, v46
	v_mov_b32_e32 v50, v53
	v_exp_f32_e32 v52, v52
	v_mul_f32_e32 v53, 0xbfb8aa3b, v47
	v_exp_f32_e32 v53, v53
	global_store_dwordx2 v[66:67], v[50:51], off offset:32
	v_add_f32_e32 v50, 1.0, v52
	v_mul_f32_e32 v52, 0xbfb8aa3b, v48
	v_add_f32_e32 v51, 1.0, v53
	v_exp_f32_e32 v53, v52
	v_mul_f32_e32 v52, 0xbfb8aa3b, v49
	v_exp_f32_e32 v54, v52
	v_rcp_f32_e32 v52, v51
	v_add_f32_e32 v51, 1.0, v53
	v_rcp_f32_e32 v50, v50
	v_add_f32_e32 v53, 1.0, v54
	v_rcp_f32_e32 v51, v51
	v_rcp_f32_e32 v53, v53
	v_mov_b32_e32 v54, v46
	v_mov_b32_e32 v55, v48
	v_mov_b32_e32 v48, v47
	v_pk_mul_f32 v[50:51], v[54:55], v[50:51]
	v_mov_b32_e32 v55, v44
	v_pk_mul_f32 v[46:47], v[48:49], v[52:53]
	v_mov_b32_e32 v44, v43
	v_mov_b32_e32 v54, v42
	v_pk_mul_f32 v[42:43], v[44:45], v[46:47]
	v_pk_mul_f32 v[50:51], v[54:55], v[50:51]
	v_cvt_pk_bf16_f32 v44, v51, v43
	v_cvt_pk_bf16_f32 v45, v50, v42
	v_mov_b32_e32 v43, v44
	v_mul_f32_e32 v44, 0xbfb8aa3b, v38
	v_mov_b32_e32 v42, v45
	v_exp_f32_e32 v44, v44
	v_mul_f32_e32 v45, 0xbfb8aa3b, v39
	v_exp_f32_e32 v45, v45
	global_store_dwordx2 v[66:67], v[42:43], off offset:64
	v_add_f32_e32 v42, 1.0, v44
	v_mul_f32_e32 v44, 0xbfb8aa3b, v40
	v_add_f32_e32 v43, 1.0, v45
	v_exp_f32_e32 v45, v44
	v_mul_f32_e32 v44, 0xbfb8aa3b, v41
	v_exp_f32_e32 v46, v44
	v_rcp_f32_e32 v44, v43
	v_add_f32_e32 v43, 1.0, v45
	v_rcp_f32_e32 v42, v42
	v_add_f32_e32 v45, 1.0, v46
	v_rcp_f32_e32 v43, v43
	v_rcp_f32_e32 v45, v45
	v_mov_b32_e32 v46, v38
	v_mov_b32_e32 v47, v40
	v_mov_b32_e32 v40, v39
	v_pk_mul_f32 v[42:43], v[46:47], v[42:43]
	v_mov_b32_e32 v47, v36
	v_pk_mul_f32 v[38:39], v[40:41], v[44:45]
	v_mov_b32_e32 v36, v35
	v_mov_b32_e32 v46, v34
	v_pk_mul_f32 v[34:35], v[36:37], v[38:39]
	v_pk_mul_f32 v[42:43], v[46:47], v[42:43]
	v_cvt_pk_bf16_f32 v36, v43, v35
	v_cvt_pk_bf16_f32 v37, v42, v34
	v_mov_b32_e32 v35, v36
	v_mov_b32_e32 v34, v37
	global_store_dwordx2 v[66:67], v[34:35], off offset:96
	v_mul_f32_e32 v35, 0xbfb8aa3b, v30
	v_exp_f32_e32 v36, v35
	v_mul_f32_e32 v35, 0xbfb8aa3b, v31
	v_mul_f32_e32 v38, 0xbfb8aa3b, v32
	v_exp_f32_e32 v37, v35
	v_exp_f32_e32 v39, v38
	v_mul_f32_e32 v38, 0xbfb8aa3b, v33
	v_exp_f32_e32 v40, v38
	v_add_f32_e32 v37, 1.0, v37
	v_add_f32_e32 v36, 1.0, v36
	v_rcp_f32_e32 v38, v37
	v_add_f32_e32 v37, 1.0, v39
	v_add_f32_e32 v39, 1.0, v40
	v_rcp_f32_e32 v36, v36
	v_rcp_f32_e32 v37, v37
	v_rcp_f32_e32 v39, v39
	v_mov_b32_e32 v40, v30
	v_mov_b32_e32 v41, v32
	v_mov_b32_e32 v32, v31
	v_pk_mul_f32 v[36:37], v[40:41], v[36:37]
	v_mov_b32_e32 v41, v28
	v_pk_mul_f32 v[30:31], v[32:33], v[38:39]
	v_mov_b32_e32 v28, v27
	v_mov_b32_e32 v40, v26
	v_pk_mul_f32 v[26:27], v[28:29], v[30:31]
	v_pk_mul_f32 v[36:37], v[40:41], v[36:37]
	v_cvt_pk_bf16_f32 v28, v37, v27
	v_cvt_pk_bf16_f32 v29, v36, v26
	v_mov_b32_e32 v27, v28
	v_mul_f32_e32 v28, 0xbfb8aa3b, v22
	v_mov_b32_e32 v26, v29
	v_exp_f32_e32 v28, v28
	v_mul_f32_e32 v29, 0xbfb8aa3b, v23
	v_or_b32_e32 v34, 48, v110
	v_exp_f32_e32 v29, v29
	v_mad_i64_i32 v[34:35], s[6:7], v34, s52, v[106:107]
	v_lshl_add_u64 v[34:35], v[34:35], 0, v[108:109]
	global_store_dwordx2 v[34:35], v[26:27], off
	v_add_f32_e32 v26, 1.0, v28
	v_mul_f32_e32 v28, 0xbfb8aa3b, v24
	v_add_f32_e32 v27, 1.0, v29
	v_exp_f32_e32 v29, v28
	v_mul_f32_e32 v28, 0xbfb8aa3b, v25
	v_exp_f32_e32 v30, v28
	v_rcp_f32_e32 v28, v27
	v_add_f32_e32 v27, 1.0, v29
	v_rcp_f32_e32 v26, v26
	v_add_f32_e32 v29, 1.0, v30
	v_rcp_f32_e32 v27, v27
	v_rcp_f32_e32 v29, v29
	v_mov_b32_e32 v30, v22
	v_mov_b32_e32 v31, v24
	v_mov_b32_e32 v24, v23
	v_pk_mul_f32 v[26:27], v[30:31], v[26:27]
	v_mov_b32_e32 v31, v20
	v_pk_mul_f32 v[22:23], v[24:25], v[28:29]
	v_mov_b32_e32 v20, v19
	v_mov_b32_e32 v30, v18
	v_pk_mul_f32 v[18:19], v[20:21], v[22:23]
	v_pk_mul_f32 v[26:27], v[30:31], v[26:27]
	v_cvt_pk_bf16_f32 v20, v27, v19
	v_cvt_pk_bf16_f32 v21, v26, v18
	v_mov_b32_e32 v19, v20
	v_mul_f32_e32 v20, 0xbfb8aa3b, v14
	v_mov_b32_e32 v18, v21
	v_exp_f32_e32 v20, v20
	v_mul_f32_e32 v21, 0xbfb8aa3b, v15
	v_exp_f32_e32 v21, v21
	global_store_dwordx2 v[34:35], v[18:19], off offset:32
	v_add_f32_e32 v18, 1.0, v20
	v_mul_f32_e32 v20, 0xbfb8aa3b, v16
	v_add_f32_e32 v19, 1.0, v21
	v_exp_f32_e32 v21, v20
	v_mul_f32_e32 v20, 0xbfb8aa3b, v17
	v_exp_f32_e32 v22, v20
	v_rcp_f32_e32 v20, v19
	v_add_f32_e32 v19, 1.0, v21
	v_rcp_f32_e32 v18, v18
	v_add_f32_e32 v21, 1.0, v22
	v_rcp_f32_e32 v19, v19
	v_rcp_f32_e32 v21, v21
	v_mov_b32_e32 v22, v14
	v_mov_b32_e32 v23, v16
	v_mov_b32_e32 v16, v15
	v_pk_mul_f32 v[18:19], v[22:23], v[18:19]
	v_mov_b32_e32 v23, v12
	v_pk_mul_f32 v[14:15], v[16:17], v[20:21]
	v_mov_b32_e32 v12, v11
	v_mov_b32_e32 v22, v10
	v_pk_mul_f32 v[10:11], v[12:13], v[14:15]
	v_pk_mul_f32 v[18:19], v[22:23], v[18:19]
	v_cvt_pk_bf16_f32 v12, v19, v11
	v_cvt_pk_bf16_f32 v13, v18, v10
	v_mov_b32_e32 v11, v12
	v_mul_f32_e32 v12, 0xbfb8aa3b, v6
	v_mov_b32_e32 v10, v13
	v_exp_f32_e32 v12, v12
	v_mul_f32_e32 v13, 0xbfb8aa3b, v7
	v_exp_f32_e32 v13, v13
	global_store_dwordx2 v[34:35], v[10:11], off offset:64
	v_add_f32_e32 v10, 1.0, v12
	v_mul_f32_e32 v12, 0xbfb8aa3b, v8
	v_add_f32_e32 v11, 1.0, v13
	v_exp_f32_e32 v13, v12
	v_mul_f32_e32 v12, 0xbfb8aa3b, v9
	v_exp_f32_e32 v14, v12
	v_rcp_f32_e32 v12, v11
	v_add_f32_e32 v11, 1.0, v13
	v_rcp_f32_e32 v10, v10
	v_add_f32_e32 v13, 1.0, v14
	v_rcp_f32_e32 v11, v11
	v_rcp_f32_e32 v13, v13
	v_mov_b32_e32 v14, v6
	v_mov_b32_e32 v15, v8
	v_mov_b32_e32 v8, v7
	v_pk_mul_f32 v[10:11], v[14:15], v[10:11]
	v_mov_b32_e32 v15, v4
	v_pk_mul_f32 v[6:7], v[8:9], v[12:13]
	v_mov_b32_e32 v4, v3
	v_mov_b32_e32 v14, v2
	v_pk_mul_f32 v[2:3], v[4:5], v[6:7]
	v_pk_mul_f32 v[10:11], v[14:15], v[10:11]
	v_cvt_pk_bf16_f32 v4, v11, v3
	v_cvt_pk_bf16_f32 v5, v10, v2
	s_add_i32 s20, s20, s11
	v_mov_b32_e32 v3, v4
	v_mov_b32_e32 v2, v5
	s_cmpk_gt_i32 s20, 0x5ff
	global_store_dwordx2 v[34:35], v[2:3], off offset:96
	s_cbranch_scc0 .LBB0_465

.LBB0_474:
	s_add_i32 s4, s19, 4
	s_min_u32 s4, s4, 15
	s_lshl_b32 s4, s4, 7
	v_lshl_add_u64 v[74:75], v[54:55], 0, s[4:5]
	v_add_co_u32_e32 v78, vcc, s34, v74
	v_lshl_add_u64 v[82:83], v[56:57], 0, s[4:5]
	s_nop 0
	v_addc_co_u32_e32 v79, vcc, 0, v75, vcc
	v_add_co_u32_e32 v86, vcc, s34, v82
	global_load_dwordx4 v[74:77], v[74:75], off
	s_nop 0
	global_load_dwordx4 v[78:81], v[78:79], off
	v_addc_co_u32_e32 v87, vcc, 0, v83, vcc
	global_load_dwordx4 v[82:85], v[82:83], off
	s_nop 0
	global_load_dwordx4 v[86:89], v[86:87], off
	v_add_u32_e32 v73, v61, v64
	ds_read_b128 v[90:93], v65
	ds_read_b128 v[94:97], v65 offset:2304
	ds_read_b128 v[98:101], v73 offset:36864
	ds_read_b128 v[102:105], v73 offset:39168
	ds_read_b128 v[106:109], v73 offset:41472
	ds_read_b128 v[110:113], v73 offset:43776
	s_add_i32 s19, s19, 2
	s_waitcnt lgkmcnt(3)
	v_mfma_f32_16x16x32_bf16 v[42:45], v[98:101], v[90:93], v[42:45]
	s_waitcnt lgkmcnt(2)
	v_mfma_f32_16x16x32_bf16 v[46:49], v[102:105], v[90:93], v[46:49]
	s_waitcnt lgkmcnt(1)
	v_mfma_f32_16x16x32_bf16 v[34:37], v[106:109], v[90:93], v[34:37]
	s_waitcnt lgkmcnt(0)
	v_mfma_f32_16x16x32_bf16 v[38:41], v[110:113], v[90:93], v[38:41]
	v_mfma_f32_16x16x32_bf16 v[10:13], v[98:101], v[94:97], v[10:13]
	ds_read_b128 v[90:93], v65 offset:64
	ds_read_b128 v[98:101], v65 offset:2368
	v_mfma_f32_16x16x32_bf16 v[14:17], v[102:105], v[94:97], v[14:17]
	v_mfma_f32_16x16x32_bf16 v[2:5], v[106:109], v[94:97], v[2:5]
	ds_read_b128 v[102:105], v73 offset:36928
	ds_read_b128 v[106:109], v73 offset:39232
	ds_read_b128 v[114:117], v73 offset:41536
	ds_read_b128 v[118:121], v73 offset:43840
	v_mfma_f32_16x16x32_bf16 v[6:9], v[110:113], v[94:97], v[6:9]
	s_waitcnt lgkmcnt(3)
	v_mfma_f32_16x16x32_bf16 v[42:45], v[102:105], v[90:93], v[42:45]
	s_waitcnt vmcnt(7)
	ds_write_b128 v72, v[18:21] offset:55296
	s_waitcnt vmcnt(6)
	ds_write_b128 v72, v[22:25] offset:64512
	s_waitcnt vmcnt(5)
	ds_write_b128 v66, v[26:29]
	s_waitcnt vmcnt(4)
	ds_write_b128 v66, v[30:33] offset:9216
	s_waitcnt lgkmcnt(6)
	v_mfma_f32_16x16x32_bf16 v[46:49], v[106:109], v[90:93], v[46:49]
	s_waitcnt lgkmcnt(5)
	v_mfma_f32_16x16x32_bf16 v[34:37], v[114:117], v[90:93], v[34:37]
	s_waitcnt lgkmcnt(4)
	v_mfma_f32_16x16x32_bf16 v[38:41], v[118:121], v[90:93], v[38:41]
	v_mfma_f32_16x16x32_bf16 v[10:13], v[102:105], v[98:101], v[10:13]
	v_mfma_f32_16x16x32_bf16 v[14:17], v[106:109], v[98:101], v[14:17]
	v_mfma_f32_16x16x32_bf16 v[2:5], v[114:117], v[98:101], v[2:5]
	v_mfma_f32_16x16x32_bf16 v[6:9], v[118:121], v[98:101], v[6:9]
	s_min_u32 s4, s19, 12
	s_lshl_b32 s4, s4, 7
	v_lshl_add_u64 v[18:19], v[54:55], 0, s[4:5]
	v_add_co_u32_e32 v22, vcc, s34, v18
	v_lshl_add_u64 v[26:27], v[56:57], 0, s[4:5]
	s_nop 0
	v_addc_co_u32_e32 v23, vcc, 0, v19, vcc
	v_add_co_u32_e32 v30, vcc, s34, v26
	s_waitcnt lgkmcnt(0)
	s_barrier
	global_load_dwordx4 v[18:21], v[18:19], off offset:384
	s_nop 0
	global_load_dwordx4 v[22:25], v[22:23], off offset:384
	v_addc_co_u32_e32 v31, vcc, 0, v27, vcc
	global_load_dwordx4 v[26:29], v[26:27], off offset:384
	s_nop 0
	global_load_dwordx4 v[30:33], v[30:31], off offset:384
	ds_read_b128 v[90:93], v65 offset:55296
	ds_read_b128 v[94:97], v65 offset:57600
	ds_read_b128 v[98:101], v67
	ds_read_b128 v[102:105], v67 offset:2304
	ds_read_b128 v[106:109], v67 offset:4608
	ds_read_b128 v[110:113], v67 offset:6912
	s_waitcnt lgkmcnt(3)
	v_mfma_f32_16x16x32_bf16 v[42:45], v[98:101], v[90:93], v[42:45]
	s_waitcnt lgkmcnt(2)
	v_mfma_f32_16x16x32_bf16 v[46:49], v[102:105], v[90:93], v[46:49]
	s_waitcnt lgkmcnt(1)
	v_mfma_f32_16x16x32_bf16 v[34:37], v[106:109], v[90:93], v[34:37]
	s_waitcnt lgkmcnt(0)
	v_mfma_f32_16x16x32_bf16 v[38:41], v[110:113], v[90:93], v[38:41]
	v_mfma_f32_16x16x32_bf16 v[10:13], v[98:101], v[94:97], v[10:13]
	ds_read_b128 v[90:93], v65 offset:55360
	ds_read_b128 v[98:101], v65 offset:57664
	v_mfma_f32_16x16x32_bf16 v[14:17], v[102:105], v[94:97], v[14:17]
	v_mfma_f32_16x16x32_bf16 v[2:5], v[106:109], v[94:97], v[2:5]
	ds_read_b128 v[102:105], v68 offset:64
	ds_read_b128 v[106:109], v69 offset:64
	ds_read_b128 v[114:117], v70 offset:64
	ds_read_b128 v[118:121], v71 offset:64
	v_mfma_f32_16x16x32_bf16 v[6:9], v[110:113], v[94:97], v[6:9]
	s_waitcnt lgkmcnt(3)
	v_mfma_f32_16x16x32_bf16 v[42:45], v[102:105], v[90:93], v[42:45]
	s_waitcnt vmcnt(7)
	ds_write_b128 v72, v[74:77]
	s_waitcnt vmcnt(6)
	ds_write_b128 v72, v[78:81] offset:9216
	s_waitcnt vmcnt(5)
	ds_write_b128 v72, v[82:85] offset:36864
	s_waitcnt vmcnt(4)
	ds_write_b128 v72, v[86:89] offset:46080
	s_waitcnt lgkmcnt(6)
	v_mfma_f32_16x16x32_bf16 v[46:49], v[106:109], v[90:93], v[46:49]
	s_waitcnt lgkmcnt(5)
	v_mfma_f32_16x16x32_bf16 v[34:37], v[114:117], v[90:93], v[34:37]
	s_waitcnt lgkmcnt(4)
	v_mfma_f32_16x16x32_bf16 v[38:41], v[118:121], v[90:93], v[38:41]
	v_mfma_f32_16x16x32_bf16 v[10:13], v[102:105], v[98:101], v[10:13]
	v_mfma_f32_16x16x32_bf16 v[14:17], v[106:109], v[98:101], v[14:17]
	v_mfma_f32_16x16x32_bf16 v[2:5], v[114:117], v[98:101], v[2:5]
	v_mfma_f32_16x16x32_bf16 v[6:9], v[118:121], v[98:101], v[6:9]
	s_waitcnt lgkmcnt(0)
	s_barrier
	s_cmp_gt_u32 s19, 13
	s_cbranch_scc0 .LBB0_474
	s_waitcnt vmcnt(3)
	v_mul_f32_e32 v19, 0xbfb8aa3b, v42
	v_exp_f32_e32 v19, v19
	s_waitcnt vmcnt(2)
	v_mul_f32_e32 v22, 0xbfb8aa3b, v43
	v_exp_f32_e32 v25, v22
	s_waitcnt vmcnt(1)
	v_mul_f32_e32 v26, 0xbfb8aa3b, v45
	v_add_f32_e32 v19, 1.0, v19
	v_rcp_f32_e32 v24, v19
	v_add_f32_e32 v19, 1.0, v25
	v_mul_f32_e32 v25, 0xbfb8aa3b, v44
	v_exp_f32_e32 v25, v25
	v_exp_f32_e32 v27, v26
	v_rcp_f32_e32 v26, v19
	v_mov_b32_e32 v28, v42
	v_add_f32_e32 v19, 1.0, v25
	v_rcp_f32_e32 v25, v19
	v_add_f32_e32 v19, 1.0, v27
	v_rcp_f32_e32 v27, v19
	v_mov_b32_e32 v29, v44
	v_pk_mul_f32 v[24:25], v[28:29], v[24:25]
	v_mov_b32_e32 v28, v46
	v_mov_b32_e32 v29, v48
	v_mov_b32_e32 v44, v43
	v_pk_mul_f32 v[24:25], v[28:29], v[24:25]
	v_pk_mul_f32 v[26:27], v[44:45], v[26:27]
	v_mov_b32_e32 v48, v47
	v_pk_mul_f32 v[26:27], v[48:49], v[26:27]
	v_cvt_pk_bf16_f32 v24, v24, v26
	v_cvt_pk_bf16_f32 v25, v25, v27
	v_or_b32_e32 v18, s17, v58
	v_ashrrev_i32_e32 v18, 1, v18
	v_mul_f32_e32 v26, 0xbfb8aa3b, v34
	v_or_b32_e32 v18, v18, v62
	v_exp_f32_e32 v26, v26
	v_mul_f32_e32 v27, 0xbfb8aa3b, v35
	s_waitcnt vmcnt(0)
	v_add_u32_e32 v30, s16, v60
	v_mov_b64_e32 v[20:21], s[14:15]
	v_ashrrev_i32_e32 v19, 31, v18
	v_exp_f32_e32 v27, v27
	v_mad_i64_i32 v[22:23], s[16:17], v30, s52, v[20:21]
	v_lshlrev_b64 v[18:19], 1, v[18:19]
	v_lshl_add_u64 v[22:23], v[22:23], 0, v[18:19]
	s_waitcnt vmcnt(0)
	global_store_dwordx2 v[22:23], v[24:25], off
	v_add_f32_e32 v24, 1.0, v26
	v_mul_f32_e32 v26, 0xbfb8aa3b, v36
	v_add_f32_e32 v25, 1.0, v27
	v_exp_f32_e32 v27, v26
	v_mul_f32_e32 v26, 0xbfb8aa3b, v37
	v_exp_f32_e32 v28, v26
	v_rcp_f32_e32 v26, v25
	v_add_f32_e32 v25, 1.0, v27
	v_rcp_f32_e32 v24, v24
	v_rcp_f32_e32 v25, v25
	v_add_f32_e32 v27, 1.0, v28
	v_rcp_f32_e32 v27, v27
	v_mov_b32_e32 v28, v34
	v_mov_b32_e32 v29, v36
	v_pk_mul_f32 v[24:25], v[28:29], v[24:25]
	v_mov_b32_e32 v28, v38
	v_mov_b32_e32 v29, v40
	v_mov_b32_e32 v36, v35
	v_pk_mul_f32 v[24:25], v[28:29], v[24:25]
	v_pk_mul_f32 v[26:27], v[36:37], v[26:27]
	v_mov_b32_e32 v40, v39
	v_pk_mul_f32 v[26:27], v[40:41], v[26:27]
	v_and_b32_sdwa v28, v25, v177 dst_sel:DWORD dst_unused:UNUSED_PAD src0_sel:WORD_1 src1_sel:DWORD
	v_and_b32_sdwa v29, v24, v177 dst_sel:DWORD dst_unused:UNUSED_PAD src0_sel:WORD_1 src1_sel:DWORD
	v_add3_u32 v24, v24, v29, s28
	v_add3_u32 v25, v25, v28, s28
	v_and_b32_sdwa v28, v27, v177 dst_sel:DWORD dst_unused:UNUSED_PAD src0_sel:WORD_1 src1_sel:DWORD
	v_and_b32_sdwa v29, v26, v177 dst_sel:DWORD dst_unused:UNUSED_PAD src0_sel:WORD_1 src1_sel:DWORD
	v_add3_u32 v27, v27, v28, s28
	v_add3_u32 v26, v26, v29, s28
	v_and_b32_e32 v27, 0xffff0000, v27
	v_and_b32_e32 v26, 0xffff0000, v26
	v_or_b32_sdwa v25, v27, v25 dst_sel:DWORD dst_unused:UNUSED_PAD src0_sel:DWORD src1_sel:WORD_1
	v_or_b32_sdwa v24, v26, v24 dst_sel:DWORD dst_unused:UNUSED_PAD src0_sel:DWORD src1_sel:WORD_1
	global_store_dwordx2 v[22:23], v[24:25], off offset:32
	v_mul_f32_e32 v23, 0xbfb8aa3b, v10
	v_mul_f32_e32 v24, 0xbfb8aa3b, v11
	v_exp_f32_e32 v23, v23
	v_exp_f32_e32 v24, v24
	v_or_b32_e32 v22, 16, v30
	v_mad_i64_i32 v[20:21], s[16:17], v22, s52, v[20:21]
	v_add_f32_e32 v22, 1.0, v23
	v_add_f32_e32 v23, 1.0, v24
	v_mul_f32_e32 v24, 0xbfb8aa3b, v12
	v_exp_f32_e32 v25, v24
	v_mul_f32_e32 v24, 0xbfb8aa3b, v13
	v_exp_f32_e32 v26, v24
	v_rcp_f32_e32 v24, v23
	v_add_f32_e32 v23, 1.0, v25
	v_rcp_f32_e32 v22, v22
	v_add_f32_e32 v25, 1.0, v26
	v_rcp_f32_e32 v23, v23
	v_rcp_f32_e32 v25, v25
	v_lshl_add_u64 v[18:19], v[20:21], 0, v[18:19]
	v_mov_b32_e32 v20, v10
	v_mov_b32_e32 v21, v12
	v_mov_b32_e32 v12, v11
	v_pk_mul_f32 v[20:21], v[20:21], v[22:23]
	v_mov_b32_e32 v23, v16
	v_pk_mul_f32 v[10:11], v[12:13], v[24:25]
	v_mov_b32_e32 v16, v15
	v_mov_b32_e32 v22, v14
	v_pk_mul_f32 v[10:11], v[16:17], v[10:11]
	v_pk_mul_f32 v[20:21], v[22:23], v[20:21]
	v_cvt_pk_bf16_f32 v12, v21, v11
	v_cvt_pk_bf16_f32 v13, v20, v10
	v_mov_b32_e32 v11, v12
	v_mul_f32_e32 v12, 0xbfb8aa3b, v2
	v_mov_b32_e32 v10, v13
	v_exp_f32_e32 v12, v12
	v_mul_f32_e32 v13, 0xbfb8aa3b, v3
	v_exp_f32_e32 v13, v13
	global_store_dwordx2 v[18:19], v[10:11], off
	v_add_f32_e32 v10, 1.0, v12
	v_mul_f32_e32 v12, 0xbfb8aa3b, v4
	v_add_f32_e32 v11, 1.0, v13
	v_exp_f32_e32 v13, v12
	v_mul_f32_e32 v12, 0xbfb8aa3b, v5
	v_exp_f32_e32 v14, v12
	v_rcp_f32_e32 v12, v11
	v_add_f32_e32 v11, 1.0, v13
	v_rcp_f32_e32 v10, v10
	v_add_f32_e32 v13, 1.0, v14
	v_rcp_f32_e32 v11, v11
	v_rcp_f32_e32 v13, v13
	v_mov_b32_e32 v14, v2
	v_mov_b32_e32 v15, v4
	v_mov_b32_e32 v4, v3
	v_pk_mul_f32 v[10:11], v[14:15], v[10:11]
	v_mov_b32_e32 v15, v8
	v_pk_mul_f32 v[2:3], v[4:5], v[12:13]
	v_mov_b32_e32 v8, v7
	v_mov_b32_e32 v14, v6
	v_pk_mul_f32 v[2:3], v[8:9], v[2:3]
	v_pk_mul_f32 v[10:11], v[14:15], v[10:11]
	v_and_b32_sdwa v6, v3, v177 dst_sel:DWORD dst_unused:UNUSED_PAD src0_sel:WORD_1 src1_sel:DWORD
	v_cvt_pk_bf16_f32 v5, v10, v2
	v_and_b32_sdwa v4, v11, v177 dst_sel:DWORD dst_unused:UNUSED_PAD src0_sel:WORD_1 src1_sel:DWORD
	v_add3_u32 v3, v3, v6, s28
	v_add3_u32 v4, v11, v4, s28
	v_and_b32_e32 v3, 0xffff0000, v3
	v_or_b32_sdwa v3, v3, v4 dst_sel:DWORD dst_unused:UNUSED_PAD src0_sel:DWORD src1_sel:WORD_1
	v_mov_b32_e32 v2, v5
	s_mov_b32 s4, 0
	global_store_dwordx2 v[18:19], v[2:3], off offset:32
	s_branch .LBB0_469

.LBB0_604:
	s_or_b64 exec, exec, s[46:47]
	v_lshl_add_u64 v[2:3], v[2:3], 0, v[0:1]
	global_load_dwordx4 v[36:39], v[2:3], off
	global_load_dwordx4 v[40:43], v[2:3], off offset:1024
	global_load_dwordx4 v[44:47], v[2:3], off offset:2048
	s_nop 0
	global_load_dwordx4 v[2:5], v[2:3], off offset:3072
	s_nop 0
	global_load_dwordx4 v[48:51], v[8:9], off
	global_load_dwordx4 v[78:81], v[10:11], off
	global_load_dwordx4 v[90:93], v[12:13], off
	global_load_dwordx4 v[102:105], v[14:15], off
	v_min_i32_e32 v19, 0x4000, v6
	v_ashrrev_i32_e32 v19, 11, v19
	v_mul_hi_i32_i24_e32 v25, 0x9000, v19
	v_mul_i32_i24_e32 v24, 0x9000, v19
	v_lshl_add_u64 v[24:25], s[16:17], 0, v[24:25]
	v_lshl_add_u64 v[26:27], v[24:25], 0, s[38:39]
	v_lshl_add_u64 v[28:29], v[26:27], 0, v[0:1]
	global_load_dwordx4 v[52:55], v[28:29], off
	global_load_dwordx4 v[82:85], v[28:29], off offset:1024
	global_load_dwordx4 v[94:97], v[28:29], off offset:2048
	global_load_dwordx4 v[106:109], v[28:29], off offset:3072
	v_lshl_add_u64 v[28:29], v[24:25], 0, v[0:1]
	global_load_dwordx4 v[56:59], v[28:29], off
	global_load_dwordx4 v[86:89], v[28:29], off offset:1024
	global_load_dwordx4 v[98:101], v[28:29], off offset:2048
	global_load_dwordx4 v[110:113], v[28:29], off offset:3072
	s_mov_b32 s4, s42
	s_waitcnt vmcnt(15)
	v_mov_b32_e32 v60, v37
	s_waitcnt vmcnt(14)
	v_mov_b32_e32 v61, v41
	v_mov_b32_e32 v24, v36
	v_mov_b32_e32 v25, v40
	s_waitcnt vmcnt(13)
	v_mov_b32_e32 v68, v45
	s_waitcnt vmcnt(12)
	v_mov_b32_e32 v69, v3
	v_pk_mul_f32 v[60:61], v[60:61], v[60:61]
	v_mov_b32_e32 v62, v38
	v_mov_b32_e32 v63, v42
	v_mov_b32_e32 v66, v44
	v_mov_b32_e32 v67, v2
	v_pk_mul_f32 v[68:69], v[68:69], v[68:69]
	v_pk_fma_f32 v[24:25], v[24:25], v[24:25], v[60:61]
	v_mov_b32_e32 v64, v39
	v_mov_b32_e32 v65, v43
	v_mov_b32_e32 v70, v46
	v_mov_b32_e32 v71, v4
	v_pk_fma_f32 v[60:61], v[66:67], v[66:67], v[68:69]
	v_pk_fma_f32 v[24:25], v[62:63], v[62:63], v[24:25]
	v_mov_b32_e32 v72, v47
	v_mov_b32_e32 v73, v5
	v_pk_fma_f32 v[60:61], v[70:71], v[70:71], v[60:61]
	v_pk_fma_f32 v[24:25], v[64:65], v[64:65], v[24:25]
	v_pk_fma_f32 v[60:61], v[72:73], v[72:73], v[60:61]
	v_add_f32_e32 v19, v24, v25
	v_add_f32_e32 v19, v19, v60
	v_add_f32_e32 v19, v19, v61
	ds_bpermute_b32 v21, v30, v19
	v_lshlrev_b64 v[24:25], 11, v[6:7]
	s_waitcnt vmcnt(11)
	v_mov_b32_e32 v60, v48
	v_mov_b32_e32 v48, v36
	v_mov_b32_e32 v36, v37
	s_waitcnt lgkmcnt(0)
	v_add_f32_e32 v19, v19, v21
	ds_bpermute_b32 v21, v31, v19
	v_mov_b32_e32 v37, v39
	s_waitcnt vmcnt(3)
	v_mov_b32_e32 v62, v56
	v_mov_b32_e32 v61, v50
	v_mov_b32_e32 v50, v49
	s_waitcnt lgkmcnt(0)
	v_add_f32_e32 v21, v19, v21
	ds_bpermute_b32 v23, v32, v21
	v_mov_b32_e32 v49, v38
	v_mov_b32_e32 v39, v54
	v_mov_b32_e32 v54, v53
	v_mov_b32_e32 v38, v52
	s_waitcnt lgkmcnt(0)
	v_add_f32_e32 v7, v21, v23
	ds_bpermute_b32 v21, v33, v7
	v_mov_b32_e32 v63, v58
	v_mov_b32_e32 v58, v57
	v_pk_add_f32 v[52:53], v[54:55], 1.0 op_sel_hi:[1,0]
	v_pk_add_f32 v[38:39], v[38:39], 1.0 op_sel_hi:[1,0]
	s_waitcnt lgkmcnt(0)
	v_add_f32_e32 v7, v7, v21
	ds_bpermute_b32 v21, v34, v7
	v_lshl_add_u64 v[24:25], v[16:17], 0, v[24:25]
	v_mov_b32_e32 v19, v1
	s_waitcnt lgkmcnt(0)
	v_add_f32_e32 v7, v7, v21
	ds_bpermute_b32 v21, v35, v7
	s_waitcnt lgkmcnt(0)
	v_add_f32_e32 v7, v7, v21
	v_fmamk_f32 v7, v7, 0x3a800000, v174
	v_mul_f32_e32 v21, 0x4b800000, v7
	v_cmp_gt_f32_e32 vcc, s27, v7
	s_nop 1
	v_cndmask_b32_e32 v7, v7, v21, vcc
	v_rsq_f32_e32 v7, v7
	s_nop 0
	v_mul_f32_e32 v21, 0x45800000, v7
	v_cndmask_b32_e32 v56, v7, v21, vcc
	v_pk_mul_f32 v[36:37], v[36:37], v[56:57] op_sel_hi:[1,0]
	v_pk_mul_f32 v[48:49], v[48:49], v[56:57] op_sel_hi:[1,0]
	v_pk_mul_f32 v[36:37], v[50:51], v[36:37]
	v_pk_mul_f32 v[48:49], v[60:61], v[48:49]
	v_pk_fma_f32 v[36:37], v[52:53], v[36:37], v[58:59]
	v_pk_fma_f32 v[38:39], v[38:39], v[48:49], v[62:63]
	v_cvt_pk_bf16_f32 v21, v38, v36
	v_cvt_pk_bf16_f32 v37, v39, v37
	v_mov_b32_e32 v36, v21
	global_store_dwordx2 v[24:25], v[36:37], off
	v_lshl_add_u64 v[48:49], v[26:27], 0, v[18:19]
	s_waitcnt vmcnt(1)
	v_mov_b32_e32 v52, v86
	v_mov_b32_e32 v53, v87
	v_mov_b32_e32 v54, v88
	v_mov_b32_e32 v55, v89
	v_mov_b32_e32 v48, v82
	v_mov_b32_e32 v49, v83
	v_mov_b32_e32 v50, v84
	v_mov_b32_e32 v51, v85
	v_mov_b32_e32 v36, v78
	v_mov_b32_e32 v37, v79
	v_mov_b32_e32 v38, v80
	v_mov_b32_e32 v39, v81
	v_mov_b32_e32 v58, v40
	v_mov_b32_e32 v59, v42
	v_mov_b32_e32 v42, v41
	v_pk_mul_f32 v[40:41], v[58:59], v[56:57] op_sel_hi:[1,0]
	v_pk_mul_f32 v[42:43], v[42:43], v[56:57] op_sel_hi:[1,0]
	v_mov_b32_e32 v21, v1
	v_mov_b32_e32 v58, v36
	v_mov_b32_e32 v59, v38
	v_mov_b32_e32 v60, v48
	v_mov_b32_e32 v61, v50
	v_mov_b32_e32 v38, v37
	v_mov_b32_e32 v50, v49
	v_mov_b32_e32 v62, v52
	v_mov_b32_e32 v63, v54
	v_mov_b32_e32 v54, v53
	v_pk_mul_f32 v[36:37], v[40:41], v[58:59]
	v_pk_add_f32 v[40:41], v[60:61], 1.0 op_sel_hi:[1,0]
	v_pk_mul_f32 v[38:39], v[42:43], v[38:39]
	v_pk_add_f32 v[42:43], v[50:51], 1.0 op_sel_hi:[1,0]
	v_pk_fma_f32 v[36:37], v[36:37], v[40:41], v[62:63]
	v_pk_fma_f32 v[38:39], v[38:39], v[42:43], v[54:55]
	v_cvt_pk_bf16_f32 v19, v36, v38
	v_cvt_pk_bf16_f32 v37, v37, v39
	v_mov_b32_e32 v36, v19
	global_store_dwordx2 v[24:25], v[36:37], off offset:512
	v_lshl_add_u64 v[40:41], v[26:27], 0, v[20:21]
	v_mov_b32_e32 v48, v98
	v_mov_b32_e32 v49, v99
	v_mov_b32_e32 v50, v100
	v_mov_b32_e32 v51, v101
	v_mov_b32_e32 v40, v94
	v_mov_b32_e32 v41, v95
	v_mov_b32_e32 v42, v96
	v_mov_b32_e32 v43, v97
	v_mov_b32_e32 v36, v90
	v_mov_b32_e32 v37, v91
	v_mov_b32_e32 v38, v92
	v_mov_b32_e32 v39, v93
	v_mov_b32_e32 v52, v44
	v_mov_b32_e32 v53, v46
	v_mov_b32_e32 v44, v45
	v_mov_b32_e32 v45, v47
	v_pk_mul_f32 v[46:47], v[52:53], v[56:57] op_sel_hi:[1,0]
	v_pk_mul_f32 v[44:45], v[44:45], v[56:57] op_sel_hi:[1,0]
	v_mov_b32_e32 v23, v1
	v_lshl_add_u64 v[26:27], v[26:27], 0, v[22:23]
	v_mov_b32_e32 v52, v36
	v_mov_b32_e32 v53, v38
	v_mov_b32_e32 v54, v40
	v_mov_b32_e32 v55, v42
	v_mov_b32_e32 v38, v37
	v_mov_b32_e32 v42, v41
	v_mov_b32_e32 v58, v48
	v_mov_b32_e32 v59, v50
	v_mov_b32_e32 v50, v49
	v_pk_mul_f32 v[36:37], v[46:47], v[52:53]
	v_pk_add_f32 v[40:41], v[54:55], 1.0 op_sel_hi:[1,0]
	v_pk_mul_f32 v[38:39], v[44:45], v[38:39]
	v_pk_add_f32 v[42:43], v[42:43], 1.0 op_sel_hi:[1,0]
	v_pk_fma_f32 v[36:37], v[36:37], v[40:41], v[58:59]
	v_pk_fma_f32 v[38:39], v[38:39], v[42:43], v[50:51]
	v_cvt_pk_bf16_f32 v19, v36, v38
	v_cvt_pk_bf16_f32 v37, v37, v39
	v_mov_b32_e32 v36, v19
	global_store_dwordx2 v[24:25], v[36:37], off offset:1024
	v_mov_b32_e32 v26, v110
	v_mov_b32_e32 v27, v111
	v_mov_b32_e32 v28, v112
	v_mov_b32_e32 v29, v113
	v_mov_b32_e32 v40, v106
	v_mov_b32_e32 v41, v107
	v_mov_b32_e32 v42, v108
	v_mov_b32_e32 v43, v109
	v_mov_b32_e32 v36, v102
	v_mov_b32_e32 v37, v103
	v_mov_b32_e32 v38, v104
	v_mov_b32_e32 v39, v105
	v_mov_b32_e32 v44, v2
	v_mov_b32_e32 v45, v4
	v_mov_b32_e32 v4, v3
	v_pk_mul_f32 v[2:3], v[44:45], v[56:57] op_sel_hi:[1,0]
	v_pk_mul_f32 v[4:5], v[4:5], v[56:57] op_sel_hi:[1,0]
	v_mov_b32_e32 v47, v42
	v_mov_b32_e32 v45, v38
	v_mov_b32_e32 v38, v37
	v_mov_b32_e32 v42, v41
	v_mov_b32_e32 v44, v36
	v_mov_b32_e32 v46, v40
	v_mov_b32_e32 v49, v28
	v_mov_b32_e32 v28, v27
	v_pk_mul_f32 v[4:5], v[4:5], v[38:39]
	v_pk_add_f32 v[36:37], v[42:43], 1.0 op_sel_hi:[1,0]
	v_mov_b32_e32 v48, v26
	v_pk_mul_f32 v[2:3], v[2:3], v[44:45]
	v_pk_add_f32 v[26:27], v[46:47], 1.0 op_sel_hi:[1,0]
	v_pk_fma_f32 v[4:5], v[4:5], v[36:37], v[28:29]
	v_pk_fma_f32 v[2:3], v[2:3], v[26:27], v[48:49]
	v_and_b32_sdwa v21, v5, v177 dst_sel:DWORD dst_unused:UNUSED_PAD src0_sel:WORD_1 src1_sel:DWORD
	v_and_b32_sdwa v23, v4, v177 dst_sel:DWORD dst_unused:UNUSED_PAD src0_sel:WORD_1 src1_sel:DWORD
	v_and_b32_sdwa v7, v3, v177 dst_sel:DWORD dst_unused:UNUSED_PAD src0_sel:WORD_1 src1_sel:DWORD
	v_and_b32_sdwa v19, v2, v177 dst_sel:DWORD dst_unused:UNUSED_PAD src0_sel:WORD_1 src1_sel:DWORD
	v_add3_u32 v5, v5, v21, s28
	v_add3_u32 v4, v4, v23, s28
	v_add3_u32 v2, v2, v19, s28
	v_add3_u32 v3, v3, v7, s28
	v_and_b32_e32 v5, 0xffff0000, v5
	v_and_b32_e32 v4, 0xffff0000, v4
	v_or_b32_sdwa v3, v5, v3 dst_sel:DWORD dst_unused:UNUSED_PAD src0_sel:DWORD src1_sel:WORD_1
	v_or_b32_sdwa v2, v4, v2 dst_sel:DWORD dst_unused:UNUSED_PAD src0_sel:DWORD src1_sel:WORD_1
	global_store_dwordx2 v[24:25], v[2:3], off offset:1536
	s_nop 0
	v_lshl_add_u32 v6, s4, 3, v6
	v_cmp_lt_i32_e32 vcc, s29, v6
	s_or_b64 s[18:19], vcc, s[18:19]
	s_andn2_b64 exec, exec, s[18:19]
	s_cbranch_execz .LBB0_609

.LBB0_665:
	s_bitcmp1_b32 s4, 0
	s_cselect_b32 s15, 0x12000, 0
	v_or_b32_e32 v208, s15, v206
	v_add_u32_e32 v214, v208, v0
	v_add_u32_e32 v208, v208, v167
	ds_read_b128 v[184:187], v214
	ds_read_b128 v[218:221], v208 offset:32768
	ds_read_b128 v[198:201], v214 offset:2048
	ds_read_b128 v[210:213], v214 offset:4096
	ds_read_b128 v[214:217], v214 offset:6144
	ds_read_b128 v[222:225], v208 offset:34816
	ds_read_b128 v[226:229], v208 offset:36864
	ds_read_b128 v[230:233], v208 offset:38912
	ds_read_b128 v[234:237], v208 offset:40960
	ds_read_b128 v[238:241], v208 offset:43008
	ds_read_b128 v[242:245], v208 offset:45056
	ds_read_b128 v[246:249], v208 offset:47104
	s_add_i32 s14, s4, 1
	s_bitcmp1_b32 s14, 0
	s_cselect_b32 s16, 0x12000, 0
	v_add_u32_e32 v208, s16, v166
	v_add_u32_e32 v171, s16, v166
	v_xor_b32_e32 v169, 64, v206
	v_add3_u32 v169, s15, v167, v169
	s_waitcnt lgkmcnt(10)
	v_mfma_f32_16x16x32_bf16 v[158:161], v[218:221], v[184:187], v[158:161]
	s_waitcnt lgkmcnt(9)
	v_mfma_f32_16x16x32_bf16 v[130:133], v[218:221], v[198:201], v[130:133]
	s_waitcnt lgkmcnt(8)
	v_mfma_f32_16x16x32_bf16 v[66:69], v[218:221], v[210:213], v[66:69]
	s_waitcnt lgkmcnt(7)
	v_mfma_f32_16x16x32_bf16 v[34:37], v[218:221], v[214:217], v[34:37]
	ds_read_b128 v[218:221], v169 offset:32768
	s_waitcnt lgkmcnt(7)
	v_mfma_f32_16x16x32_bf16 v[154:157], v[222:225], v[184:187], v[154:157]
	v_mfma_f32_16x16x32_bf16 v[122:125], v[222:225], v[198:201], v[122:125]
	v_mfma_f32_16x16x32_bf16 v[58:61], v[222:225], v[210:213], v[58:61]
	v_mfma_f32_16x16x32_bf16 v[26:29], v[222:225], v[214:217], v[26:29]
	ds_read_b128 v[222:225], v169 offset:34816
	s_waitcnt lgkmcnt(7)
	v_mfma_f32_16x16x32_bf16 v[150:153], v[226:229], v[184:187], v[150:153]
	v_mfma_f32_16x16x32_bf16 v[114:117], v[226:229], v[198:201], v[114:117]
	v_mfma_f32_16x16x32_bf16 v[54:57], v[226:229], v[210:213], v[54:57]
	v_mfma_f32_16x16x32_bf16 v[22:25], v[226:229], v[214:217], v[22:25]
	ds_read_b128 v[226:229], v169 offset:36864
	s_waitcnt lgkmcnt(7)
	v_mfma_f32_16x16x32_bf16 v[146:149], v[230:233], v[184:187], v[146:149]
	v_mfma_f32_16x16x32_bf16 v[82:85], v[230:233], v[198:201], v[82:85]
	v_mfma_f32_16x16x32_bf16 v[50:53], v[230:233], v[210:213], v[50:53]
	v_mfma_f32_16x16x32_bf16 v[18:21], v[230:233], v[214:217], v[18:21]
	ds_read_b128 v[230:233], v169 offset:38912
	s_waitcnt lgkmcnt(7)
	v_mfma_f32_16x16x32_bf16 v[142:145], v[234:237], v[184:187], v[142:145]
	v_mfma_f32_16x16x32_bf16 v[78:81], v[234:237], v[198:201], v[78:81]
	v_mfma_f32_16x16x32_bf16 v[46:49], v[234:237], v[210:213], v[46:49]
	v_mfma_f32_16x16x32_bf16 v[14:17], v[234:237], v[214:217], v[14:17]
	ds_read_b128 v[234:237], v169 offset:40960
	s_waitcnt lgkmcnt(7)
	v_mfma_f32_16x16x32_bf16 v[138:141], v[238:241], v[184:187], v[138:141]
	v_mfma_f32_16x16x32_bf16 v[74:77], v[238:241], v[198:201], v[74:77]
	v_mfma_f32_16x16x32_bf16 v[42:45], v[238:241], v[210:213], v[42:45]
	v_mfma_f32_16x16x32_bf16 v[10:13], v[238:241], v[214:217], v[10:13]
	ds_read_b128 v[238:241], v169 offset:43008
	s_waitcnt lgkmcnt(7)
	v_mfma_f32_16x16x32_bf16 v[134:137], v[242:245], v[184:187], v[134:137]
	v_mfma_f32_16x16x32_bf16 v[70:73], v[242:245], v[198:201], v[70:73]
	v_mfma_f32_16x16x32_bf16 v[38:41], v[242:245], v[210:213], v[38:41]
	v_mfma_f32_16x16x32_bf16 v[6:9], v[242:245], v[214:217], v[6:9]
	ds_read_b128 v[242:245], v169 offset:45056
	s_waitcnt lgkmcnt(7)
	v_mfma_f32_16x16x32_bf16 v[126:129], v[246:249], v[184:187], v[126:129]
	v_mfma_f32_16x16x32_bf16 v[62:65], v[246:249], v[198:201], v[62:65]
	v_xor_b32_e32 v169, 64, v206
	v_add3_u32 v169, s15, v0, v169
	ds_read_b128 v[184:187], v169
	ds_read_b128 v[198:201], v169 offset:2048
	v_mfma_f32_16x16x32_bf16 v[30:33], v[246:249], v[210:213], v[30:33]
	ds_read_b128 v[210:213], v169 offset:4096
	v_mfma_f32_16x16x32_bf16 v[2:5], v[246:249], v[214:217], v[2:5]
	ds_read_b128 v[214:217], v169 offset:6144
	v_xor_b32_e32 v169, 64, v206
	v_add3_u32 v169, s15, v167, v169
	ds_read_b128 v[246:249], v169 offset:47104
	s_waitcnt lgkmcnt(4)
	v_mfma_f32_16x16x32_bf16 v[158:161], v[218:221], v[184:187], v[158:161]
	s_waitcnt lgkmcnt(3)
	v_mfma_f32_16x16x32_bf16 v[130:133], v[218:221], v[198:201], v[130:133]
	s_waitcnt lgkmcnt(2)
	v_mfma_f32_16x16x32_bf16 v[66:69], v[218:221], v[210:213], v[66:69]
	s_waitcnt lgkmcnt(1)
	v_mfma_f32_16x16x32_bf16 v[34:37], v[218:221], v[214:217], v[34:37]
	s_waitcnt vmcnt(7)
	ds_write_b128 v171, v[94:97]
	v_mfma_f32_16x16x32_bf16 v[154:157], v[222:225], v[184:187], v[154:157]
	v_mfma_f32_16x16x32_bf16 v[122:125], v[222:225], v[198:201], v[122:125]
	global_load_dwordx4 v[94:97], v168, vcc offset:256
	v_mfma_f32_16x16x32_bf16 v[58:61], v[222:225], v[210:213], v[58:61]
	v_mfma_f32_16x16x32_bf16 v[26:29], v[222:225], v[214:217], v[26:29]
	s_waitcnt vmcnt(7)
	ds_write_b128 v171, v[86:89] offset:8192
	v_mfma_f32_16x16x32_bf16 v[150:153], v[226:229], v[184:187], v[150:153]
	v_mfma_f32_16x16x32_bf16 v[114:117], v[226:229], v[198:201], v[114:117]
	v_add_u32_e32 v86, s34, v168
	global_load_dwordx4 v[86:89], v86, vcc offset:256
	v_mfma_f32_16x16x32_bf16 v[54:57], v[226:229], v[210:213], v[54:57]
	v_mfma_f32_16x16x32_bf16 v[22:25], v[226:229], v[214:217], v[22:25]
	s_waitcnt vmcnt(7)
	ds_write_b128 v171, v[90:93] offset:16384
	v_mfma_f32_16x16x32_bf16 v[146:149], v[230:233], v[184:187], v[146:149]
	v_mfma_f32_16x16x32_bf16 v[82:85], v[230:233], v[198:201], v[82:85]
	v_add_u32_e32 v90, s35, v168
	global_load_dwordx4 v[90:93], v90, vcc offset:256
	v_mfma_f32_16x16x32_bf16 v[50:53], v[230:233], v[210:213], v[50:53]
	v_mfma_f32_16x16x32_bf16 v[18:21], v[230:233], v[214:217], v[18:21]
	s_waitcnt vmcnt(7)
	ds_write_b128 v171, v[106:109] offset:24576
	v_mfma_f32_16x16x32_bf16 v[142:145], v[234:237], v[184:187], v[142:145]
	v_mfma_f32_16x16x32_bf16 v[78:81], v[234:237], v[198:201], v[78:81]
	v_add_u32_e32 v106, s36, v168
	global_load_dwordx4 v[106:109], v106, vcc offset:256
	v_mfma_f32_16x16x32_bf16 v[46:49], v[234:237], v[210:213], v[46:49]
	v_mfma_f32_16x16x32_bf16 v[14:17], v[234:237], v[214:217], v[14:17]
	s_waitcnt vmcnt(7)
	ds_write_b128 v171, v[102:105] offset:32768
	v_mfma_f32_16x16x32_bf16 v[138:141], v[238:241], v[184:187], v[138:141]
	v_mfma_f32_16x16x32_bf16 v[74:77], v[238:241], v[198:201], v[74:77]
	global_load_dwordx4 v[102:105], v170, s[100:101] offset:256
	v_mfma_f32_16x16x32_bf16 v[42:45], v[238:241], v[210:213], v[42:45]
	v_mfma_f32_16x16x32_bf16 v[10:13], v[238:241], v[214:217], v[10:13]
	s_waitcnt vmcnt(7)
	ds_write_b128 v171, v[98:101] offset:40960
	v_mfma_f32_16x16x32_bf16 v[134:137], v[242:245], v[184:187], v[134:137]
	v_mfma_f32_16x16x32_bf16 v[70:73], v[242:245], v[198:201], v[70:73]
	v_add_u32_e32 v98, s34, v170
	global_load_dwordx4 v[98:101], v98, s[100:101] offset:256
	v_mfma_f32_16x16x32_bf16 v[38:41], v[242:245], v[210:213], v[38:41]
	v_mfma_f32_16x16x32_bf16 v[6:9], v[242:245], v[214:217], v[6:9]
	s_waitcnt vmcnt(7)
	ds_write_b128 v171, v[118:121] offset:49152
	s_waitcnt lgkmcnt(7)
	v_mfma_f32_16x16x32_bf16 v[126:129], v[246:249], v[184:187], v[126:129]
	v_mfma_f32_16x16x32_bf16 v[62:65], v[246:249], v[198:201], v[62:65]
	v_add_u32_e32 v118, s35, v170
	global_load_dwordx4 v[118:121], v118, s[100:101] offset:256
	v_mfma_f32_16x16x32_bf16 v[30:33], v[246:249], v[210:213], v[30:33]
	v_mfma_f32_16x16x32_bf16 v[2:5], v[246:249], v[214:217], v[2:5]
	s_waitcnt vmcnt(7)
	ds_write_b128 v171, v[110:113] offset:57344
	v_add_u32_e32 v110, s36, v170
	global_load_dwordx4 v[110:113], v110, s[100:101] offset:256
	v_add_u32_e32 v168, 0x80, v168
	v_add_u32_e32 v170, 0x80, v170
	s_waitcnt lgkmcnt(0)
	s_barrier
	s_cmp_eq_u32 s14, 16
	s_mov_b32 s4, s14
	s_cbranch_scc0 .LBB0_665
	s_waitcnt vmcnt(3)
	v_or_b32_e32 v88, s7, v207
	v_add_u32_e32 v94, s6, v205
	v_mov_b64_e32 v[86:87], s[12:13]
	v_ashrrev_i32_e32 v89, 31, v88
	v_mad_i64_i32 v[90:91], s[6:7], v94, s8, v[86:87]
	v_lshlrev_b64 v[88:89], 1, v[88:89]
	v_lshl_add_u64 v[90:91], v[90:91], 0, v[88:89]
	v_cvt_pk_bf16_f32 v93, v160, v161
	v_cvt_pk_bf16_f32 v92, v158, v159
	s_waitcnt vmcnt(0)
	global_store_dwordx2 v[90:91], v[92:93], off
	v_cvt_pk_bf16_f32 v93, v156, v157
	v_cvt_pk_bf16_f32 v92, v154, v155
	global_store_dwordx2 v[90:91], v[92:93], off offset:32
	v_cvt_pk_bf16_f32 v93, v152, v153
	v_cvt_pk_bf16_f32 v92, v150, v151
	global_store_dwordx2 v[90:91], v[92:93], off offset:64
	v_cvt_pk_bf16_f32 v93, v148, v149
	v_cvt_pk_bf16_f32 v92, v146, v147
	global_store_dwordx2 v[90:91], v[92:93], off offset:96
	v_cvt_pk_bf16_f32 v93, v144, v145
	v_cvt_pk_bf16_f32 v92, v142, v143
	global_store_dwordx2 v[90:91], v[92:93], off offset:128
	v_cvt_pk_bf16_f32 v93, v140, v141
	v_cvt_pk_bf16_f32 v92, v138, v139
	global_store_dwordx2 v[90:91], v[92:93], off offset:160
	v_cvt_pk_bf16_f32 v93, v136, v137
	v_cvt_pk_bf16_f32 v92, v134, v135
	global_store_dwordx2 v[90:91], v[92:93], off offset:192
	v_cvt_pk_bf16_f32 v93, v128, v129
	v_cvt_pk_bf16_f32 v92, v126, v127
	global_store_dwordx2 v[90:91], v[92:93], off offset:224
	v_or_b32_e32 v90, 16, v94
	v_mad_i64_i32 v[90:91], s[6:7], v90, s8, v[86:87]
	v_lshl_add_u64 v[90:91], v[90:91], 0, v[88:89]
	v_cvt_pk_bf16_f32 v93, v132, v133
	v_cvt_pk_bf16_f32 v92, v130, v131
	global_store_dwordx2 v[90:91], v[92:93], off
	v_cvt_pk_bf16_f32 v93, v124, v125
	v_cvt_pk_bf16_f32 v92, v122, v123
	global_store_dwordx2 v[90:91], v[92:93], off offset:32
	v_and_b32_sdwa v93, v114, v177 dst_sel:DWORD dst_unused:UNUSED_PAD src0_sel:WORD_1 src1_sel:DWORD
	v_add3_u32 v95, v114, v93, s28
	v_and_b32_sdwa v96, v115, v177 dst_sel:DWORD dst_unused:UNUSED_PAD src0_sel:WORD_1 src1_sel:DWORD
	v_add3_u32 v96, v115, v96, s28
	v_and_b32_e32 v96, 0xffff0000, v96
	v_cvt_pk_bf16_f32 v93, v116, v117
	v_or_b32_sdwa v92, v96, v95 dst_sel:DWORD dst_unused:UNUSED_PAD src0_sel:DWORD src1_sel:WORD_1
	global_store_dwordx2 v[90:91], v[92:93], off offset:64
	v_and_b32_sdwa v92, v84, v177 dst_sel:DWORD dst_unused:UNUSED_PAD src0_sel:WORD_1 src1_sel:DWORD
	v_and_b32_sdwa v93, v82, v177 dst_sel:DWORD dst_unused:UNUSED_PAD src0_sel:WORD_1 src1_sel:DWORD
	v_add3_u32 v82, v82, v93, s28
	v_add3_u32 v84, v84, v92, s28
	v_and_b32_sdwa v92, v85, v177 dst_sel:DWORD dst_unused:UNUSED_PAD src0_sel:WORD_1 src1_sel:DWORD
	v_and_b32_sdwa v93, v83, v177 dst_sel:DWORD dst_unused:UNUSED_PAD src0_sel:WORD_1 src1_sel:DWORD
	v_add3_u32 v85, v85, v92, s28
	v_add3_u32 v83, v83, v93, s28
	v_and_b32_e32 v85, 0xffff0000, v85
	v_and_b32_e32 v92, 0xffff0000, v83
	v_or_b32_sdwa v83, v85, v84 dst_sel:DWORD dst_unused:UNUSED_PAD src0_sel:DWORD src1_sel:WORD_1
	v_or_b32_sdwa v82, v92, v82 dst_sel:DWORD dst_unused:UNUSED_PAD src0_sel:DWORD src1_sel:WORD_1
	global_store_dwordx2 v[90:91], v[82:83], off offset:96
	v_and_b32_sdwa v82, v80, v177 dst_sel:DWORD dst_unused:UNUSED_PAD src0_sel:WORD_1 src1_sel:DWORD
	v_and_b32_sdwa v83, v78, v177 dst_sel:DWORD dst_unused:UNUSED_PAD src0_sel:WORD_1 src1_sel:DWORD
	v_add3_u32 v78, v78, v83, s28
	v_add3_u32 v80, v80, v82, s28
	v_and_b32_sdwa v82, v81, v177 dst_sel:DWORD dst_unused:UNUSED_PAD src0_sel:WORD_1 src1_sel:DWORD
	v_and_b32_sdwa v83, v79, v177 dst_sel:DWORD dst_unused:UNUSED_PAD src0_sel:WORD_1 src1_sel:DWORD
	v_add3_u32 v81, v81, v82, s28
	v_add3_u32 v79, v79, v83, s28
	v_and_b32_e32 v81, 0xffff0000, v81
	v_and_b32_e32 v82, 0xffff0000, v79
	v_or_b32_sdwa v79, v81, v80 dst_sel:DWORD dst_unused:UNUSED_PAD src0_sel:DWORD src1_sel:WORD_1
	v_or_b32_sdwa v78, v82, v78 dst_sel:DWORD dst_unused:UNUSED_PAD src0_sel:DWORD src1_sel:WORD_1
	global_store_dwordx2 v[90:91], v[78:79], off offset:128
	v_and_b32_sdwa v78, v76, v177 dst_sel:DWORD dst_unused:UNUSED_PAD src0_sel:WORD_1 src1_sel:DWORD
	v_and_b32_sdwa v79, v74, v177 dst_sel:DWORD dst_unused:UNUSED_PAD src0_sel:WORD_1 src1_sel:DWORD
	v_add3_u32 v74, v74, v79, s28
	v_add3_u32 v76, v76, v78, s28
	v_and_b32_sdwa v78, v77, v177 dst_sel:DWORD dst_unused:UNUSED_PAD src0_sel:WORD_1 src1_sel:DWORD
	v_and_b32_sdwa v79, v75, v177 dst_sel:DWORD dst_unused:UNUSED_PAD src0_sel:WORD_1 src1_sel:DWORD
	v_add3_u32 v77, v77, v78, s28
	v_add3_u32 v75, v75, v79, s28
	v_and_b32_e32 v77, 0xffff0000, v77
	v_and_b32_e32 v78, 0xffff0000, v75
	v_or_b32_sdwa v75, v77, v76 dst_sel:DWORD dst_unused:UNUSED_PAD src0_sel:DWORD src1_sel:WORD_1
	v_or_b32_sdwa v74, v78, v74 dst_sel:DWORD dst_unused:UNUSED_PAD src0_sel:DWORD src1_sel:WORD_1
	global_store_dwordx2 v[90:91], v[74:75], off offset:160
	v_and_b32_sdwa v74, v72, v177 dst_sel:DWORD dst_unused:UNUSED_PAD src0_sel:WORD_1 src1_sel:DWORD
	v_and_b32_sdwa v75, v70, v177 dst_sel:DWORD dst_unused:UNUSED_PAD src0_sel:WORD_1 src1_sel:DWORD
	v_add3_u32 v70, v70, v75, s28
	v_add3_u32 v72, v72, v74, s28
	v_and_b32_sdwa v74, v73, v177 dst_sel:DWORD dst_unused:UNUSED_PAD src0_sel:WORD_1 src1_sel:DWORD
	v_and_b32_sdwa v75, v71, v177 dst_sel:DWORD dst_unused:UNUSED_PAD src0_sel:WORD_1 src1_sel:DWORD
	v_add3_u32 v73, v73, v74, s28
	v_add3_u32 v71, v71, v75, s28
	v_and_b32_e32 v73, 0xffff0000, v73
	v_and_b32_e32 v74, 0xffff0000, v71
	v_or_b32_sdwa v71, v73, v72 dst_sel:DWORD dst_unused:UNUSED_PAD src0_sel:DWORD src1_sel:WORD_1
	v_or_b32_sdwa v70, v74, v70 dst_sel:DWORD dst_unused:UNUSED_PAD src0_sel:DWORD src1_sel:WORD_1
	global_store_dwordx2 v[90:91], v[70:71], off offset:192
	v_cvt_pk_bf16_f32 v64, v64, v65
	v_and_b32_sdwa v71, v62, v177 dst_sel:DWORD dst_unused:UNUSED_PAD src0_sel:WORD_1 src1_sel:DWORD
	v_add3_u32 v62, v62, v71, s28
	v_and_b32_sdwa v71, v63, v177 dst_sel:DWORD dst_unused:UNUSED_PAD src0_sel:WORD_1 src1_sel:DWORD
	v_add3_u32 v63, v63, v71, s28
	v_and_b32_e32 v70, 0xffff0000, v63
	v_mov_b32_e32 v63, v64
	v_cvt_pk_bf16_f32 v64, v68, v69
	v_and_b32_sdwa v65, v66, v177 dst_sel:DWORD dst_unused:UNUSED_PAD src0_sel:WORD_1 src1_sel:DWORD
	v_or_b32_sdwa v62, v70, v62 dst_sel:DWORD dst_unused:UNUSED_PAD src0_sel:DWORD src1_sel:WORD_1
	v_add3_u32 v66, v66, v65, s28
	v_and_b32_sdwa v68, v67, v177 dst_sel:DWORD dst_unused:UNUSED_PAD src0_sel:WORD_1 src1_sel:DWORD
	global_store_dwordx2 v[90:91], v[62:63], off offset:224
	v_or_b32_e32 v62, 32, v94
	v_add3_u32 v67, v67, v68, s28
	v_mad_i64_i32 v[62:63], s[6:7], v62, s8, v[86:87]
	v_and_b32_e32 v67, 0xffff0000, v67
	v_lshl_add_u64 v[62:63], v[62:63], 0, v[88:89]
	v_mov_b32_e32 v65, v64
	v_or_b32_sdwa v64, v67, v66 dst_sel:DWORD dst_unused:UNUSED_PAD src0_sel:DWORD src1_sel:WORD_1
	global_store_dwordx2 v[62:63], v[64:65], off
	v_and_b32_sdwa v64, v60, v177 dst_sel:DWORD dst_unused:UNUSED_PAD src0_sel:WORD_1 src1_sel:DWORD
	v_and_b32_sdwa v65, v58, v177 dst_sel:DWORD dst_unused:UNUSED_PAD src0_sel:WORD_1 src1_sel:DWORD
	v_add3_u32 v58, v58, v65, s28
	v_add3_u32 v60, v60, v64, s28
	v_and_b32_sdwa v64, v61, v177 dst_sel:DWORD dst_unused:UNUSED_PAD src0_sel:WORD_1 src1_sel:DWORD
	v_and_b32_sdwa v65, v59, v177 dst_sel:DWORD dst_unused:UNUSED_PAD src0_sel:WORD_1 src1_sel:DWORD
	v_add3_u32 v61, v61, v64, s28
	v_add3_u32 v59, v59, v65, s28
	v_and_b32_e32 v61, 0xffff0000, v61
	v_and_b32_e32 v64, 0xffff0000, v59
	v_or_b32_sdwa v59, v61, v60 dst_sel:DWORD dst_unused:UNUSED_PAD src0_sel:DWORD src1_sel:WORD_1
	v_or_b32_sdwa v58, v64, v58 dst_sel:DWORD dst_unused:UNUSED_PAD src0_sel:DWORD src1_sel:WORD_1
	global_store_dwordx2 v[62:63], v[58:59], off offset:32
	v_and_b32_sdwa v58, v56, v177 dst_sel:DWORD dst_unused:UNUSED_PAD src0_sel:WORD_1 src1_sel:DWORD
	v_and_b32_sdwa v59, v54, v177 dst_sel:DWORD dst_unused:UNUSED_PAD src0_sel:WORD_1 src1_sel:DWORD
	v_add3_u32 v54, v54, v59, s28
	v_add3_u32 v56, v56, v58, s28
	v_and_b32_sdwa v58, v57, v177 dst_sel:DWORD dst_unused:UNUSED_PAD src0_sel:WORD_1 src1_sel:DWORD
	v_and_b32_sdwa v59, v55, v177 dst_sel:DWORD dst_unused:UNUSED_PAD src0_sel:WORD_1 src1_sel:DWORD
	v_add3_u32 v57, v57, v58, s28
	v_add3_u32 v55, v55, v59, s28
	v_and_b32_e32 v57, 0xffff0000, v57
	v_and_b32_e32 v58, 0xffff0000, v55
	v_or_b32_sdwa v55, v57, v56 dst_sel:DWORD dst_unused:UNUSED_PAD src0_sel:DWORD src1_sel:WORD_1
	v_or_b32_sdwa v54, v58, v54 dst_sel:DWORD dst_unused:UNUSED_PAD src0_sel:DWORD src1_sel:WORD_1
	global_store_dwordx2 v[62:63], v[54:55], off offset:64
	v_and_b32_sdwa v54, v52, v177 dst_sel:DWORD dst_unused:UNUSED_PAD src0_sel:WORD_1 src1_sel:DWORD
	v_and_b32_sdwa v55, v50, v177 dst_sel:DWORD dst_unused:UNUSED_PAD src0_sel:WORD_1 src1_sel:DWORD
	v_add3_u32 v50, v50, v55, s28
	v_add3_u32 v52, v52, v54, s28
	v_and_b32_sdwa v54, v53, v177 dst_sel:DWORD dst_unused:UNUSED_PAD src0_sel:WORD_1 src1_sel:DWORD
	v_and_b32_sdwa v55, v51, v177 dst_sel:DWORD dst_unused:UNUSED_PAD src0_sel:WORD_1 src1_sel:DWORD
	v_add3_u32 v53, v53, v54, s28
	v_add3_u32 v51, v51, v55, s28
	v_and_b32_e32 v53, 0xffff0000, v53
	v_and_b32_e32 v54, 0xffff0000, v51
	v_or_b32_sdwa v51, v53, v52 dst_sel:DWORD dst_unused:UNUSED_PAD src0_sel:DWORD src1_sel:WORD_1
	v_or_b32_sdwa v50, v54, v50 dst_sel:DWORD dst_unused:UNUSED_PAD src0_sel:DWORD src1_sel:WORD_1
	global_store_dwordx2 v[62:63], v[50:51], off offset:96
	v_and_b32_sdwa v50, v48, v177 dst_sel:DWORD dst_unused:UNUSED_PAD src0_sel:WORD_1 src1_sel:DWORD
	v_and_b32_sdwa v51, v46, v177 dst_sel:DWORD dst_unused:UNUSED_PAD src0_sel:WORD_1 src1_sel:DWORD
	v_add3_u32 v46, v46, v51, s28
	v_add3_u32 v48, v48, v50, s28
	v_and_b32_sdwa v50, v49, v177 dst_sel:DWORD dst_unused:UNUSED_PAD src0_sel:WORD_1 src1_sel:DWORD
	v_and_b32_sdwa v51, v47, v177 dst_sel:DWORD dst_unused:UNUSED_PAD src0_sel:WORD_1 src1_sel:DWORD
	v_add3_u32 v49, v49, v50, s28
	v_add3_u32 v47, v47, v51, s28
	v_and_b32_e32 v49, 0xffff0000, v49
	v_and_b32_e32 v50, 0xffff0000, v47
	v_or_b32_sdwa v47, v49, v48 dst_sel:DWORD dst_unused:UNUSED_PAD src0_sel:DWORD src1_sel:WORD_1
	v_or_b32_sdwa v46, v50, v46 dst_sel:DWORD dst_unused:UNUSED_PAD src0_sel:DWORD src1_sel:WORD_1
	global_store_dwordx2 v[62:63], v[46:47], off offset:128
	v_and_b32_sdwa v46, v44, v177 dst_sel:DWORD dst_unused:UNUSED_PAD src0_sel:WORD_1 src1_sel:DWORD
	v_and_b32_sdwa v47, v42, v177 dst_sel:DWORD dst_unused:UNUSED_PAD src0_sel:WORD_1 src1_sel:DWORD
	v_add3_u32 v42, v42, v47, s28
	v_add3_u32 v44, v44, v46, s28
	v_and_b32_sdwa v46, v45, v177 dst_sel:DWORD dst_unused:UNUSED_PAD src0_sel:WORD_1 src1_sel:DWORD
	v_and_b32_sdwa v47, v43, v177 dst_sel:DWORD dst_unused:UNUSED_PAD src0_sel:WORD_1 src1_sel:DWORD
	v_add3_u32 v45, v45, v46, s28
	v_add3_u32 v43, v43, v47, s28
	v_and_b32_e32 v45, 0xffff0000, v45
	v_and_b32_e32 v46, 0xffff0000, v43
	v_or_b32_sdwa v43, v45, v44 dst_sel:DWORD dst_unused:UNUSED_PAD src0_sel:DWORD src1_sel:WORD_1
	v_or_b32_sdwa v42, v46, v42 dst_sel:DWORD dst_unused:UNUSED_PAD src0_sel:DWORD src1_sel:WORD_1
	global_store_dwordx2 v[62:63], v[42:43], off offset:160
	v_and_b32_sdwa v42, v40, v177 dst_sel:DWORD dst_unused:UNUSED_PAD src0_sel:WORD_1 src1_sel:DWORD
	v_and_b32_sdwa v43, v38, v177 dst_sel:DWORD dst_unused:UNUSED_PAD src0_sel:WORD_1 src1_sel:DWORD
	v_add3_u32 v38, v38, v43, s28
	v_add3_u32 v40, v40, v42, s28
	v_and_b32_sdwa v42, v41, v177 dst_sel:DWORD dst_unused:UNUSED_PAD src0_sel:WORD_1 src1_sel:DWORD
	v_and_b32_sdwa v43, v39, v177 dst_sel:DWORD dst_unused:UNUSED_PAD src0_sel:WORD_1 src1_sel:DWORD
	v_add3_u32 v41, v41, v42, s28
	v_add3_u32 v39, v39, v43, s28
	v_and_b32_e32 v41, 0xffff0000, v41
	v_and_b32_e32 v42, 0xffff0000, v39
	v_or_b32_sdwa v39, v41, v40 dst_sel:DWORD dst_unused:UNUSED_PAD src0_sel:DWORD src1_sel:WORD_1
	v_or_b32_sdwa v38, v42, v38 dst_sel:DWORD dst_unused:UNUSED_PAD src0_sel:DWORD src1_sel:WORD_1
	global_store_dwordx2 v[62:63], v[38:39], off offset:192
	v_cvt_pk_bf16_f32 v32, v32, v33
	v_and_b32_sdwa v39, v30, v177 dst_sel:DWORD dst_unused:UNUSED_PAD src0_sel:WORD_1 src1_sel:DWORD
	v_add3_u32 v30, v30, v39, s28
	v_and_b32_sdwa v39, v31, v177 dst_sel:DWORD dst_unused:UNUSED_PAD src0_sel:WORD_1 src1_sel:DWORD
	v_add3_u32 v31, v31, v39, s28
	v_and_b32_e32 v38, 0xffff0000, v31
	v_mov_b32_e32 v31, v32
	v_cvt_pk_bf16_f32 v32, v36, v37
	v_and_b32_sdwa v33, v34, v177 dst_sel:DWORD dst_unused:UNUSED_PAD src0_sel:WORD_1 src1_sel:DWORD
	v_or_b32_sdwa v30, v38, v30 dst_sel:DWORD dst_unused:UNUSED_PAD src0_sel:DWORD src1_sel:WORD_1
	v_add3_u32 v34, v34, v33, s28
	v_and_b32_sdwa v36, v35, v177 dst_sel:DWORD dst_unused:UNUSED_PAD src0_sel:WORD_1 src1_sel:DWORD
	global_store_dwordx2 v[62:63], v[30:31], off offset:224
	v_or_b32_e32 v30, 48, v94
	v_add3_u32 v35, v35, v36, s28
	v_mad_i64_i32 v[30:31], s[6:7], v30, s8, v[86:87]
	v_and_b32_e32 v35, 0xffff0000, v35
	v_lshl_add_u64 v[30:31], v[30:31], 0, v[88:89]
	v_mov_b32_e32 v33, v32
	v_or_b32_sdwa v32, v35, v34 dst_sel:DWORD dst_unused:UNUSED_PAD src0_sel:DWORD src1_sel:WORD_1
	global_store_dwordx2 v[30:31], v[32:33], off
	v_and_b32_sdwa v32, v28, v177 dst_sel:DWORD dst_unused:UNUSED_PAD src0_sel:WORD_1 src1_sel:DWORD
	v_and_b32_sdwa v33, v26, v177 dst_sel:DWORD dst_unused:UNUSED_PAD src0_sel:WORD_1 src1_sel:DWORD
	v_add3_u32 v26, v26, v33, s28
	v_add3_u32 v28, v28, v32, s28
	v_and_b32_sdwa v32, v29, v177 dst_sel:DWORD dst_unused:UNUSED_PAD src0_sel:WORD_1 src1_sel:DWORD
	v_and_b32_sdwa v33, v27, v177 dst_sel:DWORD dst_unused:UNUSED_PAD src0_sel:WORD_1 src1_sel:DWORD
	v_add3_u32 v29, v29, v32, s28
	v_add3_u32 v27, v27, v33, s28
	v_and_b32_e32 v29, 0xffff0000, v29
	v_and_b32_e32 v32, 0xffff0000, v27
	v_or_b32_sdwa v27, v29, v28 dst_sel:DWORD dst_unused:UNUSED_PAD src0_sel:DWORD src1_sel:WORD_1
	v_or_b32_sdwa v26, v32, v26 dst_sel:DWORD dst_unused:UNUSED_PAD src0_sel:DWORD src1_sel:WORD_1
	global_store_dwordx2 v[30:31], v[26:27], off offset:32
	v_and_b32_sdwa v26, v24, v177 dst_sel:DWORD dst_unused:UNUSED_PAD src0_sel:WORD_1 src1_sel:DWORD
	v_and_b32_sdwa v27, v22, v177 dst_sel:DWORD dst_unused:UNUSED_PAD src0_sel:WORD_1 src1_sel:DWORD
	v_add3_u32 v22, v22, v27, s28
	v_add3_u32 v24, v24, v26, s28
	v_and_b32_sdwa v26, v25, v177 dst_sel:DWORD dst_unused:UNUSED_PAD src0_sel:WORD_1 src1_sel:DWORD
	v_and_b32_sdwa v27, v23, v177 dst_sel:DWORD dst_unused:UNUSED_PAD src0_sel:WORD_1 src1_sel:DWORD
	v_add3_u32 v25, v25, v26, s28
	v_add3_u32 v23, v23, v27, s28
	v_and_b32_e32 v25, 0xffff0000, v25
	v_and_b32_e32 v26, 0xffff0000, v23
	v_or_b32_sdwa v23, v25, v24 dst_sel:DWORD dst_unused:UNUSED_PAD src0_sel:DWORD src1_sel:WORD_1
	v_or_b32_sdwa v22, v26, v22 dst_sel:DWORD dst_unused:UNUSED_PAD src0_sel:DWORD src1_sel:WORD_1
	global_store_dwordx2 v[30:31], v[22:23], off offset:64
	v_and_b32_sdwa v22, v20, v177 dst_sel:DWORD dst_unused:UNUSED_PAD src0_sel:WORD_1 src1_sel:DWORD
	v_and_b32_sdwa v23, v18, v177 dst_sel:DWORD dst_unused:UNUSED_PAD src0_sel:WORD_1 src1_sel:DWORD
	v_add3_u32 v18, v18, v23, s28
	v_add3_u32 v20, v20, v22, s28
	v_and_b32_sdwa v22, v21, v177 dst_sel:DWORD dst_unused:UNUSED_PAD src0_sel:WORD_1 src1_sel:DWORD
	v_and_b32_sdwa v23, v19, v177 dst_sel:DWORD dst_unused:UNUSED_PAD src0_sel:WORD_1 src1_sel:DWORD
	v_add3_u32 v21, v21, v22, s28
	v_add3_u32 v19, v19, v23, s28
	v_and_b32_e32 v21, 0xffff0000, v21
	v_and_b32_e32 v22, 0xffff0000, v19
	v_or_b32_sdwa v19, v21, v20 dst_sel:DWORD dst_unused:UNUSED_PAD src0_sel:DWORD src1_sel:WORD_1
	v_or_b32_sdwa v18, v22, v18 dst_sel:DWORD dst_unused:UNUSED_PAD src0_sel:DWORD src1_sel:WORD_1
	global_store_dwordx2 v[30:31], v[18:19], off offset:96
	v_and_b32_sdwa v18, v16, v177 dst_sel:DWORD dst_unused:UNUSED_PAD src0_sel:WORD_1 src1_sel:DWORD
	v_and_b32_sdwa v19, v14, v177 dst_sel:DWORD dst_unused:UNUSED_PAD src0_sel:WORD_1 src1_sel:DWORD
	v_add3_u32 v14, v14, v19, s28
	v_add3_u32 v16, v16, v18, s28
	v_and_b32_sdwa v18, v17, v177 dst_sel:DWORD dst_unused:UNUSED_PAD src0_sel:WORD_1 src1_sel:DWORD
	v_and_b32_sdwa v19, v15, v177 dst_sel:DWORD dst_unused:UNUSED_PAD src0_sel:WORD_1 src1_sel:DWORD
	v_add3_u32 v17, v17, v18, s28
	v_add3_u32 v15, v15, v19, s28
	v_and_b32_e32 v17, 0xffff0000, v17
	v_and_b32_e32 v18, 0xffff0000, v15
	v_or_b32_sdwa v15, v17, v16 dst_sel:DWORD dst_unused:UNUSED_PAD src0_sel:DWORD src1_sel:WORD_1
	v_or_b32_sdwa v14, v18, v14 dst_sel:DWORD dst_unused:UNUSED_PAD src0_sel:DWORD src1_sel:WORD_1
	global_store_dwordx2 v[30:31], v[14:15], off offset:128
	v_and_b32_sdwa v14, v12, v177 dst_sel:DWORD dst_unused:UNUSED_PAD src0_sel:WORD_1 src1_sel:DWORD
	v_and_b32_sdwa v15, v10, v177 dst_sel:DWORD dst_unused:UNUSED_PAD src0_sel:WORD_1 src1_sel:DWORD
	v_add3_u32 v10, v10, v15, s28
	v_add3_u32 v12, v12, v14, s28
	v_and_b32_sdwa v14, v13, v177 dst_sel:DWORD dst_unused:UNUSED_PAD src0_sel:WORD_1 src1_sel:DWORD
	v_and_b32_sdwa v15, v11, v177 dst_sel:DWORD dst_unused:UNUSED_PAD src0_sel:WORD_1 src1_sel:DWORD
	v_add3_u32 v13, v13, v14, s28
	v_add3_u32 v11, v11, v15, s28
	v_and_b32_e32 v13, 0xffff0000, v13
	v_and_b32_e32 v14, 0xffff0000, v11
	v_or_b32_sdwa v11, v13, v12 dst_sel:DWORD dst_unused:UNUSED_PAD src0_sel:DWORD src1_sel:WORD_1
	v_or_b32_sdwa v10, v14, v10 dst_sel:DWORD dst_unused:UNUSED_PAD src0_sel:DWORD src1_sel:WORD_1
	global_store_dwordx2 v[30:31], v[10:11], off offset:160
	v_and_b32_sdwa v10, v8, v177 dst_sel:DWORD dst_unused:UNUSED_PAD src0_sel:WORD_1 src1_sel:DWORD
	v_and_b32_sdwa v11, v6, v177 dst_sel:DWORD dst_unused:UNUSED_PAD src0_sel:WORD_1 src1_sel:DWORD
	v_add3_u32 v6, v6, v11, s28
	v_add3_u32 v8, v8, v10, s28
	v_and_b32_sdwa v10, v9, v177 dst_sel:DWORD dst_unused:UNUSED_PAD src0_sel:WORD_1 src1_sel:DWORD
	v_and_b32_sdwa v11, v7, v177 dst_sel:DWORD dst_unused:UNUSED_PAD src0_sel:WORD_1 src1_sel:DWORD
	v_add3_u32 v9, v9, v10, s28
	v_add3_u32 v7, v7, v11, s28
	v_and_b32_e32 v9, 0xffff0000, v9
	v_and_b32_e32 v10, 0xffff0000, v7
	v_or_b32_sdwa v7, v9, v8 dst_sel:DWORD dst_unused:UNUSED_PAD src0_sel:DWORD src1_sel:WORD_1
	v_or_b32_sdwa v6, v10, v6 dst_sel:DWORD dst_unused:UNUSED_PAD src0_sel:DWORD src1_sel:WORD_1
	global_store_dwordx2 v[30:31], v[6:7], off offset:192
	v_and_b32_sdwa v6, v4, v177 dst_sel:DWORD dst_unused:UNUSED_PAD src0_sel:WORD_1 src1_sel:DWORD
	v_and_b32_sdwa v7, v2, v177 dst_sel:DWORD dst_unused:UNUSED_PAD src0_sel:WORD_1 src1_sel:DWORD
	v_add3_u32 v2, v2, v7, s28
	v_add3_u32 v4, v4, v6, s28
	v_and_b32_sdwa v6, v5, v177 dst_sel:DWORD dst_unused:UNUSED_PAD src0_sel:WORD_1 src1_sel:DWORD
	v_and_b32_sdwa v7, v3, v177 dst_sel:DWORD dst_unused:UNUSED_PAD src0_sel:WORD_1 src1_sel:DWORD
	v_add3_u32 v5, v5, v6, s28
	v_add3_u32 v3, v3, v7, s28
	v_and_b32_e32 v5, 0xffff0000, v5
	v_and_b32_e32 v6, 0xffff0000, v3
	s_add_i32 s11, s11, s10
	v_or_b32_sdwa v3, v5, v4 dst_sel:DWORD dst_unused:UNUSED_PAD src0_sel:DWORD src1_sel:WORD_1
	v_or_b32_sdwa v2, v6, v2 dst_sel:DWORD dst_unused:UNUSED_PAD src0_sel:DWORD src1_sel:WORD_1
	s_cmpk_gt_i32 s11, 0x3ef
	global_store_dwordx2 v[30:31], v[2:3], off offset:224
	s_cbranch_scc0 .LBB0_664

.LBB0_741:
	s_waitcnt vmcnt(29)
	v_lshlrev_b32_e32 v116, 16, v104
	v_lshlrev_b32_e32 v112, 16, v76
	v_lshlrev_b32_e32 v113, 16, v103
	v_mov_b32_e32 v76, v116
	s_waitcnt vmcnt(28)
	v_lshlrev_b32_e32 v115, 16, v108
	v_mov_b32_e32 v114, v113
	v_pk_mul_f32 v[76:77], v[74:75], v[76:77]
	s_waitcnt vmcnt(27)
	v_lshlrev_b32_e32 v117, 16, v109
	v_mov_b32_e32 v108, v112
	v_mov_b32_e32 v109, v116
	v_pk_fma_f32 v[76:77], v[74:75], v[112:113], v[76:77] op_sel:[0,0,1] op_sel_hi:[1,1,0]
	v_pk_mul_f32 v[112:113], v[74:75], v[114:115] op_sel_hi:[0,1]
	v_mov_b32_e32 v104, v75
	v_pk_fma_f32 v[76:77], v[0:1], v[114:115], v[76:77] op_sel_hi:[0,1,1]
	s_waitcnt vmcnt(15)
	v_pk_fma_f32 v[108:109], v[104:105], v[108:109], v[112:113] op_sel_hi:[0,1,1]
	v_pk_fma_f32 v[108:109], v[0:1], v[116:117], v[108:109] op_sel_hi:[0,1,1]
	v_cvt_pk_bf16_f32 v77, v77, v109
	v_cvt_pk_bf16_f32 v76, v76, v108
	v_mov_b32_e32 v109, v77
	v_lshlrev_b32_e32 v77, 16, v110
	v_mov_b32_e32 v108, v76
	v_lshlrev_b32_e32 v76, 16, v91
	v_lshlrev_b32_e32 v111, 16, v94
	v_mov_b32_e32 v116, v77
	v_mov_b32_e32 v110, v76
	v_mov_b32_e32 v118, v117
	v_mov_b32_e32 v119, v111
	v_pk_mul_f32 v[116:117], v[74:75], v[116:117]
	v_lshlrev_b32_e32 v113, 16, v107
	v_mov_b32_e32 v112, v111
	v_pk_mov_b32 v[114:115], v[114:115], v[110:111] op_sel:[1,0]
	v_pk_mul_f32 v[118:119], v[74:75], v[118:119] op_sel_hi:[0,1]
	v_pk_fma_f32 v[110:111], v[74:75], v[110:111], v[116:117] op_sel:[0,0,1] op_sel_hi:[1,1,0]
	v_pk_fma_f32 v[114:115], v[104:105], v[114:115], v[118:119] op_sel_hi:[0,1,1]
	v_pk_fma_f32 v[110:111], v[0:1], v[112:113], v[110:111] op_sel_hi:[0,1,1]
	v_pk_fma_f32 v[114:115], v[0:1], v[76:77], v[114:115] op_sel_hi:[0,1,1]
	v_cvt_pk_bf16_f32 v94, v114, v110
	v_and_b32_sdwa v91, v115, v177 dst_sel:DWORD dst_unused:UNUSED_PAD src0_sel:WORD_1 src1_sel:DWORD
	v_lshlrev_b32_e32 v114, 16, v95
	v_lshlrev_b32_e32 v95, 16, v97
	v_add3_u32 v91, v115, v91, s28
	v_mov_b32_e32 v110, v94
	v_lshlrev_b32_e32 v115, 16, v101
	v_mov_b32_e32 v94, v114
	v_mov_b32_e32 v116, v113
	v_mov_b32_e32 v117, v95
	v_and_b32_sdwa v103, v111, v177 dst_sel:DWORD dst_unused:UNUSED_PAD src0_sel:WORD_1 src1_sel:DWORD
	v_pk_mov_b32 v[76:77], v[76:77], v[94:95] op_sel:[1,0]
	v_pk_mul_f32 v[116:117], v[74:75], v[116:117] op_sel_hi:[0,1]
	v_mov_b32_e32 v112, v115
	v_add3_u32 v103, v111, v103, s28
	v_pk_fma_f32 v[76:77], v[104:105], v[76:77], v[116:117] op_sel_hi:[0,1,1]
	v_pk_mul_f32 v[112:113], v[74:75], v[112:113]
	v_and_b32_e32 v103, 0xffff0000, v103
	v_lshlrev_b32_e32 v101, 16, v100
	v_mov_b32_e32 v100, v95
	v_pk_fma_f32 v[76:77], v[0:1], v[114:115], v[76:77] op_sel_hi:[0,1,1]
	v_pk_fma_f32 v[94:95], v[74:75], v[94:95], v[112:113] op_sel:[0,0,1] op_sel_hi:[1,1,0]
	v_or_b32_sdwa v111, v103, v91 dst_sel:DWORD dst_unused:UNUSED_PAD src0_sel:DWORD src1_sel:WORD_1
	v_pk_fma_f32 v[94:95], v[0:1], v[100:101], v[94:95] op_sel_hi:[0,1,1]
	v_cvt_pk_bf16_f32 v77, v77, v95
	v_cvt_pk_bf16_f32 v76, v76, v94
	v_mov_b32_e32 v113, v77
	v_lshlrev_b32_e32 v77, 16, v106
	v_mov_b32_e32 v112, v76
	v_lshlrev_b32_e32 v76, 16, v86
	v_lshlrev_b32_e32 v95, 16, v88
	v_mov_b32_e32 v100, v77
	v_mov_b32_e32 v94, v76
	v_mov_b32_e32 v116, v101
	v_mov_b32_e32 v117, v95
	v_pk_mul_f32 v[100:101], v[74:75], v[100:101]
	v_lshlrev_b32_e32 v107, 16, v105
	v_mov_b32_e32 v106, v95
	v_pk_mov_b32 v[114:115], v[114:115], v[94:95] op_sel:[1,0]
	v_pk_mul_f32 v[116:117], v[74:75], v[116:117] op_sel_hi:[0,1]
	v_pk_fma_f32 v[94:95], v[74:75], v[94:95], v[100:101] op_sel:[0,0,1] op_sel_hi:[1,1,0]
	v_pk_fma_f32 v[114:115], v[104:105], v[114:115], v[116:117] op_sel_hi:[0,1,1]
	v_pk_fma_f32 v[94:95], v[0:1], v[106:107], v[94:95] op_sel_hi:[0,1,1]
	v_pk_fma_f32 v[114:115], v[0:1], v[76:77], v[114:115] op_sel_hi:[0,1,1]
	v_cvt_pk_bf16_f32 v88, v114, v94
	v_mov_b32_e32 v114, v88
	s_waitcnt vmcnt(14)
	v_lshlrev_b32_e32 v94, 16, v89
	s_waitcnt vmcnt(13)
	v_lshlrev_b32_e32 v89, 16, v90
	v_cvt_pk_bf16_f32 v115, v115, v95
	s_waitcnt vmcnt(12)
	v_lshlrev_b32_e32 v95, 16, v98
	v_mov_b32_e32 v88, v94
	s_waitcnt vmcnt(11)
	v_lshlrev_b32_e32 v91, 16, v96
	v_mov_b32_e32 v96, v107
	v_mov_b32_e32 v97, v89
	v_pk_mov_b32 v[76:77], v[76:77], v[88:89] op_sel:[1,0]
	v_pk_mul_f32 v[96:97], v[74:75], v[96:97] op_sel_hi:[0,1]
	v_mov_b32_e32 v106, v95
	v_pk_fma_f32 v[76:77], v[104:105], v[76:77], v[96:97] op_sel_hi:[0,1,1]
	v_pk_mul_f32 v[96:97], v[74:75], v[106:107]
	v_mov_b32_e32 v90, v89
	v_pk_fma_f32 v[76:77], v[0:1], v[94:95], v[76:77] op_sel_hi:[0,1,1]
	v_pk_fma_f32 v[88:89], v[74:75], v[88:89], v[96:97] op_sel:[0,0,1] op_sel_hi:[1,1,0]
	v_and_b32_sdwa v86, v77, v177 dst_sel:DWORD dst_unused:UNUSED_PAD src0_sel:WORD_1 src1_sel:DWORD
	v_pk_fma_f32 v[88:89], v[0:1], v[90:91], v[88:89] op_sel_hi:[0,1,1]
	v_cvt_pk_bf16_f32 v76, v76, v88
	v_add3_u32 v77, v77, v86, s28
	v_and_b32_sdwa v86, v89, v177 dst_sel:DWORD dst_unused:UNUSED_PAD src0_sel:WORD_1 src1_sel:DWORD
	v_add3_u32 v86, v89, v86, s28
	v_and_b32_e32 v86, 0xffff0000, v86
	v_or_b32_sdwa v89, v86, v77 dst_sel:DWORD dst_unused:UNUSED_PAD src0_sel:DWORD src1_sel:WORD_1
	v_mov_b32_e32 v88, v76
	s_waitcnt vmcnt(8)
	v_lshlrev_b32_e32 v77, 16, v102
	v_lshlrev_b32_e32 v76, 16, v82
	v_lshlrev_b32_e32 v83, 16, v83
	v_mov_b32_e32 v82, v76
	s_waitcnt vmcnt(7)
	v_lshlrev_b32_e32 v97, 16, v99
	v_mov_b32_e32 v98, v91
	v_mov_b32_e32 v99, v83
	v_mov_b32_e32 v90, v77
	v_pk_mov_b32 v[94:95], v[94:95], v[82:83] op_sel:[1,0]
	v_pk_mul_f32 v[98:99], v[74:75], v[98:99] op_sel_hi:[0,1]
	v_pk_mul_f32 v[90:91], v[74:75], v[90:91]
	v_mov_b32_e32 v96, v83
	v_pk_fma_f32 v[94:95], v[104:105], v[94:95], v[98:99] op_sel_hi:[0,1,1]
	v_pk_fma_f32 v[82:83], v[74:75], v[82:83], v[90:91] op_sel:[0,0,1] op_sel_hi:[1,1,0]
	v_pk_fma_f32 v[94:95], v[0:1], v[76:77], v[94:95] op_sel_hi:[0,1,1]
	v_pk_fma_f32 v[82:83], v[0:1], v[96:97], v[82:83] op_sel_hi:[0,1,1]
	v_cvt_pk_bf16_f32 v90, v94, v82
	v_cvt_pk_bf16_f32 v86, v95, v83
	v_mov_b32_e32 v91, v86
	s_waitcnt vmcnt(5)
	v_lshlrev_b32_e32 v83, 16, v87
	s_waitcnt vmcnt(4)
	v_lshlrev_b32_e32 v95, 16, v92
	v_lshlrev_b32_e32 v82, 16, v84
	s_waitcnt vmcnt(3)
	v_lshlrev_b32_e32 v87, 16, v93
	v_mov_b32_e32 v92, v97
	v_mov_b32_e32 v93, v83
	v_pk_mov_b32 v[76:77], v[76:77], v[82:83] op_sel:[1,0]
	v_pk_mul_f32 v[92:93], v[74:75], v[92:93] op_sel_hi:[0,1]
	v_mov_b32_e32 v96, v95
	v_mov_b32_e32 v94, v82
	v_pk_fma_f32 v[76:77], v[104:105], v[76:77], v[92:93] op_sel_hi:[0,1,1]
	v_pk_mul_f32 v[92:93], v[74:75], v[96:97]
	v_mov_b32_e32 v86, v83
	v_pk_fma_f32 v[76:77], v[0:1], v[94:95], v[76:77] op_sel_hi:[0,1,1]
	v_pk_fma_f32 v[82:83], v[74:75], v[82:83], v[92:93] op_sel:[0,0,1] op_sel_hi:[1,1,0]
	v_and_b32_sdwa v84, v77, v177 dst_sel:DWORD dst_unused:UNUSED_PAD src0_sel:WORD_1 src1_sel:DWORD
	v_pk_fma_f32 v[82:83], v[0:1], v[86:87], v[82:83] op_sel_hi:[0,1,1]
	v_and_b32_sdwa v86, v76, v177 dst_sel:DWORD dst_unused:UNUSED_PAD src0_sel:WORD_1 src1_sel:DWORD
	v_add3_u32 v76, v76, v86, s28
	v_add3_u32 v77, v77, v84, s28
	v_and_b32_sdwa v84, v83, v177 dst_sel:DWORD dst_unused:UNUSED_PAD src0_sel:WORD_1 src1_sel:DWORD
	v_and_b32_sdwa v86, v82, v177 dst_sel:DWORD dst_unused:UNUSED_PAD src0_sel:WORD_1 src1_sel:DWORD
	v_add3_u32 v83, v83, v84, s28
	v_add3_u32 v82, v82, v86, s28
	v_and_b32_e32 v83, 0xffff0000, v83
	v_and_b32_e32 v82, 0xffff0000, v82
	v_or_b32_sdwa v83, v83, v77 dst_sel:DWORD dst_unused:UNUSED_PAD src0_sel:DWORD src1_sel:WORD_1
	v_or_b32_sdwa v82, v82, v76 dst_sel:DWORD dst_unused:UNUSED_PAD src0_sel:DWORD src1_sel:WORD_1
	s_waitcnt vmcnt(2)
	v_lshlrev_b32_e32 v76, 16, v81
	v_mul_f32_e32 v77, v74, v87
	v_fmac_f32_e32 v77, v75, v95
	v_mul_f32_e32 v81, v74, v76
	v_fmac_f32_e32 v77, v0, v76
	s_waitcnt vmcnt(1)
	v_lshlrev_b32_e32 v80, 16, v80
	v_fmac_f32_e32 v81, v75, v87
	v_fmac_f32_e32 v81, v0, v80
	v_bfe_u32 v84, v77, 16, 1
	v_add3_u32 v77, v77, v84, s28
	v_bfe_u32 v84, v81, 16, 1
	v_lshrrev_b32_e32 v77, 16, v77
	v_add3_u32 v81, v81, v84, s28
	v_and_or_b32 v84, v81, s42, v77
	s_waitcnt vmcnt(0)
	v_lshlrev_b32_e32 v77, 16, v85
	v_mul_f32_e32 v81, v74, v80
	v_fmac_f32_e32 v81, v75, v76
	v_mul_f32_e32 v74, v74, v77
	v_fmac_f32_e32 v81, v0, v77
	v_fmac_f32_e32 v74, v75, v80
	v_fmac_f32_e32 v74, v0, v79
	v_bfe_u32 v0, v81, 16, 1
	v_add3_u32 v0, v81, v0, s28
	v_bfe_u32 v75, v74, 16, 1
	v_lshrrev_b32_e32 v0, 16, v0
	v_add3_u32 v74, v74, v75, s28
	v_and_or_b32 v85, v74, s42, v0
	v_lshl_add_u64 v[74:75], s[52:53], 0, v[30:31]
	s_mov_b32 s2, 0xe735000
	v_add_co_u32_e32 v74, vcc, s2, v74
	v_add_u32_e32 v78, 0x200, v78
	s_nop 0
	v_addc_co_u32_e32 v75, vcc, 0, v75, vcc
	s_mov_b64 s[2:3], 0x1200000
	v_cmp_lt_i32_e32 vcc, s33, v78
	v_lshl_add_u64 v[30:31], v[30:31], 0, s[2:3]
	v_lshl_add_u64 v[4:5], v[4:5], 0, s[0:1]
	v_lshl_add_u64 v[6:7], v[6:7], 0, s[0:1]
	v_lshl_add_u64 v[8:9], v[8:9], 0, s[0:1]
	v_lshl_add_u64 v[10:11], v[10:11], 0, s[0:1]
	v_lshl_add_u64 v[12:13], v[12:13], 0, s[0:1]
	v_lshl_add_u64 v[14:15], v[14:15], 0, s[0:1]
	v_lshl_add_u64 v[16:17], v[16:17], 0, s[0:1]
	v_lshl_add_u64 v[18:19], v[18:19], 0, s[0:1]
	v_lshl_add_u64 v[20:21], v[20:21], 0, s[0:1]
	v_lshl_add_u64 v[22:23], v[22:23], 0, s[0:1]
	v_lshl_add_u64 v[24:25], v[24:25], 0, s[0:1]
	v_lshl_add_u64 v[26:27], v[26:27], 0, s[0:1]
	v_lshl_add_u64 v[28:29], v[28:29], 0, s[0:1]
	v_lshl_add_u64 v[32:33], v[32:33], 0, s[0:1]
	v_lshl_add_u64 v[34:35], v[34:35], 0, s[0:1]
	v_lshl_add_u64 v[36:37], v[36:37], 0, s[0:1]
	v_lshl_add_u64 v[38:39], v[38:39], 0, s[0:1]
	v_lshl_add_u64 v[40:41], v[40:41], 0, s[0:1]
	v_lshl_add_u64 v[42:43], v[42:43], 0, s[0:1]
	v_lshl_add_u64 v[44:45], v[44:45], 0, s[0:1]
	v_lshl_add_u64 v[46:47], v[46:47], 0, s[0:1]
	v_lshl_add_u64 v[48:49], v[48:49], 0, s[0:1]
	v_lshl_add_u64 v[50:51], v[50:51], 0, s[0:1]
	v_lshl_add_u64 v[52:53], v[52:53], 0, s[0:1]
	v_lshl_add_u64 v[54:55], v[54:55], 0, s[0:1]
	v_lshl_add_u64 v[56:57], v[56:57], 0, s[0:1]
	v_lshl_add_u64 v[58:59], v[58:59], 0, s[0:1]
	v_lshl_add_u64 v[60:61], v[60:61], 0, s[0:1]
	v_lshl_add_u64 v[62:63], v[62:63], 0, s[0:1]
	v_lshl_add_u64 v[64:65], v[64:65], 0, s[0:1]
	v_lshl_add_u64 v[66:67], v[66:67], 0, s[0:1]
	v_lshl_add_u64 v[68:69], v[68:69], 0, s[0:1]
	v_lshl_add_u64 v[70:71], v[70:71], 0, s[0:1]
	v_lshl_add_u64 v[72:73], v[72:73], 0, s[0:1]
	s_or_b64 s[46:47], vcc, s[46:47]
	s_mov_b64 s[40:41], 0x800
	v_lshl_add_u64 v[2:3], v[2:3], 0, s[6:7]
	global_store_dwordx4 v[74:75], v[108:111], off offset:2048
	global_store_dwordx4 v[74:75], v[112:115], off offset:2064
	global_store_dwordx4 v[74:75], v[88:91], off offset:2080
	global_store_dwordx4 v[74:75], v[82:85], off offset:2096
	s_andn2_b64 exec, exec, s[46:47]
	s_cbranch_execz .LBB0_722

.LBB0_974:
	s_waitcnt lgkmcnt(0)
	s_add_u32 s90, s18, 0x6035800
	s_addc_u32 s91, s19, 0
	s_or_b32 s15, s14, 64
	v_ashrrev_i32_e32 v51, 2, v50
	v_mov_b32_e32 v0, s15
	v_mov_b32_e32 v2, s14
	v_cmp_gt_i32_e32 vcc, 64, v51
	s_and_b32 s10, s4, 3
	s_lshl_b32 s4, s10, 7
	v_cndmask_b32_e32 v0, v0, v2, vcc
	v_and_b32_e32 v2, 63, v51
	v_add_u32_e32 v0, v0, v2
	v_mov_b64_e32 v[2:3], s[90:91]
	v_mad_i64_i32 v[2:3], s[20:21], v0, s24, v[2:3]
	v_lshlrev_b32_e32 v0, 4, v50
	v_and_b32_e32 v10, 48, v0
	v_lshl_add_u64 v[2:3], v[2:3], 0, s[4:5]
	v_lshlrev_b32_e32 v0, 1, v10
	s_waitcnt vmcnt(2)
	v_lshl_add_u64 v[6:7], v[2:3], 0, v[0:1]
	s_load_dwordx4 s[44:47], s[16:17], 0x98
	s_waitcnt lgkmcnt(0)
	s_barrier
	global_load_dwordx4 v[2:5], v[6:7], off offset:1536
	s_nop 0
	global_load_dwordx4 v[6:9], v[6:7], off offset:1552
	v_readlane_b32 s2, v255, 55
	v_readlane_b32 s3, v255, 56
	s_lshl_b64 s[48:49], s[2:3], 2
	s_add_u32 s20, s44, s48
	v_lshlrev_b32_e32 v22, 2, v10
	s_addc_u32 s21, s45, s49
	global_load_dwordx4 v[10:13], v22, s[20:21]
	global_load_dwordx4 v[14:17], v22, s[20:21] offset:16
	global_load_dwordx4 v[18:21], v22, s[20:21] offset:32
	s_nop 0
	global_load_dwordx4 v[22:25], v22, s[20:21] offset:48
	v_cmp_lt_i32_e32 vcc, v188, v182
	s_movk_i32 s2, 0x90
	s_waitcnt vmcnt(5)
	v_lshlrev_b32_e32 v29, 16, v5
	v_cndmask_b32_e32 v26, v181, v188, vcc
	v_cmp_lt_i32_e32 vcc, v191, v182
	v_lshlrev_b32_e32 v58, 2, v26
	v_lshlrev_b32_e32 v26, 16, v2
	v_cndmask_b32_e32 v27, v181, v191, vcc
	v_lshlrev_b32_e32 v59, 2, v27
	v_lshlrev_b32_e32 v27, 16, v3
	v_and_b32_e32 v3, 0xffff0000, v3
	v_and_b32_e32 v2, 0xffff0000, v2
	v_pk_mul_f32 v[34:35], v[26:27], v[26:27]
	v_pk_mul_f32 v[36:37], v[2:3], v[2:3]
	v_lshlrev_b32_e32 v28, 16, v4
	v_add_f32_e32 v34, v34, v36
	v_add_f32_e32 v34, v34, v35
	v_and_b32_e32 v5, 0xffff0000, v5
	v_and_b32_e32 v4, 0xffff0000, v4
	v_pk_mul_f32 v[38:39], v[28:29], v[28:29]
	v_add_f32_e32 v34, v37, v34
	v_pk_mul_f32 v[40:41], v[4:5], v[4:5]
	v_add_f32_e32 v34, v38, v34
	s_waitcnt vmcnt(4)
	v_lshlrev_b32_e32 v30, 16, v6
	v_and_b32_e32 v6, 0xffff0000, v6
	v_add_f32_e32 v34, v40, v34
	v_mov_b32_e32 v42, v6
	v_mov_b32_e32 v43, v30
	v_add_f32_e32 v34, v39, v34
	v_lshlrev_b32_e32 v31, 16, v7
	v_and_b32_e32 v7, 0xffff0000, v7
	v_pk_mul_f32 v[42:43], v[42:43], v[42:43]
	v_add_f32_e32 v34, v41, v34
	v_mov_b32_e32 v44, v7
	v_mov_b32_e32 v45, v31
	v_add_f32_e32 v34, v43, v34
	v_lshlrev_b32_e32 v32, 16, v8
	v_and_b32_e32 v8, 0xffff0000, v8
	v_pk_mul_f32 v[44:45], v[44:45], v[44:45]
	v_add_f32_e32 v34, v42, v34
	v_mov_b32_e32 v46, v8
	v_mov_b32_e32 v47, v32
	v_add_f32_e32 v34, v45, v34
	v_lshlrev_b32_e32 v33, 16, v9
	v_and_b32_e32 v9, 0xffff0000, v9
	v_pk_mul_f32 v[46:47], v[46:47], v[46:47]
	v_add_f32_e32 v34, v44, v34
	v_mov_b32_e32 v48, v9
	v_mov_b32_e32 v49, v33
	v_add_f32_e32 v34, v47, v34
	v_pk_mul_f32 v[48:49], v[48:49], v[48:49]
	v_add_f32_e32 v34, v46, v34
	v_add_f32_e32 v34, v49, v34
	v_add_f32_e32 v38, v48, v34
	ds_bpermute_b32 v39, v58, v38
	v_mad_u64_u32 v[34:35], s[20:21], v51, s2, v[0:1]
	s_waitcnt vmcnt(3)
	v_mov_b32_e32 v36, v10
	s_waitcnt vmcnt(2)
	v_mov_b32_e32 v10, v14
	s_waitcnt lgkmcnt(0)
	v_add_f32_e32 v0, v38, v39
	ds_bpermute_b32 v35, v59, v0
	v_mov_b32_e32 v37, v12
	v_mov_b32_e32 v12, v11
	v_mov_b32_e32 v11, v16
	v_mov_b32_e32 v16, v15
	s_waitcnt lgkmcnt(0)
	v_add_f32_e32 v0, v0, v35
	v_fmamk_f32 v0, v0, 0x3c800000, v174
	v_mul_f32_e32 v14, 0x4b800000, v0
	v_cmp_gt_f32_e32 vcc, s27, v0
	s_waitcnt vmcnt(1)
	v_mov_b32_e32 v15, v20
	v_mov_b32_e32 v20, v19
	v_cndmask_b32_e32 v0, v0, v14, vcc
	v_rsq_f32_e32 v0, v0
	v_mov_b32_e32 v14, v18
	s_movk_i32 s2, 0x1d1
	v_mul_f32_e32 v18, 0x45800000, v0
	v_cndmask_b32_e32 v0, v0, v18, vcc
	v_pk_mul_f32 v[2:3], v[0:1], v[2:3] op_sel_hi:[0,1]
	v_pk_mul_f32 v[18:19], v[0:1], v[26:27] op_sel_hi:[0,1]
	v_pk_mul_f32 v[4:5], v[0:1], v[4:5] op_sel_hi:[0,1]
	v_pk_mul_f32 v[2:3], v[12:13], v[2:3]
	v_pk_mul_f32 v[18:19], v[36:37], v[18:19]
	v_pk_mul_f32 v[4:5], v[16:17], v[4:5]
	v_and_b32_sdwa v16, v3, v177 dst_sel:DWORD dst_unused:UNUSED_PAD src0_sel:WORD_1 src1_sel:DWORD
	v_and_b32_sdwa v17, v2, v177 dst_sel:DWORD dst_unused:UNUSED_PAD src0_sel:WORD_1 src1_sel:DWORD
	v_and_b32_sdwa v12, v19, v177 dst_sel:DWORD dst_unused:UNUSED_PAD src0_sel:WORD_1 src1_sel:DWORD
	v_and_b32_sdwa v13, v18, v177 dst_sel:DWORD dst_unused:UNUSED_PAD src0_sel:WORD_1 src1_sel:DWORD
	v_add3_u32 v3, v3, v16, s28
	v_add3_u32 v2, v2, v17, s28
	v_pk_mul_f32 v[26:27], v[0:1], v[28:29] op_sel_hi:[0,1]
	v_add3_u32 v13, v18, v13, s28
	v_add3_u32 v12, v19, v12, s28
	v_and_b32_e32 v3, 0xffff0000, v3
	v_and_b32_e32 v2, 0xffff0000, v2
	v_pk_mul_f32 v[10:11], v[10:11], v[26:27]
	v_or_b32_sdwa v3, v3, v12 dst_sel:DWORD dst_unused:UNUSED_PAD src0_sel:DWORD src1_sel:WORD_1
	v_or_b32_sdwa v2, v2, v13 dst_sel:DWORD dst_unused:UNUSED_PAD src0_sel:DWORD src1_sel:WORD_1
	v_cvt_pk_bf16_f32 v11, v11, v5
	v_cvt_pk_bf16_f32 v10, v10, v4
	v_mov_b32_e32 v5, v11
	v_mov_b32_e32 v4, v10
	v_pk_mul_f32 v[10:11], v[0:1], v[30:31] op_sel_hi:[0,1]
	v_pk_mul_f32 v[10:11], v[14:15], v[10:11]
	v_pk_mul_f32 v[6:7], v[0:1], v[6:7] op_sel_hi:[0,1]
	v_pk_mul_f32 v[6:7], v[20:21], v[6:7]
	v_cvt_pk_bf16_f32 v11, v11, v7
	v_cvt_pk_bf16_f32 v10, v10, v6
	v_mov_b32_e32 v7, v11
	v_mov_b32_e32 v6, v10
	v_pk_mul_f32 v[10:11], v[0:1], v[32:33] op_sel_hi:[0,1]
	s_waitcnt vmcnt(0)
	v_mov_b32_e32 v12, v22
	v_mov_b32_e32 v13, v24
	v_pk_mul_f32 v[10:11], v[12:13], v[10:11]
	v_pk_mul_f32 v[8:9], v[0:1], v[8:9] op_sel_hi:[0,1]
	v_mov_b32_e32 v24, v23
	v_pk_mul_f32 v[8:9], v[24:25], v[8:9]
	v_and_b32_sdwa v0, v11, v177 dst_sel:DWORD dst_unused:UNUSED_PAD src0_sel:WORD_1 src1_sel:DWORD
	v_cvt_pk_bf16_f32 v10, v10, v8
	v_add3_u32 v0, v11, v0, s28
	v_and_b32_sdwa v11, v9, v177 dst_sel:DWORD dst_unused:UNUSED_PAD src0_sel:WORD_1 src1_sel:DWORD
	v_add3_u32 v9, v9, v11, s28
	v_and_b32_e32 v9, 0xffff0000, v9
	v_cmp_gt_i32_e32 vcc, s2, v50
	v_or_b32_sdwa v9, v9, v0 dst_sel:DWORD dst_unused:UNUSED_PAD src0_sel:DWORD src1_sel:WORD_1
	v_mov_b32_e32 v8, v10
	ds_write_b128 v34, v[2:5]
	ds_write_b128 v34, v[6:9] offset:16
	s_and_saveexec_b64 s[44:45], vcc
	s_cbranch_execz .LBB0_982
	s_load_dwordx2 s[50:51], s[16:17], 0xa8
	v_max_i32_e32 v0, 0xffffffd1, v50
	v_sub_u32_e32 v0, v0, v50
	v_add_u32_e32 v0, 0x1ff, v0
	s_movk_i32 s2, 0x1ff
	v_cmp_lt_u32_e32 vcc, s2, v0
	s_mov_b64 s[54:55], -1
	v_mov_b32_e32 v2, v50
	s_and_saveexec_b64 s[52:53], vcc
	s_cbranch_execz .LBB0_979
	v_readlane_b32 s2, v255, 57
	s_or_b32 s2, s10, s2
	s_mul_i32 s4, s2, 0x1d1
	v_lshrrev_b32_e32 v0, 9, v0
	s_lshl_b64 s[20:21], s[4:5], 2
	v_add_u32_e32 v0, 1, v0
	s_waitcnt lgkmcnt(0)
	s_add_u32 s54, s50, s20
	v_and_b32_e32 v4, 0xfffffe, v0
	v_add_u32_e32 v51, 0x200, v50
	s_addc_u32 s55, s51, s21
	v_lshl_add_u32 v5, v50, 2, v195
	s_mov_b64 s[56:57], 0
	v_mov_b32_e32 v6, v4
	v_mov_b64_e32 v[2:3], v[50:51]
	v_readlane_b32 s3, v255, 58

.LBB0_1034:
	s_waitcnt vmcnt(1)
	v_mov_b32_e32 v3, v67
	s_nop 1
	v_permlane32_swap_b32_e32 v67, v3
	v_add_f32_e32 v3, v67, v3
	v_mov_b32_e32 v4, v3
	s_nop 1
	v_permlane16_swap_b32_e32 v3, v4
	v_add_f32_e32 v3, v3, v4
	v_div_scale_f32 v4, s[6:7], v3, v3, 1.0
	v_rcp_f32_e32 v5, v4
	s_movk_i32 s2, 0x100
	v_mov_b32_e32 v2, s15
	s_waitcnt vmcnt(0)
	v_mov_b32_e32 v6, s14
	v_cmp_gt_u32_e32 vcc, s2, v50
	s_lshl_b32 s4, s26, 1
	v_mov_b32_e32 v9, v12
	v_cndmask_b32_e32 v6, v2, v6, vcc
	v_fma_f32 v2, -v4, v5, 1.0
	v_fmac_f32_e32 v5, v2, v5
	v_div_scale_f32 v2, vcc, 1.0, v3, 1.0
	v_mul_f32_e32 v7, v2, v5
	v_fma_f32 v8, -v4, v7, v2
	v_fmac_f32_e32 v7, v8, v5
	v_fma_f32 v2, -v4, v7, v2
	v_add_u32_e32 v4, v6, v51
	v_div_fmas_f32 v2, v2, v5, v7
	v_ashrrev_i32_e32 v5, 31, v4
	v_lshlrev_b64 v[4:5], 11, v[4:5]
	v_div_fixup_f32 v2, v2, v3, 1.0
	v_lshl_add_u64 v[4:5], s[18:19], 0, v[4:5]
	v_mov_b32_e32 v8, v10
	v_lshl_add_u64 v[4:5], v[4:5], 0, s[4:5]
	v_pk_mul_f32 v[8:9], v[8:9], v[2:3] op_sel_hi:[1,0]
	v_mov_b32_e32 v12, v11
	v_lshl_add_u64 v[4:5], v[0:1], 1, v[4:5]
	v_pk_mul_f32 v[10:11], v[12:13], v[2:3] op_sel_hi:[1,0]
	v_cvt_pk_bf16_f32 v0, v9, v11
	v_and_b32_sdwa v3, v8, v177 dst_sel:DWORD dst_unused:UNUSED_PAD src0_sel:WORD_1 src1_sel:DWORD
	v_add3_u32 v3, v8, v3, s28
	v_and_b32_sdwa v9, v10, v177 dst_sel:DWORD dst_unused:UNUSED_PAD src0_sel:WORD_1 src1_sel:DWORD
	s_mov_b64 s[6:7], 0x3200200
	v_add3_u32 v9, v10, v9, s28
	s_mov_b32 s2, 0x3200000
	v_lshl_add_u64 v[6:7], v[4:5], 0, s[6:7]
	v_and_b32_e32 v10, 0xffff0000, v9
	v_add_co_u32_e32 v4, vcc, s2, v4
	v_mov_b32_e32 v9, v0
	v_or_b32_sdwa v8, v10, v3 dst_sel:DWORD dst_unused:UNUSED_PAD src0_sel:DWORD src1_sel:WORD_1
	v_addc_co_u32_e32 v5, vcc, 0, v5, vcc
	global_store_dwordx2 v[4:5], v[8:9], off offset:512
	v_mov_b32_e32 v4, v22
	v_mov_b32_e32 v5, v24
	v_pk_mul_f32 v[4:5], v[4:5], v[2:3] op_sel_hi:[1,0]
	v_mov_b32_e32 v24, v23
	v_pk_mul_f32 v[8:9], v[24:25], v[2:3] op_sel_hi:[1,0]
	v_cvt_pk_bf16_f32 v0, v5, v9
	v_and_b32_sdwa v3, v4, v177 dst_sel:DWORD dst_unused:UNUSED_PAD src0_sel:WORD_1 src1_sel:DWORD
	v_add3_u32 v3, v4, v3, s28
	v_and_b32_sdwa v5, v8, v177 dst_sel:DWORD dst_unused:UNUSED_PAD src0_sel:WORD_1 src1_sel:DWORD
	v_add3_u32 v5, v8, v5, s28
	v_and_b32_e32 v8, 0xffff0000, v5
	v_mov_b32_e32 v5, v0
	v_or_b32_sdwa v4, v8, v3 dst_sel:DWORD dst_unused:UNUSED_PAD src0_sel:DWORD src1_sel:WORD_1
	global_store_dwordx2 v[6:7], v[4:5], off offset:32
	v_mov_b32_e32 v4, v26
	v_mov_b32_e32 v5, v28
	v_pk_mul_f32 v[4:5], v[4:5], v[2:3] op_sel_hi:[1,0]
	v_mov_b32_e32 v28, v27
	v_pk_mul_f32 v[8:9], v[28:29], v[2:3] op_sel_hi:[1,0]
	v_cvt_pk_bf16_f32 v0, v5, v9
	v_and_b32_sdwa v3, v4, v177 dst_sel:DWORD dst_unused:UNUSED_PAD src0_sel:WORD_1 src1_sel:DWORD
	v_add3_u32 v3, v4, v3, s28
	v_and_b32_sdwa v5, v8, v177 dst_sel:DWORD dst_unused:UNUSED_PAD src0_sel:WORD_1 src1_sel:DWORD
	v_add3_u32 v5, v8, v5, s28
	v_and_b32_e32 v8, 0xffff0000, v5
	v_mov_b32_e32 v5, v0
	v_or_b32_sdwa v4, v8, v3 dst_sel:DWORD dst_unused:UNUSED_PAD src0_sel:DWORD src1_sel:WORD_1
	global_store_dwordx2 v[6:7], v[4:5], off offset:64
	v_mov_b32_e32 v4, v30
	v_mov_b32_e32 v5, v32
	v_pk_mul_f32 v[4:5], v[4:5], v[2:3] op_sel_hi:[1,0]
	v_mov_b32_e32 v32, v31
	v_pk_mul_f32 v[2:3], v[32:33], v[2:3] op_sel_hi:[1,0]
	v_and_b32_sdwa v0, v5, v177 dst_sel:DWORD dst_unused:UNUSED_PAD src0_sel:WORD_1 src1_sel:DWORD
	v_and_b32_sdwa v8, v4, v177 dst_sel:DWORD dst_unused:UNUSED_PAD src0_sel:WORD_1 src1_sel:DWORD
	v_add3_u32 v4, v4, v8, s28
	v_add3_u32 v0, v5, v0, s28
	v_and_b32_sdwa v5, v3, v177 dst_sel:DWORD dst_unused:UNUSED_PAD src0_sel:WORD_1 src1_sel:DWORD
	v_and_b32_sdwa v8, v2, v177 dst_sel:DWORD dst_unused:UNUSED_PAD src0_sel:WORD_1 src1_sel:DWORD
	v_add3_u32 v3, v3, v5, s28
	v_add3_u32 v2, v2, v8, s28
	v_and_b32_e32 v3, 0xffff0000, v3
	v_and_b32_e32 v2, 0xffff0000, v2
	v_readlane_b32 s90, v255, 10
	v_or_b32_sdwa v3, v3, v0 dst_sel:DWORD dst_unused:UNUSED_PAD src0_sel:DWORD src1_sel:WORD_1
	v_or_b32_sdwa v2, v2, v4 dst_sel:DWORD dst_unused:UNUSED_PAD src0_sel:DWORD src1_sel:WORD_1
	v_readlane_b32 s91, v255, 11
	global_store_dwordx2 v[6:7], v[2:3], off offset:96
	s_mov_b64 s[18:19], 0

.LBB0_1070:
	v_div_scale_f32 v0, s[14:15], v42, v42, 1.0
	v_rcp_f32_e32 v34, v0
	s_load_dwordx2 s[14:15], s[16:17], 0x90
	v_readlane_b32 s2, v255, 52
	s_or_b32 s4, s6, s2
	v_fma_f32 v35, -v0, v34, 1.0
	v_fmac_f32_e32 v34, v35, v34
	v_div_scale_f32 v35, vcc, 1.0, v42, 1.0
	s_lshl_b64 s[16:17], s[4:5], 2
	v_mul_f32_e32 v36, v35, v34
	s_waitcnt lgkmcnt(0)
	s_add_u32 s14, s14, s16
	v_fma_f32 v37, -v0, v36, v35
	s_addc_u32 s15, s15, s17
	v_fmac_f32_e32 v36, v37, v34
	s_add_u32 s16, s46, 0x900000
	v_fma_f32 v0, -v0, v36, v35
	s_addc_u32 s17, s47, 0
	v_div_fmas_f32 v0, v0, v34, v36
	global_load_dword v36, v1, s[14:15]
	s_and_b64 s[14:15], s[18:19], exec
	v_div_fixup_f32 v34, v0, v42, 1.0
	v_lshlrev_b32_e32 v0, 2, v38
	s_cselect_b32 s2, 11, 8
	v_or3_b32 v38, v0, v41, v40
	v_lshlrev_b32_e32 v0, s2, v39
	v_or_b32_e32 v0, s7, v0
	v_ashrrev_i32_e32 v39, 31, v38
	v_lshl_add_u64 v[40:41], v[0:1], 0, v[38:39]
	v_lshlrev_b64 v[40:41], 1, v[40:41]
	v_lshl_add_u64 v[44:45], s[16:17], 0, v[40:41]
	v_lshl_add_u64 v[42:43], s[46:47], 0, v[40:41]
	global_load_dwordx2 v[44:45], v[44:45], off
	s_nop 0
	global_load_dwordx2 v[46:47], v[42:43], off
	v_mov_b32_e32 v52, v18
	v_mov_b32_e32 v53, v20
	v_mov_b32_e32 v20, v19
	s_add_u32 s2, s50, s10
	s_addc_u32 s3, s51, 0
	s_add_u32 s18, s2, 0xde35800
	s_addc_u32 s19, s3, 0
	v_lshl_add_u64 v[40:41], s[18:19], 0, v[40:41]
	s_waitcnt vmcnt(1)
	v_lshlrev_b32_e32 v49, 16, v45
	s_waitcnt vmcnt(0)
	v_lshlrev_b32_e32 v51, 16, v47
	v_lshlrev_b32_e32 v50, 16, v46
	v_and_b32_e32 v47, 0xffff0000, v47
	v_and_b32_e32 v46, 0xffff0000, v46
	v_pk_mul_f32 v[18:19], v[36:37], v[46:47] op_sel_hi:[0,1]
	v_lshlrev_b32_e32 v48, 16, v44
	v_and_b32_e32 v45, 0xffff0000, v45
	v_and_b32_e32 v44, 0xffff0000, v44
	v_pk_mul_f32 v[50:51], v[36:37], v[50:51] op_sel_hi:[0,1]
	v_pk_fma_f32 v[18:19], v[34:35], v[20:21], v[18:19] op_sel_hi:[0,1,1]
	v_pk_fma_f32 v[50:51], v[34:35], v[52:53], v[50:51] op_sel_hi:[0,1,1]
	v_pk_mul_f32 v[18:19], v[18:19], v[44:45]
	v_pk_mul_f32 v[48:49], v[50:51], v[48:49]
	v_and_b32_sdwa v35, v19, v177 dst_sel:DWORD dst_unused:UNUSED_PAD src0_sel:WORD_1 src1_sel:DWORD
	v_and_b32_sdwa v37, v18, v177 dst_sel:DWORD dst_unused:UNUSED_PAD src0_sel:WORD_1 src1_sel:DWORD
	v_and_b32_sdwa v20, v49, v177 dst_sel:DWORD dst_unused:UNUSED_PAD src0_sel:WORD_1 src1_sel:DWORD
	v_and_b32_sdwa v21, v48, v177 dst_sel:DWORD dst_unused:UNUSED_PAD src0_sel:WORD_1 src1_sel:DWORD
	v_add3_u32 v19, v19, v35, s28
	v_add3_u32 v18, v18, v37, s28
	v_add3_u32 v21, v48, v21, s28
	v_add3_u32 v20, v49, v20, s28
	v_and_b32_e32 v19, 0xffff0000, v19
	v_and_b32_e32 v18, 0xffff0000, v18
	v_or_b32_sdwa v19, v19, v20 dst_sel:DWORD dst_unused:UNUSED_PAD src0_sel:DWORD src1_sel:WORD_1
	v_or_b32_sdwa v18, v18, v21 dst_sel:DWORD dst_unused:UNUSED_PAD src0_sel:DWORD src1_sel:WORD_1
	global_store_dwordx2 v[40:41], v[18:19], off
	v_or_b32_e32 v18, 8, v38
	v_ashrrev_i32_e32 v19, 31, v18
	v_lshl_add_u64 v[18:19], v[0:1], 0, v[18:19]
	v_lshl_add_u64 v[18:19], v[18:19], 1, s[16:17]
	global_load_dwordx2 v[18:19], v[18:19], off
	s_nop 0
	global_load_dwordx2 v[20:21], v[42:43], off offset:16
	v_mov_b32_e32 v49, v24
	v_mov_b32_e32 v24, v23
	v_mov_b32_e32 v48, v22
	s_waitcnt vmcnt(1)
	v_lshlrev_b32_e32 v45, 16, v19
	s_waitcnt vmcnt(0)
	v_lshlrev_b32_e32 v47, 16, v21
	v_lshlrev_b32_e32 v46, 16, v20
	v_and_b32_e32 v21, 0xffff0000, v21
	v_and_b32_e32 v20, 0xffff0000, v20
	v_pk_mul_f32 v[20:21], v[36:37], v[20:21] op_sel_hi:[0,1]
	v_lshlrev_b32_e32 v44, 16, v18
	v_and_b32_e32 v19, 0xffff0000, v19
	v_and_b32_e32 v18, 0xffff0000, v18
	v_pk_mul_f32 v[46:47], v[36:37], v[46:47] op_sel_hi:[0,1]
	v_pk_fma_f32 v[20:21], v[34:35], v[24:25], v[20:21] op_sel_hi:[0,1,1]
	v_pk_fma_f32 v[46:47], v[34:35], v[48:49], v[46:47] op_sel_hi:[0,1,1]
	v_pk_mul_f32 v[18:19], v[20:21], v[18:19]
	v_pk_mul_f32 v[44:45], v[46:47], v[44:45]
	v_cvt_pk_bf16_f32 v20, v45, v19
	v_cvt_pk_bf16_f32 v21, v44, v18
	v_mov_b32_e32 v19, v20
	v_mov_b32_e32 v18, v21
	global_store_dwordx2 v[40:41], v[18:19], off offset:16
	v_or_b32_e32 v18, 16, v38
	v_ashrrev_i32_e32 v19, 31, v18
	v_lshl_add_u64 v[18:19], v[0:1], 0, v[18:19]
	v_lshl_add_u64 v[18:19], v[18:19], 1, s[16:17]
	global_load_dwordx2 v[18:19], v[18:19], off
	s_nop 0
	global_load_dwordx2 v[20:21], v[42:43], off offset:32
	v_mov_b32_e32 v44, v26
	v_mov_b32_e32 v45, v28
	v_mov_b32_e32 v28, v27
	v_mov_b32_e32 v26, v30
	v_mov_b32_e32 v27, v32
	v_mov_b32_e32 v32, v31
	s_waitcnt vmcnt(1)
	v_lshlrev_b32_e32 v23, 16, v19
	s_waitcnt vmcnt(0)
	v_lshlrev_b32_e32 v25, 16, v21
	v_lshlrev_b32_e32 v24, 16, v20
	v_and_b32_e32 v21, 0xffff0000, v21
	v_and_b32_e32 v20, 0xffff0000, v20
	v_pk_mul_f32 v[24:25], v[36:37], v[24:25] op_sel_hi:[0,1]
	v_lshlrev_b32_e32 v22, 16, v18
	v_pk_fma_f32 v[24:25], v[34:35], v[44:45], v[24:25] op_sel_hi:[0,1,1]
	v_pk_mul_f32 v[20:21], v[36:37], v[20:21] op_sel_hi:[0,1]
	v_and_b32_e32 v19, 0xffff0000, v19
	v_and_b32_e32 v18, 0xffff0000, v18
	v_pk_mul_f32 v[22:23], v[24:25], v[22:23]
	v_pk_fma_f32 v[20:21], v[34:35], v[28:29], v[20:21] op_sel_hi:[0,1,1]
	v_pk_mul_f32 v[18:19], v[20:21], v[18:19]
	v_cvt_pk_bf16_f32 v20, v23, v19
	v_cvt_pk_bf16_f32 v21, v22, v18
	v_mov_b32_e32 v19, v20
	v_mov_b32_e32 v18, v21
	global_store_dwordx2 v[40:41], v[18:19], off offset:32
	v_or_b32_e32 v18, 24, v38
	v_ashrrev_i32_e32 v19, 31, v18
	v_lshl_add_u64 v[18:19], v[0:1], 0, v[18:19]
	v_lshl_add_u64 v[18:19], v[18:19], 1, s[16:17]
	global_load_dwordx2 v[18:19], v[18:19], off
	s_nop 0
	global_load_dwordx2 v[20:21], v[42:43], off offset:48
	s_waitcnt vmcnt(1)
	v_lshlrev_b32_e32 v23, 16, v19
	s_waitcnt vmcnt(0)
	v_lshlrev_b32_e32 v25, 16, v21
	v_lshlrev_b32_e32 v24, 16, v20
	v_and_b32_e32 v21, 0xffff0000, v21
	v_and_b32_e32 v20, 0xffff0000, v20
	v_pk_mul_f32 v[24:25], v[36:37], v[24:25] op_sel_hi:[0,1]
	v_lshlrev_b32_e32 v22, 16, v18
	v_pk_fma_f32 v[24:25], v[34:35], v[26:27], v[24:25] op_sel_hi:[0,1,1]
	v_pk_mul_f32 v[20:21], v[36:37], v[20:21] op_sel_hi:[0,1]
	v_and_b32_e32 v19, 0xffff0000, v19
	v_and_b32_e32 v18, 0xffff0000, v18
	v_pk_mul_f32 v[22:23], v[24:25], v[22:23]
	v_pk_fma_f32 v[20:21], v[34:35], v[32:33], v[20:21] op_sel_hi:[0,1,1]
	v_pk_mul_f32 v[18:19], v[20:21], v[18:19]
	v_and_b32_sdwa v20, v23, v177 dst_sel:DWORD dst_unused:UNUSED_PAD src0_sel:WORD_1 src1_sel:DWORD
	v_and_b32_sdwa v21, v22, v177 dst_sel:DWORD dst_unused:UNUSED_PAD src0_sel:WORD_1 src1_sel:DWORD
	v_add3_u32 v21, v22, v21, s28
	v_add3_u32 v20, v23, v20, s28
	v_and_b32_sdwa v22, v19, v177 dst_sel:DWORD dst_unused:UNUSED_PAD src0_sel:WORD_1 src1_sel:DWORD
	v_and_b32_sdwa v23, v18, v177 dst_sel:DWORD dst_unused:UNUSED_PAD src0_sel:WORD_1 src1_sel:DWORD
	v_add3_u32 v19, v19, v22, s28
	v_add3_u32 v18, v18, v23, s28
	v_and_b32_e32 v19, 0xffff0000, v19
	v_and_b32_e32 v18, 0xffff0000, v18
	v_or_b32_sdwa v19, v19, v20 dst_sel:DWORD dst_unused:UNUSED_PAD src0_sel:DWORD src1_sel:WORD_1
	v_or_b32_sdwa v18, v18, v21 dst_sel:DWORD dst_unused:UNUSED_PAD src0_sel:DWORD src1_sel:WORD_1
	global_store_dwordx2 v[40:41], v[18:19], off offset:48
	s_and_saveexec_b64 s[6:7], s[44:45]
	s_xor_b64 s[6:7], exec, s[6:7]
	s_cbranch_execz .LBB0_961
	v_add_u32_e32 v18, 0x400, v38
	v_ashrrev_i32_e32 v19, 31, v18
	v_lshl_add_u64 v[18:19], v[0:1], 0, v[18:19]
	v_lshlrev_b64 v[18:19], 1, v[18:19]
	v_lshl_add_u64 v[20:21], s[16:17], 0, v[18:19]
	v_lshl_add_u64 v[22:23], s[46:47], 0, v[18:19]
	global_load_dwordx2 v[20:21], v[20:21], off
	s_nop 0
	global_load_dwordx2 v[22:23], v[22:23], off
	v_mov_b32_e32 v37, v36
	v_mov_b32_e32 v35, v34
	v_mov_b32_e32 v28, v2
	v_mov_b32_e32 v29, v4
	v_mov_b32_e32 v4, v3
	v_lshl_add_u64 v[18:19], s[18:19], 0, v[18:19]
	s_waitcnt vmcnt(1)
	v_lshlrev_b32_e32 v25, 16, v21
	s_waitcnt vmcnt(0)
	v_lshlrev_b32_e32 v27, 16, v23
	v_lshlrev_b32_e32 v26, 16, v22
	v_and_b32_e32 v23, 0xffff0000, v23
	v_and_b32_e32 v22, 0xffff0000, v22
	v_pk_mul_f32 v[2:3], v[36:37], v[22:23]
	v_lshlrev_b32_e32 v24, 16, v20
	v_and_b32_e32 v21, 0xffff0000, v21
	v_and_b32_e32 v20, 0xffff0000, v20
	v_pk_mul_f32 v[26:27], v[36:37], v[26:27]
	v_pk_fma_f32 v[2:3], v[34:35], v[4:5], v[2:3]
	v_pk_fma_f32 v[26:27], v[34:35], v[28:29], v[26:27]
	v_pk_mul_f32 v[2:3], v[2:3], v[20:21]
	v_pk_mul_f32 v[24:25], v[26:27], v[24:25]
	v_cvt_pk_bf16_f32 v4, v25, v3
	v_cvt_pk_bf16_f32 v5, v24, v2
	v_mov_b32_e32 v3, v4
	v_mov_b32_e32 v2, v5
	global_store_dwordx2 v[18:19], v[2:3], off
	v_add_u32_e32 v2, 0x408, v38
	v_ashrrev_i32_e32 v3, 31, v2
	v_lshl_add_u64 v[2:3], v[0:1], 0, v[2:3]
	v_lshlrev_b64 v[2:3], 1, v[2:3]
	v_lshl_add_u64 v[4:5], s[16:17], 0, v[2:3]
	v_lshl_add_u64 v[18:19], s[46:47], 0, v[2:3]
	global_load_dwordx2 v[4:5], v[4:5], off
	s_nop 0
	global_load_dwordx2 v[18:19], v[18:19], off
	v_mov_b32_e32 v24, v6
	v_mov_b32_e32 v25, v8
	v_mov_b32_e32 v8, v7
	v_lshl_add_u64 v[2:3], s[18:19], 0, v[2:3]
	s_waitcnt vmcnt(1)
	v_lshlrev_b32_e32 v21, 16, v5
	s_waitcnt vmcnt(0)
	v_lshlrev_b32_e32 v23, 16, v19
	v_lshlrev_b32_e32 v22, 16, v18
	v_and_b32_e32 v19, 0xffff0000, v19
	v_and_b32_e32 v18, 0xffff0000, v18
	v_pk_mul_f32 v[6:7], v[36:37], v[18:19]
	v_lshlrev_b32_e32 v20, 16, v4
	v_and_b32_e32 v5, 0xffff0000, v5
	v_and_b32_e32 v4, 0xffff0000, v4
	v_pk_mul_f32 v[22:23], v[36:37], v[22:23]
	v_pk_fma_f32 v[6:7], v[34:35], v[8:9], v[6:7]
	v_pk_fma_f32 v[22:23], v[34:35], v[24:25], v[22:23]
	v_pk_mul_f32 v[4:5], v[6:7], v[4:5]
	v_pk_mul_f32 v[20:21], v[22:23], v[20:21]
	v_cvt_pk_bf16_f32 v6, v21, v5
	v_cvt_pk_bf16_f32 v7, v20, v4
	v_mov_b32_e32 v5, v6
	v_mov_b32_e32 v4, v7
	global_store_dwordx2 v[2:3], v[4:5], off
	v_add_u32_e32 v2, 0x410, v38
	v_ashrrev_i32_e32 v3, 31, v2
	v_lshl_add_u64 v[2:3], v[0:1], 0, v[2:3]
	v_lshlrev_b64 v[2:3], 1, v[2:3]
	v_lshl_add_u64 v[4:5], s[16:17], 0, v[2:3]
	v_lshl_add_u64 v[6:7], s[46:47], 0, v[2:3]
	global_load_dwordx2 v[4:5], v[4:5], off
	s_nop 0
	global_load_dwordx2 v[6:7], v[6:7], off
	v_mov_b32_e32 v20, v10
	v_mov_b32_e32 v21, v12
	v_mov_b32_e32 v12, v11
	v_lshl_add_u64 v[2:3], s[18:19], 0, v[2:3]
	s_waitcnt vmcnt(1)
	v_lshlrev_b32_e32 v9, 16, v5
	s_waitcnt vmcnt(0)
	v_lshlrev_b32_e32 v19, 16, v7
	v_lshlrev_b32_e32 v18, 16, v6
	v_and_b32_e32 v7, 0xffff0000, v7
	v_and_b32_e32 v6, 0xffff0000, v6
	v_pk_mul_f32 v[18:19], v[36:37], v[18:19]
	v_lshlrev_b32_e32 v8, 16, v4
	v_pk_fma_f32 v[18:19], v[34:35], v[20:21], v[18:19]
	v_pk_mul_f32 v[6:7], v[36:37], v[6:7]
	v_and_b32_e32 v5, 0xffff0000, v5
	v_and_b32_e32 v4, 0xffff0000, v4
	v_pk_mul_f32 v[8:9], v[18:19], v[8:9]
	v_pk_fma_f32 v[6:7], v[34:35], v[12:13], v[6:7]
	v_mov_b32_e32 v12, v14
	v_pk_mul_f32 v[4:5], v[6:7], v[4:5]
	v_cvt_pk_bf16_f32 v6, v9, v5
	v_cvt_pk_bf16_f32 v7, v8, v4
	v_mov_b32_e32 v5, v6
	v_mov_b32_e32 v4, v7
	global_store_dwordx2 v[2:3], v[4:5], off
	v_add_u32_e32 v2, 0x418, v38
	v_ashrrev_i32_e32 v3, 31, v2
	v_lshl_add_u64 v[2:3], v[0:1], 0, v[2:3]
	v_lshlrev_b64 v[2:3], 1, v[2:3]
	v_lshl_add_u64 v[4:5], s[16:17], 0, v[2:3]
	v_lshl_add_u64 v[6:7], s[46:47], 0, v[2:3]
	global_load_dwordx2 v[4:5], v[4:5], off
	s_nop 0
	global_load_dwordx2 v[6:7], v[6:7], off
	v_mov_b32_e32 v13, v16
	v_mov_b32_e32 v16, v15
	v_lshl_add_u64 v[2:3], s[18:19], 0, v[2:3]
	s_waitcnt vmcnt(1)
	v_lshlrev_b32_e32 v9, 16, v5
	s_waitcnt vmcnt(0)
	v_lshlrev_b32_e32 v11, 16, v7
	v_lshlrev_b32_e32 v10, 16, v6
	v_and_b32_e32 v7, 0xffff0000, v7
	v_and_b32_e32 v6, 0xffff0000, v6
	v_pk_mul_f32 v[10:11], v[36:37], v[10:11]
	v_lshlrev_b32_e32 v8, 16, v4
	v_pk_fma_f32 v[10:11], v[34:35], v[12:13], v[10:11]
	v_pk_mul_f32 v[6:7], v[36:37], v[6:7]
	v_and_b32_e32 v5, 0xffff0000, v5
	v_and_b32_e32 v4, 0xffff0000, v4
	v_pk_mul_f32 v[8:9], v[10:11], v[8:9]
	v_pk_fma_f32 v[6:7], v[34:35], v[16:17], v[6:7]
	v_and_b32_sdwa v0, v9, v177 dst_sel:DWORD dst_unused:UNUSED_PAD src0_sel:WORD_1 src1_sel:DWORD
	v_pk_mul_f32 v[4:5], v[6:7], v[4:5]
	v_and_b32_sdwa v6, v8, v177 dst_sel:DWORD dst_unused:UNUSED_PAD src0_sel:WORD_1 src1_sel:DWORD
	v_add3_u32 v6, v8, v6, s28
	v_and_b32_sdwa v7, v5, v177 dst_sel:DWORD dst_unused:UNUSED_PAD src0_sel:WORD_1 src1_sel:DWORD
	v_and_b32_sdwa v8, v4, v177 dst_sel:DWORD dst_unused:UNUSED_PAD src0_sel:WORD_1 src1_sel:DWORD
	v_add3_u32 v5, v5, v7, s28
	v_add3_u32 v4, v4, v8, s28
	v_add3_u32 v0, v9, v0, s28
	v_and_b32_e32 v5, 0xffff0000, v5
	v_and_b32_e32 v4, 0xffff0000, v4
	v_or_b32_sdwa v5, v5, v0 dst_sel:DWORD dst_unused:UNUSED_PAD src0_sel:DWORD src1_sel:WORD_1
	v_or_b32_sdwa v4, v4, v6 dst_sel:DWORD dst_unused:UNUSED_PAD src0_sel:DWORD src1_sel:WORD_1
	global_store_dwordx2 v[2:3], v[4:5], off
	s_branch .LBB0_961

.Lgate_loop:
	v_lshl_add_u64 v[248:249], v[2:3], 0, s[38:39]
	v_lshl_add_u64 v[248:249], v[248:249], 0, s[38:39]
	v_lshl_add_u64 v[198:199], v[248:249], 0, s[38:39]
	v_lshl_add_u64 v[198:199], v[198:199], 0, s[38:39]
	global_load_dwordx4 v[136:139], v[2:3], off offset:-2048
	global_load_dwordx4 v[140:143], v[2:3], off offset:-1024
	global_load_dwordx4 v[144:147], v[2:3], off
	global_load_dwordx4 v[148:151], v[2:3], off offset:1024
	global_load_dwordx4 v[152:155], v[2:3], off offset:2048
	global_load_dwordx4 v[156:159], v[2:3], off offset:3072
	global_load_dwordx4 v[160:163], v[248:249], off offset:-4096
	global_load_dwordx4 v[164:167], v[248:249], off offset:-3072
	global_load_dwordx4 v[168:171], v[248:249], off offset:-2048
	global_load_dwordx4 v[204:207], v[248:249], off offset:-1024
	global_load_dwordx4 v[212:215], v[248:249], off
	global_load_dwordx4 v[216:219], v[248:249], off offset:1024
	global_load_dwordx4 v[220:223], v[248:249], off offset:2048
	global_load_dwordx4 v[224:227], v[248:249], off offset:3072
	global_load_dwordx4 v[228:231], v[198:199], off offset:-4096
	global_load_dwordx4 v[232:235], v[198:199], off offset:-3072
	v_add_u32_e32 v0, s6, v33
	ds_read_b128 v[8:11], v0
	ds_read_b128 v[12:15], v0 offset:256
	ds_read_b128 v[236:239], v0 offset:512
	v_mov_b64_e32 v[2:3], v[198:199]
	s_add_i32 s6, s6, 64
	ds_read_b128 v[240:243], v0 offset:16
	ds_read_b128 v[244:247], v0 offset:272
	ds_read_b128 v[184:187], v0 offset:528
	s_waitcnt vmcnt(12)
	s_waitcnt lgkmcnt(3)
	v_pk_fma_f32 v[76:77], v[8:9], v[136:137], v[76:77] op_sel_hi:[0,1,1]
	v_pk_fma_f32 v[74:75], v[8:9], v[138:139], v[74:75] op_sel_hi:[0,1,1]
	v_pk_fma_f32 v[70:71], v[12:13], v[136:137], v[70:71] op_sel_hi:[0,1,1]
	v_pk_fma_f32 v[68:69], v[12:13], v[138:139], v[68:69] op_sel_hi:[0,1,1]
	v_pk_fma_f32 v[60:61], v[236:237], v[136:137], v[60:61] op_sel_hi:[0,1,1]
	v_pk_fma_f32 v[58:59], v[236:237], v[138:139], v[58:59] op_sel_hi:[0,1,1]
	v_pk_fma_f32 v[76:77], v[8:9], v[140:141], v[76:77] op_sel:[1,0,0]
	v_pk_fma_f32 v[74:75], v[8:9], v[142:143], v[74:75] op_sel:[1,0,0]
	v_pk_fma_f32 v[70:71], v[12:13], v[140:141], v[70:71] op_sel:[1,0,0]
	v_pk_fma_f32 v[68:69], v[12:13], v[142:143], v[68:69] op_sel:[1,0,0]
	v_pk_fma_f32 v[60:61], v[236:237], v[140:141], v[60:61] op_sel:[1,0,0]
	v_pk_fma_f32 v[58:59], v[236:237], v[142:143], v[58:59] op_sel:[1,0,0]
	v_pk_fma_f32 v[76:77], v[10:11], v[144:145], v[76:77] op_sel_hi:[0,1,1]
	v_pk_fma_f32 v[74:75], v[10:11], v[146:147], v[74:75] op_sel_hi:[0,1,1]
	v_pk_fma_f32 v[70:71], v[14:15], v[144:145], v[70:71] op_sel_hi:[0,1,1]
	v_pk_fma_f32 v[68:69], v[14:15], v[146:147], v[68:69] op_sel_hi:[0,1,1]
	v_pk_fma_f32 v[60:61], v[238:239], v[144:145], v[60:61] op_sel_hi:[0,1,1]
	v_pk_fma_f32 v[58:59], v[238:239], v[146:147], v[58:59] op_sel_hi:[0,1,1]
	v_pk_fma_f32 v[76:77], v[10:11], v[148:149], v[76:77] op_sel:[1,0,0]
	v_pk_fma_f32 v[74:75], v[10:11], v[150:151], v[74:75] op_sel:[1,0,0]
	v_pk_fma_f32 v[70:71], v[14:15], v[148:149], v[70:71] op_sel:[1,0,0]
	v_pk_fma_f32 v[68:69], v[14:15], v[150:151], v[68:69] op_sel:[1,0,0]
	v_pk_fma_f32 v[60:61], v[238:239], v[148:149], v[60:61] op_sel:[1,0,0]
	v_pk_fma_f32 v[58:59], v[238:239], v[150:151], v[58:59] op_sel:[1,0,0]
	ds_read_b128 v[8:11], v0 offset:32
	ds_read_b128 v[12:15], v0 offset:288
	ds_read_b128 v[236:239], v0 offset:544
	s_waitcnt vmcnt(8)
	s_waitcnt lgkmcnt(3)
	v_pk_fma_f32 v[76:77], v[240:241], v[152:153], v[76:77] op_sel_hi:[0,1,1]
	v_pk_fma_f32 v[74:75], v[240:241], v[154:155], v[74:75] op_sel_hi:[0,1,1]
	v_pk_fma_f32 v[70:71], v[244:245], v[152:153], v[70:71] op_sel_hi:[0,1,1]
	v_pk_fma_f32 v[68:69], v[244:245], v[154:155], v[68:69] op_sel_hi:[0,1,1]
	v_pk_fma_f32 v[60:61], v[184:185], v[152:153], v[60:61] op_sel_hi:[0,1,1]
	v_pk_fma_f32 v[58:59], v[184:185], v[154:155], v[58:59] op_sel_hi:[0,1,1]
	v_pk_fma_f32 v[76:77], v[240:241], v[156:157], v[76:77] op_sel:[1,0,0]
	v_pk_fma_f32 v[74:75], v[240:241], v[158:159], v[74:75] op_sel:[1,0,0]
	v_pk_fma_f32 v[70:71], v[244:245], v[156:157], v[70:71] op_sel:[1,0,0]
	v_pk_fma_f32 v[68:69], v[244:245], v[158:159], v[68:69] op_sel:[1,0,0]
	v_pk_fma_f32 v[60:61], v[184:185], v[156:157], v[60:61] op_sel:[1,0,0]
	v_pk_fma_f32 v[58:59], v[184:185], v[158:159], v[58:59] op_sel:[1,0,0]
	v_pk_fma_f32 v[76:77], v[242:243], v[160:161], v[76:77] op_sel_hi:[0,1,1]
	v_pk_fma_f32 v[74:75], v[242:243], v[162:163], v[74:75] op_sel_hi:[0,1,1]
	v_pk_fma_f32 v[70:71], v[246:247], v[160:161], v[70:71] op_sel_hi:[0,1,1]
	v_pk_fma_f32 v[68:69], v[246:247], v[162:163], v[68:69] op_sel_hi:[0,1,1]
	v_pk_fma_f32 v[60:61], v[186:187], v[160:161], v[60:61] op_sel_hi:[0,1,1]
	v_pk_fma_f32 v[58:59], v[186:187], v[162:163], v[58:59] op_sel_hi:[0,1,1]
	v_pk_fma_f32 v[76:77], v[242:243], v[164:165], v[76:77] op_sel:[1,0,0]
	v_pk_fma_f32 v[74:75], v[242:243], v[166:167], v[74:75] op_sel:[1,0,0]
	v_pk_fma_f32 v[70:71], v[246:247], v[164:165], v[70:71] op_sel:[1,0,0]
	v_pk_fma_f32 v[68:69], v[246:247], v[166:167], v[68:69] op_sel:[1,0,0]
	v_pk_fma_f32 v[60:61], v[186:187], v[164:165], v[60:61] op_sel:[1,0,0]
	v_pk_fma_f32 v[58:59], v[186:187], v[166:167], v[58:59] op_sel:[1,0,0]
	ds_read_b128 v[240:243], v0 offset:48
	ds_read_b128 v[244:247], v0 offset:304
	ds_read_b128 v[184:187], v0 offset:560
	s_waitcnt vmcnt(4)
	s_waitcnt lgkmcnt(3)
	v_pk_fma_f32 v[76:77], v[8:9], v[168:169], v[76:77] op_sel_hi:[0,1,1]
	v_pk_fma_f32 v[74:75], v[8:9], v[170:171], v[74:75] op_sel_hi:[0,1,1]
	v_pk_fma_f32 v[70:71], v[12:13], v[168:169], v[70:71] op_sel_hi:[0,1,1]
	v_pk_fma_f32 v[68:69], v[12:13], v[170:171], v[68:69] op_sel_hi:[0,1,1]
	v_pk_fma_f32 v[60:61], v[236:237], v[168:169], v[60:61] op_sel_hi:[0,1,1]
	v_pk_fma_f32 v[58:59], v[236:237], v[170:171], v[58:59] op_sel_hi:[0,1,1]
	v_pk_fma_f32 v[76:77], v[8:9], v[204:205], v[76:77] op_sel:[1,0,0]
	v_pk_fma_f32 v[74:75], v[8:9], v[206:207], v[74:75] op_sel:[1,0,0]
	v_pk_fma_f32 v[70:71], v[12:13], v[204:205], v[70:71] op_sel:[1,0,0]
	v_pk_fma_f32 v[68:69], v[12:13], v[206:207], v[68:69] op_sel:[1,0,0]
	v_pk_fma_f32 v[60:61], v[236:237], v[204:205], v[60:61] op_sel:[1,0,0]
	v_pk_fma_f32 v[58:59], v[236:237], v[206:207], v[58:59] op_sel:[1,0,0]
	v_pk_fma_f32 v[76:77], v[10:11], v[212:213], v[76:77] op_sel_hi:[0,1,1]
	v_pk_fma_f32 v[74:75], v[10:11], v[214:215], v[74:75] op_sel_hi:[0,1,1]
	v_pk_fma_f32 v[70:71], v[14:15], v[212:213], v[70:71] op_sel_hi:[0,1,1]
	v_pk_fma_f32 v[68:69], v[14:15], v[214:215], v[68:69] op_sel_hi:[0,1,1]
	v_pk_fma_f32 v[60:61], v[238:239], v[212:213], v[60:61] op_sel_hi:[0,1,1]
	v_pk_fma_f32 v[58:59], v[238:239], v[214:215], v[58:59] op_sel_hi:[0,1,1]
	v_pk_fma_f32 v[76:77], v[10:11], v[216:217], v[76:77] op_sel:[1,0,0]
	v_pk_fma_f32 v[74:75], v[10:11], v[218:219], v[74:75] op_sel:[1,0,0]
	v_pk_fma_f32 v[70:71], v[14:15], v[216:217], v[70:71] op_sel:[1,0,0]
	v_pk_fma_f32 v[68:69], v[14:15], v[218:219], v[68:69] op_sel:[1,0,0]
	v_pk_fma_f32 v[60:61], v[238:239], v[216:217], v[60:61] op_sel:[1,0,0]
	v_pk_fma_f32 v[58:59], v[238:239], v[218:219], v[58:59] op_sel:[1,0,0]
	s_waitcnt vmcnt(0)
	s_waitcnt lgkmcnt(0)
	v_pk_fma_f32 v[76:77], v[240:241], v[220:221], v[76:77] op_sel_hi:[0,1,1]
	v_pk_fma_f32 v[74:75], v[240:241], v[222:223], v[74:75] op_sel_hi:[0,1,1]
	v_pk_fma_f32 v[70:71], v[244:245], v[220:221], v[70:71] op_sel_hi:[0,1,1]
	v_pk_fma_f32 v[68:69], v[244:245], v[222:223], v[68:69] op_sel_hi:[0,1,1]
	v_pk_fma_f32 v[60:61], v[184:185], v[220:221], v[60:61] op_sel_hi:[0,1,1]
	v_pk_fma_f32 v[58:59], v[184:185], v[222:223], v[58:59] op_sel_hi:[0,1,1]
	v_pk_fma_f32 v[76:77], v[240:241], v[224:225], v[76:77] op_sel:[1,0,0]
	v_pk_fma_f32 v[74:75], v[240:241], v[226:227], v[74:75] op_sel:[1,0,0]
	v_pk_fma_f32 v[70:71], v[244:245], v[224:225], v[70:71] op_sel:[1,0,0]
	v_pk_fma_f32 v[68:69], v[244:245], v[226:227], v[68:69] op_sel:[1,0,0]
	v_pk_fma_f32 v[60:61], v[184:185], v[224:225], v[60:61] op_sel:[1,0,0]
	v_pk_fma_f32 v[58:59], v[184:185], v[226:227], v[58:59] op_sel:[1,0,0]
	v_pk_fma_f32 v[76:77], v[242:243], v[228:229], v[76:77] op_sel_hi:[0,1,1]
	v_pk_fma_f32 v[74:75], v[242:243], v[230:231], v[74:75] op_sel_hi:[0,1,1]
	v_pk_fma_f32 v[70:71], v[246:247], v[228:229], v[70:71] op_sel_hi:[0,1,1]
	v_pk_fma_f32 v[68:69], v[246:247], v[230:231], v[68:69] op_sel_hi:[0,1,1]
	v_pk_fma_f32 v[60:61], v[186:187], v[228:229], v[60:61] op_sel_hi:[0,1,1]
	v_pk_fma_f32 v[58:59], v[186:187], v[230:231], v[58:59] op_sel_hi:[0,1,1]
	v_pk_fma_f32 v[76:77], v[242:243], v[232:233], v[76:77] op_sel:[1,0,0]
	v_pk_fma_f32 v[74:75], v[242:243], v[234:235], v[74:75] op_sel:[1,0,0]
	v_pk_fma_f32 v[70:71], v[246:247], v[232:233], v[70:71] op_sel:[1,0,0]
	v_pk_fma_f32 v[68:69], v[246:247], v[234:235], v[68:69] op_sel:[1,0,0]
	v_pk_fma_f32 v[60:61], v[186:187], v[232:233], v[60:61] op_sel:[1,0,0]
	v_pk_fma_f32 v[58:59], v[186:187], v[234:235], v[58:59] op_sel:[1,0,0]
	s_cmpk_lg_i32 s6, 0x100
	s_cbranch_scc1 .Lgate_loop
	v_swap_b32 v77, v74
	v_swap_b32 v71, v68
	v_swap_b32 v61, v58
	v_cmp_gt_i32_e32 vcc, s11, v18
	v_lshlrev_b32_e32 v35, 2, v32
	v_lshlrev_b32_e32 v72, 1, v20
	v_lshlrev_b32_e32 v66, 1, v34
	s_and_saveexec_b64 s[14:15], vcc
	s_cbranch_execz .LBB0_1226
	v_ashrrev_i32_e32 v19, 31, v18
	v_lshlrev_b64 v[2:3], 9, v[18:19]
	v_lshl_add_u64 v[4:5], v[28:29], 0, v[2:3]
	v_lshl_add_u64 v[2:3], v[30:31], 0, v[2:3]
	global_load_dwordx2 v[8:9], v[4:5], off
	global_load_dwordx2 v[10:11], v[2:3], off
	v_mov_b64_e32 v[6:7], s[56:57]
	v_mad_i64_i32 v[80:81], s[6:7], v18, s24, v[6:7]
	v_mov_b32_e32 v73, v1
	s_load_dwordx2 s[6:7], s[52:53], 0xc8
	v_lshl_add_u64 v[2:3], v[80:81], 0, v[72:73]
	s_movk_i32 s2, 0x1000
	v_add_co_u32_e32 v2, vcc, s2, v2
	v_readlane_b32 s2, v255, 55
	v_readlane_b32 s3, v255, 56
	s_lshl_b64 s[12:13], s[2:3], 2
	s_waitcnt lgkmcnt(0)
	s_add_u32 s6, s6, s12
	v_addc_co_u32_e32 v3, vcc, 0, v3, vcc
	s_addc_u32 s7, s7, s13
	global_load_dwordx2 v[12:13], v[2:3], off offset:512
	v_add_u32_e32 v73, -1, v18
	global_load_dwordx4 v[2:5], v35, s[6:7]
	v_mov_b32_e32 v67, v1
	v_mad_i64_i32 v[88:89], s[6:7], v73, s24, v[6:7]
	v_lshl_add_u64 v[6:7], v[80:81], 0, v[66:67]
	global_load_dwordx2 v[86:87], v[6:7], off
	v_cmp_lt_i32_e64 s[44:45], v188, v182
	v_cmp_gt_i32_e32 vcc, s93, v18
	v_mov_b32_e32 v82, 0
	v_cndmask_b32_e64 v14, v181, v188, s[44:45]
	v_cmp_lt_i32_e64 s[44:45], v191, v182
	v_lshlrev_b32_e32 v65, 2, v14
	v_cndmask_b32_e32 v0, v252, v202, vcc
	v_cndmask_b32_e64 v15, v181, v191, s[44:45]
	v_lshlrev_b32_e32 v63, 2, v15
	v_lshlrev_b64 v[14:15], 11, v[18:19]
	v_cmp_lt_i32_e64 s[44:45], v190, v182
	v_lshl_add_u64 v[78:79], v[52:53], 0, v[14:15]
	v_and_b32_e32 v0, v0, v18
	v_cndmask_b32_e64 v16, v181, v190, s[44:45]
	v_cmp_lt_i32_e64 s[44:45], v189, v182
	v_lshlrev_b32_e32 v43, 2, v16
	v_mov_b32_e32 v84, 0
	v_cndmask_b32_e64 v17, v181, v189, s[44:45]
	v_lshlrev_b32_e32 v39, 2, v17
	v_cmp_ne_u32_e64 s[44:45], 0, v0
	s_waitcnt vmcnt(4)
	v_lshlrev_b32_e32 v7, 16, v9
	v_lshlrev_b32_e32 v6, 16, v8
	s_waitcnt vmcnt(3)
	v_lshlrev_b32_e32 v15, 16, v11
	v_lshlrev_b32_e32 v14, 16, v10
	v_and_b32_e32 v9, 0xffff0000, v9
	v_and_b32_e32 v8, 0xffff0000, v8
	v_and_b32_e32 v11, 0xffff0000, v11
	v_and_b32_e32 v10, 0xffff0000, v10
	v_pk_add_f32 v[6:7], v[6:7], v[14:15]
	v_pk_add_f32 v[8:9], v[8:9], v[10:11]
	v_mov_b32_e32 v14, v6
	v_mov_b32_e32 v15, v8
	v_mov_b32_e32 v16, v9
	v_mov_b32_e32 v17, v7
	v_pk_mul_f32 v[14:15], v[14:15], v[14:15]
	v_pk_mul_f32 v[16:17], v[16:17], v[16:17]
	v_add_f32_e32 v14, v14, v15
	v_add_f32_e32 v14, v14, v17
	v_add_f32_e32 v14, v16, v14
	s_waitcnt vmcnt(2)
	v_lshlrev_b32_e32 v11, 16, v13
	v_lshlrev_b32_e32 v10, 16, v12
	v_and_b32_e32 v13, 0xffff0000, v13
	v_and_b32_e32 v12, 0xffff0000, v12
	s_waitcnt lgkmcnt(0)
	s_nop 1
	v_add_f32_dpp v85, v14, v14 quad_perm:[1,0,3,2] row_mask:0xf bank_mask:0xf bound_ctrl:1
	s_waitcnt vmcnt(1)
	v_mov_b32_e32 v14, v2
	v_mov_b32_e32 v15, v4
	v_mul_f32_e32 v73, 0xbfb8aa3b, v10
	v_mul_f32_e32 v83, 0xbfb8aa3b, v12
	s_waitcnt lgkmcnt(0)
	s_nop 1
	v_add_f32_dpp v2, v85, v85 quad_perm:[2,3,0,1] row_mask:0xf bank_mask:0xf bound_ctrl:1
	v_mul_f32_e32 v16, 0xbfb8aa3b, v11
	v_mul_f32_e32 v17, 0xbfb8aa3b, v13
	v_exp_f32_e32 v73, v73
	v_exp_f32_e32 v83, v83
	s_waitcnt lgkmcnt(0)
	s_nop 1
	v_add_f32_dpp v2, v2, v2 row_half_mirror row_mask:0xf bank_mask:0xf bound_ctrl:1
	v_exp_f32_e32 v16, v16
	v_exp_f32_e32 v17, v17
	v_add_f32_e32 v73, 1.0, v73
	v_add_f32_e32 v83, 1.0, v83
	s_waitcnt lgkmcnt(0)
	s_nop 1
	v_add_f32_dpp v2, v2, v2 row_mirror row_mask:0xf bank_mask:0xf bound_ctrl:1
	v_fmamk_f32 v2, v2, 0x3c800000, v174
	v_mul_f32_e32 v4, 0x4b800000, v2
	v_cmp_gt_f32_e64 s[46:47], s27, v2
	v_add_f32_e32 v85, 1.0, v16
	v_add_f32_e32 v91, 1.0, v17
	v_cndmask_b32_e64 v2, v2, v4, s[46:47]
	v_rcp_f32_e32 v16, v73
	v_rcp_f32_e32 v90, v83
	v_rcp_f32_e32 v17, v85
	v_rcp_f32_e32 v91, v91
	v_rsq_f32_e32 v73, v2
	v_mov_b32_e32 v4, v3
	v_pk_mul_f32 v[2:3], v[16:17], v[10:11]
	v_pk_mul_f32 v[10:11], v[90:91], v[12:13]
	v_mul_f32_e32 v12, 0x45800000, v73
	v_cndmask_b32_e64 v12, v73, v12, s[46:47]
	v_pk_mul_f32 v[8:9], v[8:9], v[12:13] op_sel_hi:[1,0]
	v_pk_mul_f32 v[6:7], v[6:7], v[12:13] op_sel_hi:[1,0]
	v_pk_mul_f32 v[4:5], v[4:5], v[8:9]
	v_pk_mul_f32 v[6:7], v[14:15], v[6:7]
	v_pk_mul_f32 v[4:5], v[10:11], v[4:5]
	v_pk_mul_f32 v[2:3], v[2:3], v[6:7]
	v_cvt_pk_bf16_f32 v3, v3, v5
	v_cvt_pk_bf16_f32 v2, v2, v4
	v_mov_b32_e32 v85, 0
	global_store_dwordx2 v[78:79], v[2:3], off offset:1024
	s_and_saveexec_b64 s[16:17], s[44:45]
	s_cbranch_execz .LBB0_1214
	v_lshl_add_u64 v[2:3], v[88:89], 0, v[66:67]
	global_load_dwordx2 v[84:85], v[2:3], off

.LBB0_1227:
	v_ashrrev_i32_e32 v65, 31, v64
	v_lshlrev_b64 v[2:3], 9, v[64:65]
	v_lshl_add_u64 v[4:5], v[28:29], 0, v[2:3]
	v_lshl_add_u64 v[2:3], v[30:31], 0, v[2:3]
	global_load_dwordx2 v[8:9], v[4:5], off
	global_load_dwordx2 v[10:11], v[2:3], off
	v_mov_b64_e32 v[6:7], s[56:57]
	v_mad_i64_i32 v[76:77], s[6:7], v64, s24, v[6:7]
	v_mov_b32_e32 v73, v1
	s_load_dwordx2 s[6:7], s[52:53], 0xc8
	v_lshl_add_u64 v[2:3], v[76:77], 0, v[72:73]
	s_movk_i32 s2, 0x1000
	v_add_co_u32_e32 v2, vcc, s2, v2
	v_readlane_b32 s2, v255, 55
	v_readlane_b32 s3, v255, 56
	s_lshl_b64 s[12:13], s[2:3], 2
	s_waitcnt lgkmcnt(0)
	s_add_u32 s6, s6, s12
	v_addc_co_u32_e32 v3, vcc, 0, v3, vcc
	s_addc_u32 s7, s7, s13
	global_load_dwordx2 v[12:13], v[2:3], off offset:512
	v_mov_b32_e32 v67, v1
	global_load_dwordx4 v[2:5], v35, s[6:7]
	v_mad_i64_i32 v[84:85], s[6:7], v18, s24, v[6:7]
	v_lshl_add_u64 v[6:7], v[76:77], 0, v[66:67]
	global_load_dwordx2 v[82:83], v[6:7], off
	v_cmp_lt_i32_e64 s[44:45], v188, v182
	v_cmp_gt_i32_e32 vcc, s97, v18
	v_mov_b32_e32 v78, 0
	v_cndmask_b32_e64 v14, v181, v188, s[44:45]
	v_cmp_lt_i32_e64 s[44:45], v191, v182
	v_lshlrev_b32_e32 v63, 2, v14
	v_cndmask_b32_e32 v0, v252, v202, vcc
	v_cndmask_b32_e64 v15, v181, v191, s[44:45]
	v_lshlrev_b32_e32 v43, 2, v15
	v_lshlrev_b64 v[14:15], 11, v[64:65]
	v_cmp_lt_i32_e64 s[44:45], v190, v182
	v_lshl_add_u64 v[74:75], v[52:53], 0, v[14:15]
	v_and_b32_e32 v0, v0, v64
	v_cndmask_b32_e64 v16, v181, v190, s[44:45]
	v_cmp_lt_i32_e64 s[44:45], v189, v182
	v_lshlrev_b32_e32 v39, 2, v16
	v_mov_b32_e32 v80, 0
	v_cndmask_b32_e64 v17, v181, v189, s[44:45]
	v_lshlrev_b32_e32 v19, 2, v17
	v_cmp_ne_u32_e64 s[44:45], 0, v0
	s_waitcnt vmcnt(4)
	v_lshlrev_b32_e32 v7, 16, v9
	v_lshlrev_b32_e32 v6, 16, v8
	s_waitcnt vmcnt(3)
	v_lshlrev_b32_e32 v15, 16, v11
	v_lshlrev_b32_e32 v14, 16, v10
	v_and_b32_e32 v9, 0xffff0000, v9
	v_and_b32_e32 v8, 0xffff0000, v8
	v_and_b32_e32 v11, 0xffff0000, v11
	v_and_b32_e32 v10, 0xffff0000, v10
	v_pk_add_f32 v[6:7], v[6:7], v[14:15]
	v_pk_add_f32 v[8:9], v[8:9], v[10:11]
	v_mov_b32_e32 v14, v6
	v_mov_b32_e32 v15, v8
	v_mov_b32_e32 v16, v9
	v_mov_b32_e32 v17, v7
	v_pk_mul_f32 v[14:15], v[14:15], v[14:15]
	v_pk_mul_f32 v[16:17], v[16:17], v[16:17]
	v_add_f32_e32 v14, v14, v15
	v_add_f32_e32 v14, v14, v17
	v_add_f32_e32 v14, v16, v14
	s_waitcnt vmcnt(2)
	v_lshlrev_b32_e32 v11, 16, v13
	v_lshlrev_b32_e32 v10, 16, v12
	v_and_b32_e32 v13, 0xffff0000, v13
	v_and_b32_e32 v12, 0xffff0000, v12
	s_waitcnt lgkmcnt(0)
	s_nop 1
	v_add_f32_dpp v81, v14, v14 quad_perm:[1,0,3,2] row_mask:0xf bank_mask:0xf bound_ctrl:1
	s_waitcnt vmcnt(1)
	v_mov_b32_e32 v14, v2
	v_mov_b32_e32 v15, v4
	v_mul_f32_e32 v73, 0xbfb8aa3b, v10
	v_mul_f32_e32 v79, 0xbfb8aa3b, v12
	s_waitcnt lgkmcnt(0)
	s_nop 1
	v_add_f32_dpp v2, v81, v81 quad_perm:[2,3,0,1] row_mask:0xf bank_mask:0xf bound_ctrl:1
	v_mul_f32_e32 v16, 0xbfb8aa3b, v11
	v_mul_f32_e32 v17, 0xbfb8aa3b, v13
	v_exp_f32_e32 v73, v73
	v_exp_f32_e32 v79, v79
	s_waitcnt lgkmcnt(0)
	s_nop 1
	v_add_f32_dpp v2, v2, v2 row_half_mirror row_mask:0xf bank_mask:0xf bound_ctrl:1
	v_exp_f32_e32 v16, v16
	v_exp_f32_e32 v17, v17
	v_add_f32_e32 v73, 1.0, v73
	v_add_f32_e32 v79, 1.0, v79
	s_waitcnt lgkmcnt(0)
	s_nop 1
	v_add_f32_dpp v2, v2, v2 row_mirror row_mask:0xf bank_mask:0xf bound_ctrl:1
	v_fmamk_f32 v2, v2, 0x3c800000, v174
	v_mul_f32_e32 v4, 0x4b800000, v2
	v_cmp_gt_f32_e64 s[46:47], s27, v2
	v_add_f32_e32 v81, 1.0, v16
	v_add_f32_e32 v87, 1.0, v17
	v_cndmask_b32_e64 v2, v2, v4, s[46:47]
	v_rcp_f32_e32 v16, v73
	v_rcp_f32_e32 v86, v79
	v_rcp_f32_e32 v17, v81
	v_rcp_f32_e32 v87, v87
	v_rsq_f32_e32 v73, v2
	v_mov_b32_e32 v4, v3
	v_pk_mul_f32 v[2:3], v[16:17], v[10:11]
	v_pk_mul_f32 v[10:11], v[86:87], v[12:13]
	v_mul_f32_e32 v12, 0x45800000, v73
	v_cndmask_b32_e64 v12, v73, v12, s[46:47]
	v_pk_mul_f32 v[8:9], v[8:9], v[12:13] op_sel_hi:[1,0]
	v_pk_mul_f32 v[6:7], v[6:7], v[12:13] op_sel_hi:[1,0]
	v_pk_mul_f32 v[4:5], v[4:5], v[8:9]
	v_pk_mul_f32 v[6:7], v[14:15], v[6:7]
	v_pk_mul_f32 v[4:5], v[10:11], v[4:5]
	v_pk_mul_f32 v[2:3], v[2:3], v[6:7]
	v_cvt_pk_bf16_f32 v3, v3, v5
	v_cvt_pk_bf16_f32 v2, v2, v4
	v_mov_b32_e32 v81, 0
	global_store_dwordx2 v[74:75], v[2:3], off offset:1024
	s_and_saveexec_b64 s[16:17], s[44:45]
	s_cbranch_execz .LBB0_1229
	v_lshl_add_u64 v[2:3], v[84:85], 0, v[66:67]
	global_load_dwordx2 v[80:81], v[2:3], off

.LBB0_1240:
	v_ashrrev_i32_e32 v63, 31, v62
	v_lshlrev_b64 v[2:3], 9, v[62:63]
	v_lshl_add_u64 v[4:5], v[28:29], 0, v[2:3]
	v_lshl_add_u64 v[2:3], v[30:31], 0, v[2:3]
	global_load_dwordx2 v[8:9], v[4:5], off
	global_load_dwordx2 v[10:11], v[2:3], off
	v_mov_b64_e32 v[6:7], s[56:57]
	v_mad_i64_i32 v[68:69], s[6:7], v62, s24, v[6:7]
	v_mov_b32_e32 v73, v1
	s_load_dwordx2 s[6:7], s[52:53], 0xc8
	v_lshl_add_u64 v[2:3], v[68:69], 0, v[72:73]
	s_movk_i32 s2, 0x1000
	v_add_co_u32_e32 v2, vcc, s2, v2
	v_readlane_b32 s2, v255, 55
	v_readlane_b32 s3, v255, 56
	s_lshl_b64 s[12:13], s[2:3], 2
	s_waitcnt lgkmcnt(0)
	s_add_u32 s6, s6, s12
	v_addc_co_u32_e32 v3, vcc, 0, v3, vcc
	s_addc_u32 s7, s7, s13
	global_load_dwordx2 v[12:13], v[2:3], off offset:512
	v_mov_b32_e32 v67, v1
	global_load_dwordx4 v[2:5], v35, s[6:7]
	v_mad_i64_i32 v[76:77], s[6:7], v64, s24, v[6:7]
	v_lshl_add_u64 v[6:7], v[68:69], 0, v[66:67]
	global_load_dwordx2 v[74:75], v[6:7], off
	v_cmp_lt_i32_e64 s[44:45], v188, v182
	s_movk_i32 s2, 0x3ffe
	v_cmp_gt_i32_e32 vcc, s2, v18
	v_cndmask_b32_e64 v14, v181, v188, s[44:45]
	v_cmp_lt_i32_e64 s[44:45], v191, v182
	v_lshlrev_b32_e32 v43, 2, v14
	v_cndmask_b32_e32 v0, v252, v202, vcc
	v_cndmask_b32_e64 v15, v181, v191, s[44:45]
	v_lshlrev_b32_e32 v39, 2, v15
	v_lshlrev_b64 v[14:15], 11, v[62:63]
	v_cmp_lt_i32_e64 s[44:45], v190, v182
	v_lshl_add_u64 v[64:65], v[52:53], 0, v[14:15]
	v_and_b32_e32 v0, v0, v62
	v_cndmask_b32_e64 v16, v181, v190, s[44:45]
	v_cmp_lt_i32_e64 s[44:45], v189, v182
	v_lshlrev_b32_e32 v35, 2, v16
	v_mov_b32_e32 v70, 0
	v_cndmask_b32_e64 v17, v181, v189, s[44:45]
	v_lshlrev_b32_e32 v19, 2, v17
	v_mov_b32_e32 v72, 0
	v_cmp_ne_u32_e64 s[44:45], 0, v0
	s_waitcnt vmcnt(4)
	v_lshlrev_b32_e32 v7, 16, v9
	v_lshlrev_b32_e32 v6, 16, v8
	s_waitcnt vmcnt(3)
	v_lshlrev_b32_e32 v15, 16, v11
	v_lshlrev_b32_e32 v14, 16, v10
	v_and_b32_e32 v9, 0xffff0000, v9
	v_and_b32_e32 v8, 0xffff0000, v8
	v_and_b32_e32 v11, 0xffff0000, v11
	v_and_b32_e32 v10, 0xffff0000, v10
	v_pk_add_f32 v[6:7], v[6:7], v[14:15]
	v_pk_add_f32 v[8:9], v[8:9], v[10:11]
	v_mov_b32_e32 v14, v6
	v_mov_b32_e32 v15, v8
	v_mov_b32_e32 v16, v9
	v_mov_b32_e32 v17, v7
	v_pk_mul_f32 v[14:15], v[14:15], v[14:15]
	v_pk_mul_f32 v[16:17], v[16:17], v[16:17]
	v_add_f32_e32 v14, v14, v15
	v_add_f32_e32 v14, v14, v17
	v_add_f32_e32 v14, v16, v14
	s_waitcnt vmcnt(2)
	v_lshlrev_b32_e32 v11, 16, v13
	v_lshlrev_b32_e32 v10, 16, v12
	v_and_b32_e32 v13, 0xffff0000, v13
	v_and_b32_e32 v12, 0xffff0000, v12
	s_waitcnt lgkmcnt(0)
	s_nop 1
	v_add_f32_dpp v78, v14, v14 quad_perm:[1,0,3,2] row_mask:0xf bank_mask:0xf bound_ctrl:1
	s_waitcnt vmcnt(1)
	v_mov_b32_e32 v14, v2
	v_mov_b32_e32 v15, v4
	v_mul_f32_e32 v71, 0xbfb8aa3b, v10
	v_mul_f32_e32 v73, 0xbfb8aa3b, v12
	s_waitcnt lgkmcnt(0)
	s_nop 1
	v_add_f32_dpp v2, v78, v78 quad_perm:[2,3,0,1] row_mask:0xf bank_mask:0xf bound_ctrl:1
	v_mul_f32_e32 v16, 0xbfb8aa3b, v11
	v_mul_f32_e32 v17, 0xbfb8aa3b, v13
	v_exp_f32_e32 v71, v71
	v_exp_f32_e32 v73, v73
	s_waitcnt lgkmcnt(0)
	s_nop 1
	v_add_f32_dpp v2, v2, v2 row_half_mirror row_mask:0xf bank_mask:0xf bound_ctrl:1
	v_exp_f32_e32 v16, v16
	v_exp_f32_e32 v17, v17
	v_add_f32_e32 v71, 1.0, v71
	v_add_f32_e32 v73, 1.0, v73
	s_waitcnt lgkmcnt(0)
	s_nop 1
	v_add_f32_dpp v2, v2, v2 row_mirror row_mask:0xf bank_mask:0xf bound_ctrl:1
	v_fmamk_f32 v2, v2, 0x3c800000, v174
	v_mul_f32_e32 v4, 0x4b800000, v2
	v_cmp_gt_f32_e64 s[46:47], s27, v2
	v_add_f32_e32 v79, 1.0, v16
	v_add_f32_e32 v80, 1.0, v17
	v_cndmask_b32_e64 v2, v2, v4, s[46:47]
	v_rcp_f32_e32 v16, v71
	v_rcp_f32_e32 v78, v73
	v_rcp_f32_e32 v17, v79
	v_rcp_f32_e32 v79, v80
	v_rsq_f32_e32 v71, v2
	v_mov_b32_e32 v4, v3
	v_pk_mul_f32 v[2:3], v[16:17], v[10:11]
	v_pk_mul_f32 v[10:11], v[78:79], v[12:13]
	v_mul_f32_e32 v12, 0x45800000, v71
	v_cndmask_b32_e64 v12, v71, v12, s[46:47]
	v_pk_mul_f32 v[8:9], v[8:9], v[12:13] op_sel_hi:[1,0]
	v_pk_mul_f32 v[6:7], v[6:7], v[12:13] op_sel_hi:[1,0]
	v_pk_mul_f32 v[4:5], v[4:5], v[8:9]
	v_pk_mul_f32 v[6:7], v[14:15], v[6:7]
	v_pk_mul_f32 v[4:5], v[10:11], v[4:5]
	v_pk_mul_f32 v[2:3], v[2:3], v[6:7]
	v_cvt_pk_bf16_f32 v3, v3, v5
	v_cvt_pk_bf16_f32 v2, v2, v4
	v_mov_b32_e32 v73, 0
	global_store_dwordx2 v[64:65], v[2:3], off offset:1024
	s_and_saveexec_b64 s[16:17], s[44:45]
	s_cbranch_execz .LBB0_1242
	v_lshl_add_u64 v[2:3], v[76:77], 0, v[66:67]
	global_load_dwordx2 v[72:73], v[2:3], off

.LBB0_1379:
	s_or_b64 exec, exec, s[46:47]
	v_lshl_add_u64 v[2:3], v[2:3], 0, v[0:1]
	global_load_dwordx4 v[36:39], v[2:3], off
	global_load_dwordx4 v[40:43], v[2:3], off offset:1024
	global_load_dwordx4 v[44:47], v[2:3], off offset:2048
	s_nop 0
	global_load_dwordx4 v[2:5], v[2:3], off offset:3072
	s_nop 0
	global_load_dwordx4 v[48:51], v[8:9], off
	global_load_dwordx4 v[78:81], v[10:11], off
	global_load_dwordx4 v[90:93], v[12:13], off
	global_load_dwordx4 v[102:105], v[14:15], off
	v_min_i32_e32 v19, 0x4000, v6
	v_ashrrev_i32_e32 v19, 11, v19
	v_mul_hi_i32_i24_e32 v25, 0x9000, v19
	v_mul_i32_i24_e32 v24, 0x9000, v19
	v_lshl_add_u64 v[24:25], s[16:17], 0, v[24:25]
	v_lshl_add_u64 v[26:27], v[24:25], 0, s[38:39]
	v_lshl_add_u64 v[28:29], v[26:27], 0, v[0:1]
	global_load_dwordx4 v[52:55], v[28:29], off
	global_load_dwordx4 v[82:85], v[28:29], off offset:1024
	global_load_dwordx4 v[94:97], v[28:29], off offset:2048
	global_load_dwordx4 v[106:109], v[28:29], off offset:3072
	v_lshl_add_u64 v[28:29], v[24:25], 0, v[0:1]
	global_load_dwordx4 v[56:59], v[28:29], off
	global_load_dwordx4 v[86:89], v[28:29], off offset:1024
	global_load_dwordx4 v[98:101], v[28:29], off offset:2048
	global_load_dwordx4 v[110:113], v[28:29], off offset:3072
	s_mov_b32 s2, s42
	s_waitcnt vmcnt(15)
	v_mov_b32_e32 v60, v37
	s_waitcnt vmcnt(14)
	v_mov_b32_e32 v61, v41
	v_mov_b32_e32 v24, v36
	v_mov_b32_e32 v25, v40
	s_waitcnt vmcnt(13)
	v_mov_b32_e32 v68, v45
	s_waitcnt vmcnt(12)
	v_mov_b32_e32 v69, v3
	v_pk_mul_f32 v[60:61], v[60:61], v[60:61]
	v_mov_b32_e32 v62, v38
	v_mov_b32_e32 v63, v42
	v_mov_b32_e32 v66, v44
	v_mov_b32_e32 v67, v2
	v_pk_mul_f32 v[68:69], v[68:69], v[68:69]
	v_pk_fma_f32 v[24:25], v[24:25], v[24:25], v[60:61]
	v_mov_b32_e32 v64, v39
	v_mov_b32_e32 v65, v43
	v_mov_b32_e32 v70, v46
	v_mov_b32_e32 v71, v4
	v_pk_fma_f32 v[60:61], v[66:67], v[66:67], v[68:69]
	v_pk_fma_f32 v[24:25], v[62:63], v[62:63], v[24:25]
	v_mov_b32_e32 v72, v47
	v_mov_b32_e32 v73, v5
	v_pk_fma_f32 v[60:61], v[70:71], v[70:71], v[60:61]
	v_pk_fma_f32 v[24:25], v[64:65], v[64:65], v[24:25]
	v_pk_fma_f32 v[60:61], v[72:73], v[72:73], v[60:61]
	v_add_f32_e32 v19, v24, v25
	v_add_f32_e32 v19, v19, v60
	v_add_f32_e32 v19, v19, v61
	ds_bpermute_b32 v21, v30, v19
	v_lshlrev_b64 v[24:25], 11, v[6:7]
	s_waitcnt vmcnt(11)
	v_mov_b32_e32 v60, v48
	v_mov_b32_e32 v48, v36
	v_mov_b32_e32 v36, v37
	s_waitcnt lgkmcnt(0)
	v_add_f32_e32 v19, v19, v21
	ds_bpermute_b32 v21, v31, v19
	v_mov_b32_e32 v37, v39
	s_waitcnt vmcnt(3)
	v_mov_b32_e32 v62, v56
	v_mov_b32_e32 v61, v50
	v_mov_b32_e32 v50, v49
	s_waitcnt lgkmcnt(0)
	v_add_f32_e32 v21, v19, v21
	ds_bpermute_b32 v23, v32, v21
	v_mov_b32_e32 v49, v38
	v_mov_b32_e32 v39, v54
	v_mov_b32_e32 v54, v53
	v_mov_b32_e32 v38, v52
	s_waitcnt lgkmcnt(0)
	v_add_f32_e32 v7, v21, v23
	ds_bpermute_b32 v21, v33, v7
	v_mov_b32_e32 v63, v58
	v_mov_b32_e32 v58, v57
	v_pk_add_f32 v[52:53], v[54:55], 1.0 op_sel_hi:[1,0]
	v_pk_add_f32 v[38:39], v[38:39], 1.0 op_sel_hi:[1,0]
	s_waitcnt lgkmcnt(0)
	v_add_f32_e32 v7, v7, v21
	ds_bpermute_b32 v21, v34, v7
	v_lshl_add_u64 v[24:25], v[16:17], 0, v[24:25]
	v_mov_b32_e32 v19, v1
	s_waitcnt lgkmcnt(0)
	v_add_f32_e32 v7, v7, v21
	ds_bpermute_b32 v21, v35, v7
	s_waitcnt lgkmcnt(0)
	v_add_f32_e32 v7, v7, v21
	v_fmamk_f32 v7, v7, 0x3a800000, v174
	v_mul_f32_e32 v21, 0x4b800000, v7
	v_cmp_gt_f32_e32 vcc, s27, v7
	s_nop 1
	v_cndmask_b32_e32 v7, v7, v21, vcc
	v_rsq_f32_e32 v7, v7
	s_nop 0
	v_mul_f32_e32 v21, 0x45800000, v7
	v_cndmask_b32_e32 v56, v7, v21, vcc
	v_pk_mul_f32 v[36:37], v[36:37], v[56:57] op_sel_hi:[1,0]
	v_pk_mul_f32 v[48:49], v[48:49], v[56:57] op_sel_hi:[1,0]
	v_pk_mul_f32 v[36:37], v[50:51], v[36:37]
	v_pk_mul_f32 v[48:49], v[60:61], v[48:49]
	v_pk_fma_f32 v[36:37], v[52:53], v[36:37], v[58:59]
	v_pk_fma_f32 v[38:39], v[38:39], v[48:49], v[62:63]
	v_cvt_pk_bf16_f32 v21, v38, v36
	v_cvt_pk_bf16_f32 v37, v39, v37
	v_mov_b32_e32 v36, v21
	global_store_dwordx2 v[24:25], v[36:37], off
	v_lshl_add_u64 v[48:49], v[26:27], 0, v[18:19]
	s_waitcnt vmcnt(1)
	v_mov_b32_e32 v52, v86
	v_mov_b32_e32 v53, v87
	v_mov_b32_e32 v54, v88
	v_mov_b32_e32 v55, v89
	v_mov_b32_e32 v48, v82
	v_mov_b32_e32 v49, v83
	v_mov_b32_e32 v50, v84
	v_mov_b32_e32 v51, v85
	v_mov_b32_e32 v36, v78
	v_mov_b32_e32 v37, v79
	v_mov_b32_e32 v38, v80
	v_mov_b32_e32 v39, v81
	v_mov_b32_e32 v58, v40
	v_mov_b32_e32 v59, v42
	v_mov_b32_e32 v42, v41
	v_pk_mul_f32 v[40:41], v[58:59], v[56:57] op_sel_hi:[1,0]
	v_pk_mul_f32 v[42:43], v[42:43], v[56:57] op_sel_hi:[1,0]
	v_mov_b32_e32 v21, v1
	v_mov_b32_e32 v58, v36
	v_mov_b32_e32 v59, v38
	v_mov_b32_e32 v60, v48
	v_mov_b32_e32 v61, v50
	v_mov_b32_e32 v38, v37
	v_mov_b32_e32 v50, v49
	v_mov_b32_e32 v62, v52
	v_mov_b32_e32 v63, v54
	v_mov_b32_e32 v54, v53
	v_pk_mul_f32 v[36:37], v[40:41], v[58:59]
	v_pk_add_f32 v[40:41], v[60:61], 1.0 op_sel_hi:[1,0]
	v_pk_mul_f32 v[38:39], v[42:43], v[38:39]
	v_pk_add_f32 v[42:43], v[50:51], 1.0 op_sel_hi:[1,0]
	v_pk_fma_f32 v[36:37], v[36:37], v[40:41], v[62:63]
	v_pk_fma_f32 v[38:39], v[38:39], v[42:43], v[54:55]
	v_cvt_pk_bf16_f32 v19, v36, v38
	v_cvt_pk_bf16_f32 v37, v37, v39
	v_mov_b32_e32 v36, v19
	global_store_dwordx2 v[24:25], v[36:37], off offset:512
	v_lshl_add_u64 v[40:41], v[26:27], 0, v[20:21]
	v_mov_b32_e32 v48, v98
	v_mov_b32_e32 v49, v99
	v_mov_b32_e32 v50, v100
	v_mov_b32_e32 v51, v101
	v_mov_b32_e32 v40, v94
	v_mov_b32_e32 v41, v95
	v_mov_b32_e32 v42, v96
	v_mov_b32_e32 v43, v97
	v_mov_b32_e32 v36, v90
	v_mov_b32_e32 v37, v91
	v_mov_b32_e32 v38, v92
	v_mov_b32_e32 v39, v93
	v_mov_b32_e32 v52, v44
	v_mov_b32_e32 v53, v46
	v_mov_b32_e32 v44, v45
	v_mov_b32_e32 v45, v47
	v_pk_mul_f32 v[46:47], v[52:53], v[56:57] op_sel_hi:[1,0]
	v_pk_mul_f32 v[44:45], v[44:45], v[56:57] op_sel_hi:[1,0]
	v_mov_b32_e32 v23, v1
	v_lshl_add_u64 v[26:27], v[26:27], 0, v[22:23]
	v_mov_b32_e32 v52, v36
	v_mov_b32_e32 v53, v38
	v_mov_b32_e32 v54, v40
	v_mov_b32_e32 v55, v42
	v_mov_b32_e32 v38, v37
	v_mov_b32_e32 v42, v41
	v_mov_b32_e32 v58, v48
	v_mov_b32_e32 v59, v50
	v_mov_b32_e32 v50, v49
	v_pk_mul_f32 v[36:37], v[46:47], v[52:53]
	v_pk_add_f32 v[40:41], v[54:55], 1.0 op_sel_hi:[1,0]
	v_pk_mul_f32 v[38:39], v[44:45], v[38:39]
	v_pk_add_f32 v[42:43], v[42:43], 1.0 op_sel_hi:[1,0]
	v_pk_fma_f32 v[36:37], v[36:37], v[40:41], v[58:59]
	v_pk_fma_f32 v[38:39], v[38:39], v[42:43], v[50:51]
	v_cvt_pk_bf16_f32 v19, v36, v38
	v_cvt_pk_bf16_f32 v37, v37, v39
	v_mov_b32_e32 v36, v19
	global_store_dwordx2 v[24:25], v[36:37], off offset:1024
	v_mov_b32_e32 v26, v110
	v_mov_b32_e32 v27, v111
	v_mov_b32_e32 v28, v112
	v_mov_b32_e32 v29, v113
	v_mov_b32_e32 v40, v106
	v_mov_b32_e32 v41, v107
	v_mov_b32_e32 v42, v108
	v_mov_b32_e32 v43, v109
	v_mov_b32_e32 v36, v102
	v_mov_b32_e32 v37, v103
	v_mov_b32_e32 v38, v104
	v_mov_b32_e32 v39, v105
	v_mov_b32_e32 v44, v2
	v_mov_b32_e32 v45, v4
	v_mov_b32_e32 v4, v3
	v_pk_mul_f32 v[2:3], v[44:45], v[56:57] op_sel_hi:[1,0]
	v_pk_mul_f32 v[4:5], v[4:5], v[56:57] op_sel_hi:[1,0]
	v_mov_b32_e32 v47, v42
	v_mov_b32_e32 v45, v38
	v_mov_b32_e32 v38, v37
	v_mov_b32_e32 v42, v41
	v_mov_b32_e32 v44, v36
	v_mov_b32_e32 v46, v40
	v_mov_b32_e32 v49, v28
	v_mov_b32_e32 v28, v27
	v_pk_mul_f32 v[4:5], v[4:5], v[38:39]
	v_pk_add_f32 v[36:37], v[42:43], 1.0 op_sel_hi:[1,0]
	v_mov_b32_e32 v48, v26
	v_pk_mul_f32 v[2:3], v[2:3], v[44:45]
	v_pk_add_f32 v[26:27], v[46:47], 1.0 op_sel_hi:[1,0]
	v_pk_fma_f32 v[4:5], v[4:5], v[36:37], v[28:29]
	v_pk_fma_f32 v[2:3], v[2:3], v[26:27], v[48:49]
	v_and_b32_sdwa v21, v5, v177 dst_sel:DWORD dst_unused:UNUSED_PAD src0_sel:WORD_1 src1_sel:DWORD
	v_and_b32_sdwa v23, v4, v177 dst_sel:DWORD dst_unused:UNUSED_PAD src0_sel:WORD_1 src1_sel:DWORD
	v_and_b32_sdwa v7, v3, v177 dst_sel:DWORD dst_unused:UNUSED_PAD src0_sel:WORD_1 src1_sel:DWORD
	v_and_b32_sdwa v19, v2, v177 dst_sel:DWORD dst_unused:UNUSED_PAD src0_sel:WORD_1 src1_sel:DWORD
	v_add3_u32 v5, v5, v21, s28
	v_add3_u32 v4, v4, v23, s28
	v_add3_u32 v2, v2, v19, s28
	v_add3_u32 v3, v3, v7, s28
	v_and_b32_e32 v5, 0xffff0000, v5
	v_and_b32_e32 v4, 0xffff0000, v4
	v_or_b32_sdwa v3, v5, v3 dst_sel:DWORD dst_unused:UNUSED_PAD src0_sel:DWORD src1_sel:WORD_1
	v_or_b32_sdwa v2, v4, v2 dst_sel:DWORD dst_unused:UNUSED_PAD src0_sel:DWORD src1_sel:WORD_1
	global_store_dwordx2 v[24:25], v[2:3], off offset:1536
	s_nop 0
	v_lshl_add_u32 v6, s2, 3, v6
	v_cmp_le_i32_e32 vcc, s11, v6
	s_or_b64 s[18:19], vcc, s[18:19]
	s_andn2_b64 exec, exec, s[18:19]
	s_cbranch_execz .LBB0_1384

.LBB0_1441:
	s_bitcmp1_b32 s4, 0
	s_cselect_b32 s2, 0x12000, 0
	v_or_b32_e32 v218, s2, v206
	v_add_u32_e32 v214, v218, v0
	v_add_u32_e32 v246, v218, v167
	ds_read_b128 v[184:187], v214
	ds_read_b128 v[218:221], v246 offset:32768
	ds_read_b128 v[198:201], v214 offset:2048
	ds_read_b128 v[210:213], v214 offset:4096
	ds_read_b128 v[214:217], v214 offset:6144
	ds_read_b128 v[222:225], v246 offset:34816
	ds_read_b128 v[226:229], v246 offset:36864
	ds_read_b128 v[230:233], v246 offset:38912
	ds_read_b128 v[234:237], v246 offset:40960
	ds_read_b128 v[238:241], v246 offset:43008
	ds_read_b128 v[242:245], v246 offset:45056
	ds_read_b128 v[246:249], v246 offset:47104
	s_add_i32 s10, s4, 1
	s_bitcmp1_b32 s10, 0
	s_cselect_b32 s3, 0x12000, 0
	v_add_u32_e32 v171, s3, v166
	v_xor_b32_e32 v169, 64, v206
	v_add3_u32 v169, s2, v167, v169
	s_waitcnt lgkmcnt(10)
	v_mfma_f32_16x16x32_bf16 v[158:161], v[218:221], v[184:187], v[158:161]
	s_waitcnt lgkmcnt(9)
	v_mfma_f32_16x16x32_bf16 v[94:97], v[218:221], v[198:201], v[94:97]
	s_waitcnt lgkmcnt(8)
	v_mfma_f32_16x16x32_bf16 v[62:65], v[218:221], v[210:213], v[62:65]
	s_waitcnt lgkmcnt(7)
	v_mfma_f32_16x16x32_bf16 v[30:33], v[218:221], v[214:217], v[30:33]
	ds_read_b128 v[218:221], v169 offset:32768
	s_waitcnt lgkmcnt(7)
	v_mfma_f32_16x16x32_bf16 v[154:157], v[222:225], v[184:187], v[154:157]
	v_mfma_f32_16x16x32_bf16 v[90:93], v[222:225], v[198:201], v[90:93]
	v_mfma_f32_16x16x32_bf16 v[58:61], v[222:225], v[210:213], v[58:61]
	v_mfma_f32_16x16x32_bf16 v[26:29], v[222:225], v[214:217], v[26:29]
	ds_read_b128 v[222:225], v169 offset:34816
	s_waitcnt lgkmcnt(7)
	v_mfma_f32_16x16x32_bf16 v[150:153], v[226:229], v[184:187], v[150:153]
	v_mfma_f32_16x16x32_bf16 v[86:89], v[226:229], v[198:201], v[86:89]
	v_mfma_f32_16x16x32_bf16 v[54:57], v[226:229], v[210:213], v[54:57]
	v_mfma_f32_16x16x32_bf16 v[22:25], v[226:229], v[214:217], v[22:25]
	ds_read_b128 v[226:229], v169 offset:36864
	s_waitcnt lgkmcnt(7)
	v_mfma_f32_16x16x32_bf16 v[146:149], v[230:233], v[184:187], v[146:149]
	v_mfma_f32_16x16x32_bf16 v[82:85], v[230:233], v[198:201], v[82:85]
	v_mfma_f32_16x16x32_bf16 v[50:53], v[230:233], v[210:213], v[50:53]
	v_mfma_f32_16x16x32_bf16 v[18:21], v[230:233], v[214:217], v[18:21]
	ds_read_b128 v[230:233], v169 offset:38912
	s_waitcnt lgkmcnt(7)
	v_mfma_f32_16x16x32_bf16 v[142:145], v[234:237], v[184:187], v[142:145]
	v_mfma_f32_16x16x32_bf16 v[78:81], v[234:237], v[198:201], v[78:81]
	v_mfma_f32_16x16x32_bf16 v[46:49], v[234:237], v[210:213], v[46:49]
	v_mfma_f32_16x16x32_bf16 v[14:17], v[234:237], v[214:217], v[14:17]
	ds_read_b128 v[234:237], v169 offset:40960
	s_waitcnt lgkmcnt(7)
	v_mfma_f32_16x16x32_bf16 v[138:141], v[238:241], v[184:187], v[138:141]
	v_mfma_f32_16x16x32_bf16 v[74:77], v[238:241], v[198:201], v[74:77]
	v_mfma_f32_16x16x32_bf16 v[42:45], v[238:241], v[210:213], v[42:45]
	v_mfma_f32_16x16x32_bf16 v[10:13], v[238:241], v[214:217], v[10:13]
	ds_read_b128 v[238:241], v169 offset:43008
	s_waitcnt lgkmcnt(7)
	v_mfma_f32_16x16x32_bf16 v[102:105], v[242:245], v[184:187], v[102:105]
	v_mfma_f32_16x16x32_bf16 v[70:73], v[242:245], v[198:201], v[70:73]
	v_mfma_f32_16x16x32_bf16 v[38:41], v[242:245], v[210:213], v[38:41]
	v_mfma_f32_16x16x32_bf16 v[6:9], v[242:245], v[214:217], v[6:9]
	ds_read_b128 v[242:245], v169 offset:45056
	s_waitcnt lgkmcnt(7)
	v_mfma_f32_16x16x32_bf16 v[98:101], v[246:249], v[184:187], v[98:101]
	v_mfma_f32_16x16x32_bf16 v[66:69], v[246:249], v[198:201], v[66:69]
	v_xor_b32_e32 v169, 64, v206
	v_add3_u32 v169, s2, v0, v169
	ds_read_b128 v[184:187], v169
	ds_read_b128 v[198:201], v169 offset:2048
	v_mfma_f32_16x16x32_bf16 v[34:37], v[246:249], v[210:213], v[34:37]
	ds_read_b128 v[210:213], v169 offset:4096
	v_mfma_f32_16x16x32_bf16 v[2:5], v[246:249], v[214:217], v[2:5]
	ds_read_b128 v[214:217], v169 offset:6144
	v_xor_b32_e32 v169, 64, v206
	v_add3_u32 v169, s2, v167, v169
	ds_read_b128 v[246:249], v169 offset:47104
	s_waitcnt lgkmcnt(4)
	v_mfma_f32_16x16x32_bf16 v[158:161], v[218:221], v[184:187], v[158:161]
	s_waitcnt lgkmcnt(3)
	v_mfma_f32_16x16x32_bf16 v[94:97], v[218:221], v[198:201], v[94:97]
	s_waitcnt lgkmcnt(2)
	v_mfma_f32_16x16x32_bf16 v[62:65], v[218:221], v[210:213], v[62:65]
	s_waitcnt lgkmcnt(1)
	v_mfma_f32_16x16x32_bf16 v[30:33], v[218:221], v[214:217], v[30:33]
	s_waitcnt vmcnt(7)
	ds_write_b128 v171, v[114:117]
	v_mfma_f32_16x16x32_bf16 v[154:157], v[222:225], v[184:187], v[154:157]
	v_mfma_f32_16x16x32_bf16 v[90:93], v[222:225], v[198:201], v[90:93]
	global_load_dwordx4 v[114:117], v168, vcc offset:256
	v_mfma_f32_16x16x32_bf16 v[58:61], v[222:225], v[210:213], v[58:61]
	v_mfma_f32_16x16x32_bf16 v[26:29], v[222:225], v[214:217], v[26:29]
	s_waitcnt vmcnt(7)
	ds_write_b128 v171, v[106:109] offset:8192
	v_mfma_f32_16x16x32_bf16 v[150:153], v[226:229], v[184:187], v[150:153]
	v_mfma_f32_16x16x32_bf16 v[86:89], v[226:229], v[198:201], v[86:89]
	v_add_u32_e32 v106, s34, v168
	global_load_dwordx4 v[106:109], v106, vcc offset:256
	v_mfma_f32_16x16x32_bf16 v[54:57], v[226:229], v[210:213], v[54:57]
	v_mfma_f32_16x16x32_bf16 v[22:25], v[226:229], v[214:217], v[22:25]
	s_waitcnt vmcnt(7)
	ds_write_b128 v171, v[110:113] offset:16384
	v_mfma_f32_16x16x32_bf16 v[146:149], v[230:233], v[184:187], v[146:149]
	v_mfma_f32_16x16x32_bf16 v[82:85], v[230:233], v[198:201], v[82:85]
	v_add_u32_e32 v110, s35, v168
	global_load_dwordx4 v[110:113], v110, vcc offset:256
	v_mfma_f32_16x16x32_bf16 v[50:53], v[230:233], v[210:213], v[50:53]
	v_mfma_f32_16x16x32_bf16 v[18:21], v[230:233], v[214:217], v[18:21]
	s_waitcnt vmcnt(7)
	ds_write_b128 v171, v[126:129] offset:24576
	v_mfma_f32_16x16x32_bf16 v[142:145], v[234:237], v[184:187], v[142:145]
	v_mfma_f32_16x16x32_bf16 v[78:81], v[234:237], v[198:201], v[78:81]
	v_add_u32_e32 v126, s36, v168
	global_load_dwordx4 v[126:129], v126, vcc offset:256
	v_mfma_f32_16x16x32_bf16 v[46:49], v[234:237], v[210:213], v[46:49]
	v_mfma_f32_16x16x32_bf16 v[14:17], v[234:237], v[214:217], v[14:17]
	s_waitcnt vmcnt(7)
	ds_write_b128 v171, v[122:125] offset:32768
	v_mfma_f32_16x16x32_bf16 v[138:141], v[238:241], v[184:187], v[138:141]
	v_mfma_f32_16x16x32_bf16 v[74:77], v[238:241], v[198:201], v[74:77]
	global_load_dwordx4 v[122:125], v170, s[100:101] offset:256
	v_mfma_f32_16x16x32_bf16 v[42:45], v[238:241], v[210:213], v[42:45]
	v_mfma_f32_16x16x32_bf16 v[10:13], v[238:241], v[214:217], v[10:13]
	s_waitcnt vmcnt(7)
	ds_write_b128 v171, v[118:121] offset:40960
	v_mfma_f32_16x16x32_bf16 v[102:105], v[242:245], v[184:187], v[102:105]
	v_mfma_f32_16x16x32_bf16 v[70:73], v[242:245], v[198:201], v[70:73]
	v_add_u32_e32 v118, s34, v170
	global_load_dwordx4 v[118:121], v118, s[100:101] offset:256
	v_mfma_f32_16x16x32_bf16 v[38:41], v[242:245], v[210:213], v[38:41]
	v_mfma_f32_16x16x32_bf16 v[6:9], v[242:245], v[214:217], v[6:9]
	s_waitcnt vmcnt(7)
	ds_write_b128 v171, v[134:137] offset:49152
	s_waitcnt lgkmcnt(7)
	v_mfma_f32_16x16x32_bf16 v[98:101], v[246:249], v[184:187], v[98:101]
	v_mfma_f32_16x16x32_bf16 v[66:69], v[246:249], v[198:201], v[66:69]
	v_add_u32_e32 v134, s35, v170
	global_load_dwordx4 v[134:137], v134, s[100:101] offset:256
	v_mfma_f32_16x16x32_bf16 v[34:37], v[246:249], v[210:213], v[34:37]
	v_mfma_f32_16x16x32_bf16 v[2:5], v[246:249], v[214:217], v[2:5]
	s_waitcnt vmcnt(7)
	ds_write_b128 v171, v[130:133] offset:57344
	v_add_u32_e32 v130, s36, v170
	global_load_dwordx4 v[130:133], v130, s[100:101] offset:256
	v_add_u32_e32 v168, 0x80, v168
	v_add_u32_e32 v170, 0x80, v170
	s_waitcnt lgkmcnt(0)
	s_barrier
	s_cmp_eq_u32 s10, 16
	s_mov_b32 s4, s10
	s_cbranch_scc0 .LBB0_1441
	s_waitcnt vmcnt(4)
	v_mul_f32_e32 v109, 0xbfb8aa3b, v158
	v_exp_f32_e32 v109, v109
	s_waitcnt vmcnt(3)
	v_mul_f32_e32 v111, 0xbfb8aa3b, v159
	v_exp_f32_e32 v111, v111
	v_mul_f32_e32 v115, 0xbfb8aa3b, v161
	v_add_f32_e32 v109, 1.0, v109
	v_rcp_f32_e32 v114, v109
	v_add_f32_e32 v109, 1.0, v111
	v_mul_f32_e32 v111, 0xbfb8aa3b, v160
	v_exp_f32_e32 v111, v111
	v_exp_f32_e32 v117, v115
	v_rcp_f32_e32 v116, v109
	s_waitcnt vmcnt(2)
	v_mov_b32_e32 v118, v158
	v_add_f32_e32 v109, 1.0, v111
	v_rcp_f32_e32 v115, v109
	v_add_f32_e32 v109, 1.0, v117
	v_rcp_f32_e32 v117, v109
	v_mov_b32_e32 v119, v160
	v_pk_mul_f32 v[114:115], v[118:119], v[114:115]
	v_mov_b32_e32 v118, v154
	v_mov_b32_e32 v119, v156
	v_mov_b32_e32 v160, v159
	v_pk_mul_f32 v[114:115], v[118:119], v[114:115]
	v_pk_mul_f32 v[116:117], v[160:161], v[116:117]
	v_mov_b32_e32 v156, v155
	v_pk_mul_f32 v[116:117], v[156:157], v[116:117]
	v_cvt_pk_bf16_f32 v111, v115, v117
	v_cvt_pk_bf16_f32 v114, v114, v116
	v_or_b32_e32 v106, s7, v207
	v_ashrrev_i32_e32 v106, 1, v106
	v_mov_b32_e32 v115, v111
	v_mul_f32_e32 v111, 0xbfb8aa3b, v150
	v_or_b32_e32 v108, v106, v208
	v_exp_f32_e32 v111, v111
	v_mul_f32_e32 v116, 0xbfb8aa3b, v151
	v_add_u32_e32 v110, s6, v205
	v_mov_b64_e32 v[106:107], s[12:13]
	v_ashrrev_i32_e32 v109, 31, v108
	v_exp_f32_e32 v116, v116
	v_mad_i64_i32 v[112:113], s[6:7], v110, s52, v[106:107]
	v_lshlrev_b64 v[108:109], 1, v[108:109]
	v_lshl_add_u64 v[112:113], v[112:113], 0, v[108:109]
	s_waitcnt vmcnt(0)
	global_store_dwordx2 v[112:113], v[114:115], off
	v_add_f32_e32 v111, 1.0, v111
	v_mul_f32_e32 v115, 0xbfb8aa3b, v152
	v_rcp_f32_e32 v114, v111
	v_add_f32_e32 v111, 1.0, v116
	v_exp_f32_e32 v115, v115
	v_mul_f32_e32 v116, 0xbfb8aa3b, v153
	v_exp_f32_e32 v117, v116
	v_rcp_f32_e32 v116, v111
	v_add_f32_e32 v111, 1.0, v115
	v_rcp_f32_e32 v115, v111
	v_add_f32_e32 v111, 1.0, v117
	v_rcp_f32_e32 v117, v111
	v_mov_b32_e32 v118, v150
	v_mov_b32_e32 v119, v152
	v_pk_mul_f32 v[114:115], v[118:119], v[114:115]
	v_mov_b32_e32 v118, v146
	v_mov_b32_e32 v119, v148
	v_mov_b32_e32 v152, v151
	v_pk_mul_f32 v[114:115], v[118:119], v[114:115]
	v_pk_mul_f32 v[116:117], v[152:153], v[116:117]
	v_mov_b32_e32 v148, v147
	v_pk_mul_f32 v[116:117], v[148:149], v[116:117]
	v_cvt_pk_bf16_f32 v111, v115, v117
	v_cvt_pk_bf16_f32 v114, v114, v116
	v_mov_b32_e32 v115, v111
	v_mul_f32_e32 v111, 0xbfb8aa3b, v142
	v_exp_f32_e32 v111, v111
	v_mul_f32_e32 v116, 0xbfb8aa3b, v143
	v_exp_f32_e32 v116, v116
	global_store_dwordx2 v[112:113], v[114:115], off offset:32
	v_add_f32_e32 v111, 1.0, v111
	v_mul_f32_e32 v115, 0xbfb8aa3b, v144
	v_rcp_f32_e32 v114, v111
	v_add_f32_e32 v111, 1.0, v116
	v_exp_f32_e32 v115, v115
	v_mul_f32_e32 v116, 0xbfb8aa3b, v145
	v_exp_f32_e32 v117, v116
	v_rcp_f32_e32 v116, v111
	v_add_f32_e32 v111, 1.0, v115
	v_rcp_f32_e32 v115, v111
	v_add_f32_e32 v111, 1.0, v117
	v_rcp_f32_e32 v117, v111
	v_mov_b32_e32 v118, v142
	v_mov_b32_e32 v119, v144
	v_pk_mul_f32 v[114:115], v[118:119], v[114:115]
	v_mov_b32_e32 v118, v138
	v_mov_b32_e32 v119, v140
	v_mov_b32_e32 v144, v143
	v_pk_mul_f32 v[114:115], v[118:119], v[114:115]
	v_pk_mul_f32 v[116:117], v[144:145], v[116:117]
	v_mov_b32_e32 v140, v139
	v_pk_mul_f32 v[116:117], v[140:141], v[116:117]
	v_cvt_pk_bf16_f32 v111, v115, v117
	v_cvt_pk_bf16_f32 v114, v114, v116
	v_mov_b32_e32 v115, v111
	v_mul_f32_e32 v111, 0xbfb8aa3b, v102
	v_exp_f32_e32 v111, v111
	v_mul_f32_e32 v116, 0xbfb8aa3b, v103
	v_exp_f32_e32 v116, v116
	global_store_dwordx2 v[112:113], v[114:115], off offset:64
	v_add_f32_e32 v111, 1.0, v111
	v_mul_f32_e32 v115, 0xbfb8aa3b, v104
	v_rcp_f32_e32 v114, v111
	v_add_f32_e32 v111, 1.0, v116
	v_exp_f32_e32 v115, v115
	v_mul_f32_e32 v116, 0xbfb8aa3b, v105
	v_exp_f32_e32 v117, v116
	v_rcp_f32_e32 v116, v111
	v_add_f32_e32 v111, 1.0, v115
	v_rcp_f32_e32 v115, v111
	v_add_f32_e32 v111, 1.0, v117
	v_rcp_f32_e32 v117, v111
	v_mov_b32_e32 v118, v102
	v_mov_b32_e32 v119, v104
	v_mov_b32_e32 v104, v103
	v_pk_mul_f32 v[114:115], v[118:119], v[114:115]
	v_mov_b32_e32 v119, v100
	v_pk_mul_f32 v[102:103], v[104:105], v[116:117]
	v_mov_b32_e32 v100, v99
	v_mov_b32_e32 v118, v98
	v_pk_mul_f32 v[98:99], v[100:101], v[102:103]
	v_pk_mul_f32 v[114:115], v[118:119], v[114:115]
	v_cvt_pk_bf16_f32 v100, v115, v99
	v_cvt_pk_bf16_f32 v101, v114, v98
	v_mov_b32_e32 v99, v100
	v_mov_b32_e32 v98, v101
	global_store_dwordx2 v[112:113], v[98:99], off offset:96
	v_mul_f32_e32 v99, 0xbfb8aa3b, v94
	v_exp_f32_e32 v100, v99
	v_mul_f32_e32 v99, 0xbfb8aa3b, v95
	v_mul_f32_e32 v102, 0xbfb8aa3b, v96
	v_exp_f32_e32 v101, v99
	v_exp_f32_e32 v103, v102
	v_mul_f32_e32 v102, 0xbfb8aa3b, v97
	v_exp_f32_e32 v104, v102
	v_add_f32_e32 v101, 1.0, v101
	v_add_f32_e32 v100, 1.0, v100
	v_rcp_f32_e32 v102, v101
	v_add_f32_e32 v101, 1.0, v103
	v_add_f32_e32 v103, 1.0, v104
	v_rcp_f32_e32 v100, v100
	v_rcp_f32_e32 v101, v101
	v_rcp_f32_e32 v103, v103
	v_mov_b32_e32 v104, v94
	v_mov_b32_e32 v105, v96
	v_mov_b32_e32 v96, v95
	v_pk_mul_f32 v[100:101], v[104:105], v[100:101]
	v_mov_b32_e32 v105, v92
	v_pk_mul_f32 v[94:95], v[96:97], v[102:103]
	v_mov_b32_e32 v92, v91
	v_mov_b32_e32 v104, v90
	v_pk_mul_f32 v[90:91], v[92:93], v[94:95]
	v_pk_mul_f32 v[100:101], v[104:105], v[100:101]
	v_cvt_pk_bf16_f32 v92, v101, v91
	v_cvt_pk_bf16_f32 v93, v100, v90
	v_mov_b32_e32 v91, v92
	v_mul_f32_e32 v92, 0xbfb8aa3b, v86
	v_mov_b32_e32 v90, v93
	v_exp_f32_e32 v92, v92
	v_mul_f32_e32 v93, 0xbfb8aa3b, v87
	v_or_b32_e32 v98, 16, v110
	v_exp_f32_e32 v93, v93
	v_mad_i64_i32 v[98:99], s[6:7], v98, s52, v[106:107]
	v_lshl_add_u64 v[98:99], v[98:99], 0, v[108:109]
	global_store_dwordx2 v[98:99], v[90:91], off
	v_add_f32_e32 v90, 1.0, v92
	v_mul_f32_e32 v92, 0xbfb8aa3b, v88
	v_add_f32_e32 v91, 1.0, v93
	v_exp_f32_e32 v93, v92
	v_mul_f32_e32 v92, 0xbfb8aa3b, v89
	v_exp_f32_e32 v94, v92
	v_rcp_f32_e32 v92, v91
	v_add_f32_e32 v91, 1.0, v93
	v_rcp_f32_e32 v90, v90
	v_add_f32_e32 v93, 1.0, v94
	v_rcp_f32_e32 v91, v91
	v_rcp_f32_e32 v93, v93
	v_mov_b32_e32 v94, v86
	v_mov_b32_e32 v95, v88
	v_mov_b32_e32 v88, v87
	v_pk_mul_f32 v[90:91], v[94:95], v[90:91]
	v_mov_b32_e32 v95, v84
	v_pk_mul_f32 v[86:87], v[88:89], v[92:93]
	v_mov_b32_e32 v84, v83
	v_mov_b32_e32 v94, v82
	v_pk_mul_f32 v[82:83], v[84:85], v[86:87]
	v_pk_mul_f32 v[90:91], v[94:95], v[90:91]
	v_cvt_pk_bf16_f32 v84, v91, v83
	v_cvt_pk_bf16_f32 v85, v90, v82
	v_mov_b32_e32 v83, v84
	v_mul_f32_e32 v84, 0xbfb8aa3b, v78
	v_mov_b32_e32 v82, v85
	v_exp_f32_e32 v84, v84
	v_mul_f32_e32 v85, 0xbfb8aa3b, v79
	v_exp_f32_e32 v85, v85
	global_store_dwordx2 v[98:99], v[82:83], off offset:32
	v_add_f32_e32 v82, 1.0, v84
	v_mul_f32_e32 v84, 0xbfb8aa3b, v80
	v_add_f32_e32 v83, 1.0, v85
	v_exp_f32_e32 v85, v84
	v_mul_f32_e32 v84, 0xbfb8aa3b, v81
	v_exp_f32_e32 v86, v84
	v_rcp_f32_e32 v84, v83
	v_add_f32_e32 v83, 1.0, v85
	v_rcp_f32_e32 v82, v82
	v_add_f32_e32 v85, 1.0, v86
	v_rcp_f32_e32 v83, v83
	v_rcp_f32_e32 v85, v85
	v_mov_b32_e32 v86, v78
	v_mov_b32_e32 v87, v80
	v_mov_b32_e32 v80, v79
	v_pk_mul_f32 v[82:83], v[86:87], v[82:83]
	v_mov_b32_e32 v87, v76
	v_pk_mul_f32 v[78:79], v[80:81], v[84:85]
	v_mov_b32_e32 v76, v75
	v_mov_b32_e32 v86, v74
	v_pk_mul_f32 v[74:75], v[76:77], v[78:79]
	v_pk_mul_f32 v[82:83], v[86:87], v[82:83]
	v_cvt_pk_bf16_f32 v76, v83, v75
	v_cvt_pk_bf16_f32 v77, v82, v74
	v_mov_b32_e32 v75, v76
	v_mul_f32_e32 v76, 0xbfb8aa3b, v70
	v_mov_b32_e32 v74, v77
	v_exp_f32_e32 v76, v76
	v_mul_f32_e32 v77, 0xbfb8aa3b, v71
	v_exp_f32_e32 v77, v77
	global_store_dwordx2 v[98:99], v[74:75], off offset:64
	v_add_f32_e32 v74, 1.0, v76
	v_mul_f32_e32 v76, 0xbfb8aa3b, v72
	v_add_f32_e32 v75, 1.0, v77
	v_exp_f32_e32 v77, v76
	v_mul_f32_e32 v76, 0xbfb8aa3b, v73
	v_exp_f32_e32 v78, v76
	v_rcp_f32_e32 v76, v75
	v_add_f32_e32 v75, 1.0, v77
	v_rcp_f32_e32 v74, v74
	v_add_f32_e32 v77, 1.0, v78
	v_rcp_f32_e32 v75, v75
	v_rcp_f32_e32 v77, v77
	v_mov_b32_e32 v78, v70
	v_mov_b32_e32 v79, v72
	v_mov_b32_e32 v72, v71
	v_pk_mul_f32 v[74:75], v[78:79], v[74:75]
	v_mov_b32_e32 v79, v68
	v_pk_mul_f32 v[70:71], v[72:73], v[76:77]
	v_mov_b32_e32 v68, v67
	v_mov_b32_e32 v78, v66
	v_pk_mul_f32 v[66:67], v[68:69], v[70:71]
	v_pk_mul_f32 v[74:75], v[78:79], v[74:75]
	v_cvt_pk_bf16_f32 v68, v75, v67
	v_cvt_pk_bf16_f32 v69, v74, v66
	v_mov_b32_e32 v67, v68
	v_mov_b32_e32 v66, v69
	global_store_dwordx2 v[98:99], v[66:67], off offset:96
	v_mul_f32_e32 v67, 0xbfb8aa3b, v62
	v_exp_f32_e32 v68, v67
	v_mul_f32_e32 v67, 0xbfb8aa3b, v63
	v_mul_f32_e32 v70, 0xbfb8aa3b, v64
	v_exp_f32_e32 v69, v67
	v_exp_f32_e32 v71, v70
	v_mul_f32_e32 v70, 0xbfb8aa3b, v65
	v_exp_f32_e32 v72, v70
	v_add_f32_e32 v69, 1.0, v69
	v_add_f32_e32 v68, 1.0, v68
	v_rcp_f32_e32 v70, v69
	v_add_f32_e32 v69, 1.0, v71
	v_add_f32_e32 v71, 1.0, v72
	v_rcp_f32_e32 v68, v68
	v_rcp_f32_e32 v69, v69
	v_rcp_f32_e32 v71, v71
	v_mov_b32_e32 v72, v62
	v_mov_b32_e32 v73, v64
	v_mov_b32_e32 v64, v63
	v_pk_mul_f32 v[68:69], v[72:73], v[68:69]
	v_mov_b32_e32 v73, v60
	v_pk_mul_f32 v[62:63], v[64:65], v[70:71]
	v_mov_b32_e32 v60, v59
	v_mov_b32_e32 v72, v58
	v_pk_mul_f32 v[58:59], v[60:61], v[62:63]
	v_pk_mul_f32 v[68:69], v[72:73], v[68:69]
	v_cvt_pk_bf16_f32 v60, v69, v59
	v_cvt_pk_bf16_f32 v61, v68, v58
	v_mov_b32_e32 v59, v60
	v_mul_f32_e32 v60, 0xbfb8aa3b, v54
	v_mov_b32_e32 v58, v61
	v_exp_f32_e32 v60, v60
	v_mul_f32_e32 v61, 0xbfb8aa3b, v55
	v_or_b32_e32 v66, 32, v110
	v_exp_f32_e32 v61, v61
	v_mad_i64_i32 v[66:67], s[6:7], v66, s52, v[106:107]
	v_lshl_add_u64 v[66:67], v[66:67], 0, v[108:109]
	global_store_dwordx2 v[66:67], v[58:59], off
	v_add_f32_e32 v58, 1.0, v60
	v_mul_f32_e32 v60, 0xbfb8aa3b, v56
	v_add_f32_e32 v59, 1.0, v61
	v_exp_f32_e32 v61, v60
	v_mul_f32_e32 v60, 0xbfb8aa3b, v57
	v_exp_f32_e32 v62, v60
	v_rcp_f32_e32 v60, v59
	v_add_f32_e32 v59, 1.0, v61
	v_rcp_f32_e32 v58, v58
	v_add_f32_e32 v61, 1.0, v62
	v_rcp_f32_e32 v59, v59
	v_rcp_f32_e32 v61, v61
	v_mov_b32_e32 v62, v54
	v_mov_b32_e32 v63, v56
	v_mov_b32_e32 v56, v55
	v_pk_mul_f32 v[58:59], v[62:63], v[58:59]
	v_mov_b32_e32 v63, v52
	v_pk_mul_f32 v[54:55], v[56:57], v[60:61]
	v_mov_b32_e32 v52, v51
	v_mov_b32_e32 v62, v50
	v_pk_mul_f32 v[50:51], v[52:53], v[54:55]
	v_pk_mul_f32 v[58:59], v[62:63], v[58:59]
	v_cvt_pk_bf16_f32 v52, v59, v51
	v_cvt_pk_bf16_f32 v53, v58, v50
	v_mov_b32_e32 v51, v52
	v_mul_f32_e32 v52, 0xbfb8aa3b, v46
	v_mov_b32_e32 v50, v53
	v_exp_f32_e32 v52, v52
	v_mul_f32_e32 v53, 0xbfb8aa3b, v47
	v_exp_f32_e32 v53, v53
	global_store_dwordx2 v[66:67], v[50:51], off offset:32
	v_add_f32_e32 v50, 1.0, v52
	v_mul_f32_e32 v52, 0xbfb8aa3b, v48
	v_add_f32_e32 v51, 1.0, v53
	v_exp_f32_e32 v53, v52
	v_mul_f32_e32 v52, 0xbfb8aa3b, v49
	v_exp_f32_e32 v54, v52
	v_rcp_f32_e32 v52, v51
	v_add_f32_e32 v51, 1.0, v53
	v_rcp_f32_e32 v50, v50
	v_add_f32_e32 v53, 1.0, v54
	v_rcp_f32_e32 v51, v51
	v_rcp_f32_e32 v53, v53
	v_mov_b32_e32 v54, v46
	v_mov_b32_e32 v55, v48
	v_mov_b32_e32 v48, v47
	v_pk_mul_f32 v[50:51], v[54:55], v[50:51]
	v_mov_b32_e32 v55, v44
	v_pk_mul_f32 v[46:47], v[48:49], v[52:53]
	v_mov_b32_e32 v44, v43
	v_mov_b32_e32 v54, v42
	v_pk_mul_f32 v[42:43], v[44:45], v[46:47]
	v_pk_mul_f32 v[50:51], v[54:55], v[50:51]
	v_cvt_pk_bf16_f32 v44, v51, v43
	v_cvt_pk_bf16_f32 v45, v50, v42
	v_mov_b32_e32 v43, v44
	v_mul_f32_e32 v44, 0xbfb8aa3b, v38
	v_mov_b32_e32 v42, v45
	v_exp_f32_e32 v44, v44
	v_mul_f32_e32 v45, 0xbfb8aa3b, v39
	v_exp_f32_e32 v45, v45
	global_store_dwordx2 v[66:67], v[42:43], off offset:64
	v_add_f32_e32 v42, 1.0, v44
	v_mul_f32_e32 v44, 0xbfb8aa3b, v40
	v_add_f32_e32 v43, 1.0, v45
	v_exp_f32_e32 v45, v44
	v_mul_f32_e32 v44, 0xbfb8aa3b, v41
	v_exp_f32_e32 v46, v44
	v_rcp_f32_e32 v44, v43
	v_add_f32_e32 v43, 1.0, v45
	v_rcp_f32_e32 v42, v42
	v_add_f32_e32 v45, 1.0, v46
	v_rcp_f32_e32 v43, v43
	v_rcp_f32_e32 v45, v45
	v_mov_b32_e32 v46, v38
	v_mov_b32_e32 v47, v40
	v_mov_b32_e32 v40, v39
	v_pk_mul_f32 v[42:43], v[46:47], v[42:43]
	v_mov_b32_e32 v47, v36
	v_pk_mul_f32 v[38:39], v[40:41], v[44:45]
	v_mov_b32_e32 v36, v35
	v_mov_b32_e32 v46, v34
	v_pk_mul_f32 v[34:35], v[36:37], v[38:39]
	v_pk_mul_f32 v[42:43], v[46:47], v[42:43]
	v_cvt_pk_bf16_f32 v36, v43, v35
	v_cvt_pk_bf16_f32 v37, v42, v34
	v_mov_b32_e32 v35, v36
	v_mov_b32_e32 v34, v37
	global_store_dwordx2 v[66:67], v[34:35], off offset:96
	v_mul_f32_e32 v35, 0xbfb8aa3b, v30
	v_exp_f32_e32 v36, v35
	v_mul_f32_e32 v35, 0xbfb8aa3b, v31
	v_mul_f32_e32 v38, 0xbfb8aa3b, v32
	v_exp_f32_e32 v37, v35
	v_exp_f32_e32 v39, v38
	v_mul_f32_e32 v38, 0xbfb8aa3b, v33
	v_exp_f32_e32 v40, v38
	v_add_f32_e32 v37, 1.0, v37
	v_add_f32_e32 v36, 1.0, v36
	v_rcp_f32_e32 v38, v37
	v_add_f32_e32 v37, 1.0, v39
	v_add_f32_e32 v39, 1.0, v40
	v_rcp_f32_e32 v36, v36
	v_rcp_f32_e32 v37, v37
	v_rcp_f32_e32 v39, v39
	v_mov_b32_e32 v40, v30
	v_mov_b32_e32 v41, v32
	v_mov_b32_e32 v32, v31
	v_pk_mul_f32 v[36:37], v[40:41], v[36:37]
	v_mov_b32_e32 v41, v28
	v_pk_mul_f32 v[30:31], v[32:33], v[38:39]
	v_mov_b32_e32 v28, v27
	v_mov_b32_e32 v40, v26
	v_pk_mul_f32 v[26:27], v[28:29], v[30:31]
	v_pk_mul_f32 v[36:37], v[40:41], v[36:37]
	v_cvt_pk_bf16_f32 v28, v37, v27
	v_cvt_pk_bf16_f32 v29, v36, v26
	v_mov_b32_e32 v27, v28
	v_mul_f32_e32 v28, 0xbfb8aa3b, v22
	v_mov_b32_e32 v26, v29
	v_exp_f32_e32 v28, v28
	v_mul_f32_e32 v29, 0xbfb8aa3b, v23
	v_or_b32_e32 v34, 48, v110
	v_exp_f32_e32 v29, v29
	v_mad_i64_i32 v[34:35], s[6:7], v34, s52, v[106:107]
	v_lshl_add_u64 v[34:35], v[34:35], 0, v[108:109]
	global_store_dwordx2 v[34:35], v[26:27], off
	v_add_f32_e32 v26, 1.0, v28
	v_mul_f32_e32 v28, 0xbfb8aa3b, v24
	v_add_f32_e32 v27, 1.0, v29
	v_exp_f32_e32 v29, v28
	v_mul_f32_e32 v28, 0xbfb8aa3b, v25
	v_exp_f32_e32 v30, v28
	v_rcp_f32_e32 v28, v27
	v_add_f32_e32 v27, 1.0, v29
	v_rcp_f32_e32 v26, v26
	v_add_f32_e32 v29, 1.0, v30
	v_rcp_f32_e32 v27, v27
	v_rcp_f32_e32 v29, v29
	v_mov_b32_e32 v30, v22
	v_mov_b32_e32 v31, v24
	v_mov_b32_e32 v24, v23
	v_pk_mul_f32 v[26:27], v[30:31], v[26:27]
	v_mov_b32_e32 v31, v20
	v_pk_mul_f32 v[22:23], v[24:25], v[28:29]
	v_mov_b32_e32 v20, v19
	v_mov_b32_e32 v30, v18
	v_pk_mul_f32 v[18:19], v[20:21], v[22:23]
	v_pk_mul_f32 v[26:27], v[30:31], v[26:27]
	v_cvt_pk_bf16_f32 v20, v27, v19
	v_cvt_pk_bf16_f32 v21, v26, v18
	v_mov_b32_e32 v19, v20
	v_mul_f32_e32 v20, 0xbfb8aa3b, v14
	v_mov_b32_e32 v18, v21
	v_exp_f32_e32 v20, v20
	v_mul_f32_e32 v21, 0xbfb8aa3b, v15
	v_exp_f32_e32 v21, v21
	global_store_dwordx2 v[34:35], v[18:19], off offset:32
	v_add_f32_e32 v18, 1.0, v20
	v_mul_f32_e32 v20, 0xbfb8aa3b, v16
	v_add_f32_e32 v19, 1.0, v21
	v_exp_f32_e32 v21, v20
	v_mul_f32_e32 v20, 0xbfb8aa3b, v17
	v_exp_f32_e32 v22, v20
	v_rcp_f32_e32 v20, v19
	v_add_f32_e32 v19, 1.0, v21
	v_rcp_f32_e32 v18, v18
	v_add_f32_e32 v21, 1.0, v22
	v_rcp_f32_e32 v19, v19
	v_rcp_f32_e32 v21, v21
	v_mov_b32_e32 v22, v14
	v_mov_b32_e32 v23, v16
	v_mov_b32_e32 v16, v15
	v_pk_mul_f32 v[18:19], v[22:23], v[18:19]
	v_mov_b32_e32 v23, v12
	v_pk_mul_f32 v[14:15], v[16:17], v[20:21]
	v_mov_b32_e32 v12, v11
	v_mov_b32_e32 v22, v10
	v_pk_mul_f32 v[10:11], v[12:13], v[14:15]
	v_pk_mul_f32 v[18:19], v[22:23], v[18:19]
	v_cvt_pk_bf16_f32 v12, v19, v11
	v_cvt_pk_bf16_f32 v13, v18, v10
	v_mov_b32_e32 v11, v12
	v_mul_f32_e32 v12, 0xbfb8aa3b, v6
	v_mov_b32_e32 v10, v13
	v_exp_f32_e32 v12, v12
	v_mul_f32_e32 v13, 0xbfb8aa3b, v7
	v_exp_f32_e32 v13, v13
	global_store_dwordx2 v[34:35], v[10:11], off offset:64
	v_add_f32_e32 v10, 1.0, v12
	v_mul_f32_e32 v12, 0xbfb8aa3b, v8
	v_add_f32_e32 v11, 1.0, v13
	v_exp_f32_e32 v13, v12
	v_mul_f32_e32 v12, 0xbfb8aa3b, v9
	v_exp_f32_e32 v14, v12
	v_rcp_f32_e32 v12, v11
	v_add_f32_e32 v11, 1.0, v13
	v_rcp_f32_e32 v10, v10
	v_add_f32_e32 v13, 1.0, v14
	v_rcp_f32_e32 v11, v11
	v_rcp_f32_e32 v13, v13
	v_mov_b32_e32 v14, v6
	v_mov_b32_e32 v15, v8
	v_mov_b32_e32 v8, v7
	v_pk_mul_f32 v[10:11], v[14:15], v[10:11]
	v_mov_b32_e32 v15, v4
	v_pk_mul_f32 v[6:7], v[8:9], v[12:13]
	v_mov_b32_e32 v4, v3
	v_mov_b32_e32 v14, v2
	v_pk_mul_f32 v[2:3], v[4:5], v[6:7]
	v_pk_mul_f32 v[10:11], v[14:15], v[10:11]
	v_cvt_pk_bf16_f32 v4, v11, v3
	v_cvt_pk_bf16_f32 v5, v10, v2
	s_add_i32 s14, s14, s11
	v_mov_b32_e32 v3, v4
	v_mov_b32_e32 v2, v5
	s_cmpk_gt_i32 s14, 0x4ff
	global_store_dwordx2 v[34:35], v[2:3], off offset:96
	s_cbranch_scc0 .LBB0_1440

.LBB0_1455:
	s_add_i32 s2, s16, 4
	s_min_u32 s2, s2, 15
	s_lshl_b32 s4, s2, 7
	v_lshl_add_u64 v[98:99], v[110:111], 0, s[4:5]
	v_add_co_u32_e32 v94, vcc, s34, v98
	v_lshl_add_u64 v[132:133], v[112:113], 0, s[4:5]
	s_nop 0
	v_addc_co_u32_e32 v95, vcc, 0, v99, vcc
	v_add_co_u32_e32 v100, vcc, s35, v98
	global_load_dwordx4 v[90:93], v[98:99], off
	s_nop 0
	v_addc_co_u32_e32 v101, vcc, 0, v99, vcc
	v_add_co_u32_e32 v102, vcc, s36, v98
	global_load_dwordx4 v[94:97], v[94:95], off
	s_nop 0
	v_addc_co_u32_e32 v103, vcc, 0, v99, vcc
	v_add_co_u32_e32 v136, vcc, s34, v132
	global_load_dwordx4 v[98:101], v[100:101], off
	s_nop 0
	v_addc_co_u32_e32 v137, vcc, 0, v133, vcc
	global_load_dwordx4 v[102:105], v[102:103], off
	v_add_u32_e32 v131, v117, v120
	global_load_dwordx4 v[132:135], v[132:133], off
	ds_read_b128 v[140:143], v121
	global_load_dwordx4 v[136:139], v[136:137], off
	ds_read_b128 v[144:147], v121 offset:2304
	ds_read_b128 v[148:151], v121 offset:4608
	ds_read_b128 v[152:155], v121 offset:6912
	ds_read_b128 v[156:159], v131 offset:36864
	ds_read_b128 v[160:163], v131 offset:39168
	ds_read_b128 v[164:167], v131 offset:41472
	ds_read_b128 v[168:171], v131 offset:43776
	s_add_i32 s16, s16, 2
	s_waitcnt lgkmcnt(3)
	v_mfma_f32_16x16x32_bf16 v[82:85], v[156:159], v[140:143], v[82:85]
	s_waitcnt lgkmcnt(2)
	v_mfma_f32_16x16x32_bf16 v[86:89], v[160:163], v[140:143], v[86:89]
	ds_read_b128 v[184:187], v121 offset:64
	s_waitcnt lgkmcnt(2)
	v_mfma_f32_16x16x32_bf16 v[74:77], v[164:167], v[140:143], v[74:77]
	s_waitcnt lgkmcnt(1)
	v_mfma_f32_16x16x32_bf16 v[78:81], v[168:171], v[140:143], v[78:81]
	ds_read_b128 v[140:143], v121 offset:2368
	v_mfma_f32_16x16x32_bf16 v[66:69], v[156:159], v[144:147], v[66:69]
	v_mfma_f32_16x16x32_bf16 v[70:73], v[160:163], v[144:147], v[70:73]
	ds_read_b128 v[198:201], v121 offset:4672
	v_mfma_f32_16x16x32_bf16 v[34:37], v[164:167], v[144:147], v[34:37]
	v_mfma_f32_16x16x32_bf16 v[38:41], v[168:171], v[144:147], v[38:41]
	ds_read_b128 v[144:147], v121 offset:6976
	v_mfma_f32_16x16x32_bf16 v[26:29], v[156:159], v[148:151], v[26:29]
	v_mfma_f32_16x16x32_bf16 v[30:33], v[160:163], v[148:151], v[30:33]
	ds_read_b128 v[204:207], v131 offset:36928
	v_mfma_f32_16x16x32_bf16 v[18:21], v[164:167], v[148:151], v[18:21]
	v_mfma_f32_16x16x32_bf16 v[22:25], v[168:171], v[148:151], v[22:25]
	ds_read_b128 v[148:151], v131 offset:39232
	v_mfma_f32_16x16x32_bf16 v[10:13], v[156:159], v[152:155], v[10:13]
	v_mfma_f32_16x16x32_bf16 v[14:17], v[160:163], v[152:155], v[14:17]
	ds_read_b128 v[156:159], v131 offset:41536
	v_mfma_f32_16x16x32_bf16 v[2:5], v[164:167], v[152:155], v[2:5]
	v_mfma_f32_16x16x32_bf16 v[6:9], v[168:171], v[152:155], v[6:9]
	ds_read_b128 v[152:155], v131 offset:43840
	s_waitcnt lgkmcnt(3)
	v_mfma_f32_16x16x32_bf16 v[82:85], v[204:207], v[184:187], v[82:85]
	s_waitcnt lgkmcnt(2)
	v_mfma_f32_16x16x32_bf16 v[86:89], v[148:151], v[184:187], v[86:89]
	s_waitcnt vmcnt(11)
	ds_write_b128 v130, v[42:45] offset:55296
	s_waitcnt lgkmcnt(2)
	v_mfma_f32_16x16x32_bf16 v[74:77], v[156:159], v[184:187], v[74:77]
	s_waitcnt lgkmcnt(1)
	v_mfma_f32_16x16x32_bf16 v[78:81], v[152:155], v[184:187], v[78:81]
	s_waitcnt vmcnt(9)
	ds_write_b128 v130, v[46:49] offset:64512
	v_mfma_f32_16x16x32_bf16 v[66:69], v[204:207], v[140:143], v[66:69]
	v_mfma_f32_16x16x32_bf16 v[70:73], v[148:151], v[140:143], v[70:73]
	s_waitcnt vmcnt(8)
	ds_write_b128 v122, v[50:53] offset:55296
	v_mfma_f32_16x16x32_bf16 v[34:37], v[156:159], v[140:143], v[34:37]
	v_mfma_f32_16x16x32_bf16 v[38:41], v[152:155], v[140:143], v[38:41]
	s_waitcnt vmcnt(7)
	ds_write_b128 v123, v[54:57] offset:55296
	v_mfma_f32_16x16x32_bf16 v[26:29], v[204:207], v[198:201], v[26:29]
	v_mfma_f32_16x16x32_bf16 v[30:33], v[148:151], v[198:201], v[30:33]
	ds_write_b128 v124, v[58:61]
	v_mfma_f32_16x16x32_bf16 v[18:21], v[156:159], v[198:201], v[18:21]
	v_mfma_f32_16x16x32_bf16 v[22:25], v[152:155], v[198:201], v[22:25]
	s_waitcnt vmcnt(6)
	ds_write_b128 v124, v[62:65] offset:9216
	v_mfma_f32_16x16x32_bf16 v[10:13], v[204:207], v[144:147], v[10:13]
	v_mfma_f32_16x16x32_bf16 v[14:17], v[148:151], v[144:147], v[14:17]
	v_mfma_f32_16x16x32_bf16 v[2:5], v[156:159], v[144:147], v[2:5]
	v_mfma_f32_16x16x32_bf16 v[6:9], v[152:155], v[144:147], v[6:9]
	s_min_u32 s2, s16, 12
	s_lshl_b32 s4, s2, 7
	v_lshl_add_u64 v[50:51], v[110:111], 0, s[4:5]
	v_add_co_u32_e32 v46, vcc, s34, v50
	v_lshl_add_u64 v[58:59], v[112:113], 0, s[4:5]
	s_nop 0
	v_addc_co_u32_e32 v47, vcc, 0, v51, vcc
	v_add_co_u32_e32 v52, vcc, s35, v50
	s_waitcnt lgkmcnt(0)
	s_barrier
	global_load_dwordx4 v[42:45], v[50:51], off offset:384
	s_nop 0
	v_addc_co_u32_e32 v53, vcc, 0, v51, vcc
	v_add_co_u32_e32 v54, vcc, s36, v50
	global_load_dwordx4 v[46:49], v[46:47], off offset:384
	s_nop 0
	v_addc_co_u32_e32 v55, vcc, 0, v51, vcc
	v_add_co_u32_e32 v62, vcc, s34, v58
	global_load_dwordx4 v[50:53], v[52:53], off offset:384
	s_nop 0
	v_addc_co_u32_e32 v63, vcc, 0, v59, vcc
	global_load_dwordx4 v[54:57], v[54:55], off offset:384
	ds_read_b128 v[140:143], v121 offset:55296
	global_load_dwordx4 v[58:61], v[58:59], off offset:384
	ds_read_b128 v[144:147], v121 offset:57600
	global_load_dwordx4 v[62:65], v[62:63], off offset:384
	ds_read_b128 v[148:151], v121 offset:59904
	ds_read_b128 v[152:155], v121 offset:62208
	ds_read_b128 v[156:159], v125
	ds_read_b128 v[160:163], v125 offset:2304
	ds_read_b128 v[164:167], v125 offset:4608
	ds_read_b128 v[168:171], v125 offset:6912
	s_waitcnt lgkmcnt(3)
	v_mfma_f32_16x16x32_bf16 v[82:85], v[156:159], v[140:143], v[82:85]
	s_waitcnt lgkmcnt(2)
	v_mfma_f32_16x16x32_bf16 v[86:89], v[160:163], v[140:143], v[86:89]
	ds_read_b128 v[184:187], v121 offset:55360
	s_waitcnt lgkmcnt(2)
	v_mfma_f32_16x16x32_bf16 v[74:77], v[164:167], v[140:143], v[74:77]
	s_waitcnt lgkmcnt(1)
	v_mfma_f32_16x16x32_bf16 v[78:81], v[168:171], v[140:143], v[78:81]
	ds_read_b128 v[140:143], v121 offset:57664
	v_mfma_f32_16x16x32_bf16 v[66:69], v[156:159], v[144:147], v[66:69]
	v_mfma_f32_16x16x32_bf16 v[70:73], v[160:163], v[144:147], v[70:73]
	ds_read_b128 v[198:201], v121 offset:59968
	v_mfma_f32_16x16x32_bf16 v[34:37], v[164:167], v[144:147], v[34:37]
	v_mfma_f32_16x16x32_bf16 v[38:41], v[168:171], v[144:147], v[38:41]
	ds_read_b128 v[144:147], v121 offset:62272
	v_mfma_f32_16x16x32_bf16 v[26:29], v[156:159], v[148:151], v[26:29]
	v_mfma_f32_16x16x32_bf16 v[30:33], v[160:163], v[148:151], v[30:33]
	ds_read_b128 v[204:207], v126 offset:64
	v_mfma_f32_16x16x32_bf16 v[18:21], v[164:167], v[148:151], v[18:21]
	v_mfma_f32_16x16x32_bf16 v[22:25], v[168:171], v[148:151], v[22:25]
	ds_read_b128 v[148:151], v127 offset:64
	v_mfma_f32_16x16x32_bf16 v[10:13], v[156:159], v[152:155], v[10:13]
	v_mfma_f32_16x16x32_bf16 v[14:17], v[160:163], v[152:155], v[14:17]
	ds_read_b128 v[156:159], v128 offset:64
	v_mfma_f32_16x16x32_bf16 v[2:5], v[164:167], v[152:155], v[2:5]
	v_mfma_f32_16x16x32_bf16 v[6:9], v[168:171], v[152:155], v[6:9]
	ds_read_b128 v[152:155], v129 offset:64
	s_waitcnt lgkmcnt(3)
	v_mfma_f32_16x16x32_bf16 v[82:85], v[204:207], v[184:187], v[82:85]
	s_waitcnt lgkmcnt(2)
	v_mfma_f32_16x16x32_bf16 v[86:89], v[148:151], v[184:187], v[86:89]
	s_waitcnt vmcnt(11)
	ds_write_b128 v130, v[90:93]
	s_waitcnt lgkmcnt(2)
	v_mfma_f32_16x16x32_bf16 v[74:77], v[156:159], v[184:187], v[74:77]
	s_waitcnt lgkmcnt(1)
	v_mfma_f32_16x16x32_bf16 v[78:81], v[152:155], v[184:187], v[78:81]
	s_waitcnt vmcnt(10)
	ds_write_b128 v130, v[94:97] offset:9216
	v_mfma_f32_16x16x32_bf16 v[66:69], v[204:207], v[140:143], v[66:69]
	v_mfma_f32_16x16x32_bf16 v[70:73], v[148:151], v[140:143], v[70:73]
	s_waitcnt vmcnt(9)
	ds_write_b128 v130, v[98:101] offset:18432
	v_mfma_f32_16x16x32_bf16 v[34:37], v[156:159], v[140:143], v[34:37]
	v_mfma_f32_16x16x32_bf16 v[38:41], v[152:155], v[140:143], v[38:41]
	s_waitcnt vmcnt(8)
	ds_write_b128 v130, v[102:105] offset:27648
	v_mfma_f32_16x16x32_bf16 v[26:29], v[204:207], v[198:201], v[26:29]
	v_mfma_f32_16x16x32_bf16 v[30:33], v[148:151], v[198:201], v[30:33]
	s_waitcnt vmcnt(7)
	ds_write_b128 v130, v[132:135] offset:36864
	v_mfma_f32_16x16x32_bf16 v[18:21], v[156:159], v[198:201], v[18:21]
	v_mfma_f32_16x16x32_bf16 v[22:25], v[152:155], v[198:201], v[22:25]
	s_waitcnt vmcnt(6)
	ds_write_b128 v130, v[136:139] offset:46080
	v_mfma_f32_16x16x32_bf16 v[10:13], v[204:207], v[144:147], v[10:13]
	v_mfma_f32_16x16x32_bf16 v[14:17], v[148:151], v[144:147], v[14:17]
	v_mfma_f32_16x16x32_bf16 v[2:5], v[156:159], v[144:147], v[2:5]
	v_mfma_f32_16x16x32_bf16 v[6:9], v[152:155], v[144:147], v[6:9]
	s_waitcnt lgkmcnt(0)
	s_barrier
	s_cmp_gt_u32 s16, 13
	s_cbranch_scc0 .LBB0_1455
	s_waitcnt vmcnt(5)
	v_mul_f32_e32 v45, 0xbfb8aa3b, v82
	v_exp_f32_e32 v45, v45
	s_waitcnt vmcnt(4)
	v_mul_f32_e32 v46, 0xbfb8aa3b, v83
	v_exp_f32_e32 v49, v46
	s_waitcnt vmcnt(3)
	v_mul_f32_e32 v50, 0xbfb8aa3b, v85
	v_add_f32_e32 v45, 1.0, v45
	v_rcp_f32_e32 v48, v45
	v_add_f32_e32 v45, 1.0, v49
	v_mul_f32_e32 v49, 0xbfb8aa3b, v84
	v_exp_f32_e32 v49, v49
	v_exp_f32_e32 v51, v50
	v_rcp_f32_e32 v50, v45
	v_mov_b32_e32 v52, v82
	v_add_f32_e32 v45, 1.0, v49
	v_rcp_f32_e32 v49, v45
	v_add_f32_e32 v45, 1.0, v51
	v_rcp_f32_e32 v51, v45
	v_mov_b32_e32 v53, v84
	v_pk_mul_f32 v[48:49], v[52:53], v[48:49]
	v_mov_b32_e32 v52, v86
	v_mov_b32_e32 v53, v88
	v_mov_b32_e32 v84, v83
	v_pk_mul_f32 v[48:49], v[52:53], v[48:49]
	v_pk_mul_f32 v[50:51], v[84:85], v[50:51]
	v_mov_b32_e32 v88, v87
	v_pk_mul_f32 v[50:51], v[88:89], v[50:51]
	v_cvt_pk_bf16_f32 v48, v48, v50
	v_cvt_pk_bf16_f32 v49, v49, v51
	v_or_b32_e32 v42, s7, v114
	v_ashrrev_i32_e32 v42, 1, v42
	v_mul_f32_e32 v50, 0xbfb8aa3b, v74
	v_or_b32_e32 v44, v42, v118
	v_exp_f32_e32 v50, v50
	v_mul_f32_e32 v51, 0xbfb8aa3b, v75
	s_waitcnt vmcnt(2)
	v_add_u32_e32 v54, s6, v116
	v_mov_b64_e32 v[42:43], s[12:13]
	v_ashrrev_i32_e32 v45, 31, v44
	v_exp_f32_e32 v51, v51
	v_mad_i64_i32 v[46:47], s[6:7], v54, s52, v[42:43]
	v_lshlrev_b64 v[44:45], 1, v[44:45]
	v_lshl_add_u64 v[46:47], v[46:47], 0, v[44:45]
	s_waitcnt vmcnt(0)
	global_store_dwordx2 v[46:47], v[48:49], off
	v_add_f32_e32 v48, 1.0, v50
	v_mul_f32_e32 v50, 0xbfb8aa3b, v76
	v_add_f32_e32 v49, 1.0, v51
	v_exp_f32_e32 v51, v50
	v_mul_f32_e32 v50, 0xbfb8aa3b, v77
	v_exp_f32_e32 v52, v50
	v_rcp_f32_e32 v50, v49
	v_add_f32_e32 v49, 1.0, v51
	v_rcp_f32_e32 v48, v48
	v_rcp_f32_e32 v49, v49
	v_add_f32_e32 v51, 1.0, v52
	v_rcp_f32_e32 v51, v51
	v_mov_b32_e32 v52, v74
	v_mov_b32_e32 v53, v76
	v_pk_mul_f32 v[48:49], v[52:53], v[48:49]
	v_mov_b32_e32 v52, v78
	v_mov_b32_e32 v53, v80
	v_mov_b32_e32 v76, v75
	v_pk_mul_f32 v[48:49], v[52:53], v[48:49]
	v_pk_mul_f32 v[50:51], v[76:77], v[50:51]
	v_mov_b32_e32 v80, v79
	v_pk_mul_f32 v[50:51], v[80:81], v[50:51]
	v_cvt_pk_bf16_f32 v49, v49, v51
	v_cvt_pk_bf16_f32 v48, v48, v50
	global_store_dwordx2 v[46:47], v[48:49], off offset:32
	v_mul_f32_e32 v47, 0xbfb8aa3b, v66
	v_exp_f32_e32 v48, v47
	v_mul_f32_e32 v47, 0xbfb8aa3b, v67
	v_exp_f32_e32 v49, v47
	v_mul_f32_e32 v50, 0xbfb8aa3b, v68
	v_exp_f32_e32 v51, v50
	v_mul_f32_e32 v50, 0xbfb8aa3b, v69
	v_exp_f32_e32 v52, v50
	v_add_f32_e32 v49, 1.0, v49
	v_add_f32_e32 v48, 1.0, v48
	v_rcp_f32_e32 v50, v49
	v_add_f32_e32 v49, 1.0, v51
	v_rcp_f32_e32 v48, v48
	v_rcp_f32_e32 v49, v49
	v_add_f32_e32 v51, 1.0, v52
	v_rcp_f32_e32 v51, v51
	v_mov_b32_e32 v52, v66
	v_mov_b32_e32 v53, v68
	v_pk_mul_f32 v[48:49], v[52:53], v[48:49]
	v_mov_b32_e32 v52, v70
	v_mov_b32_e32 v53, v72
	v_mov_b32_e32 v68, v67
	v_pk_mul_f32 v[48:49], v[52:53], v[48:49]
	v_pk_mul_f32 v[50:51], v[68:69], v[50:51]
	v_mov_b32_e32 v72, v71
	v_pk_mul_f32 v[50:51], v[72:73], v[50:51]
	v_cvt_pk_bf16_f32 v48, v48, v50
	v_cvt_pk_bf16_f32 v49, v49, v51
	v_mul_f32_e32 v50, 0xbfb8aa3b, v34
	v_exp_f32_e32 v50, v50
	v_mul_f32_e32 v51, 0xbfb8aa3b, v35
	v_or_b32_e32 v46, 16, v54
	v_exp_f32_e32 v51, v51
	v_mad_i64_i32 v[46:47], s[6:7], v46, s52, v[42:43]
	v_lshl_add_u64 v[46:47], v[46:47], 0, v[44:45]
	global_store_dwordx2 v[46:47], v[48:49], off
	v_add_f32_e32 v48, 1.0, v50
	v_mul_f32_e32 v50, 0xbfb8aa3b, v36
	v_add_f32_e32 v49, 1.0, v51
	v_exp_f32_e32 v51, v50
	v_mul_f32_e32 v50, 0xbfb8aa3b, v37
	v_exp_f32_e32 v52, v50
	v_rcp_f32_e32 v50, v49
	v_add_f32_e32 v49, 1.0, v51
	v_rcp_f32_e32 v48, v48
	v_add_f32_e32 v51, 1.0, v52
	v_rcp_f32_e32 v49, v49
	v_rcp_f32_e32 v51, v51
	v_mov_b32_e32 v52, v34
	v_mov_b32_e32 v53, v36
	v_mov_b32_e32 v36, v35
	v_pk_mul_f32 v[48:49], v[52:53], v[48:49]
	v_mov_b32_e32 v53, v40
	v_pk_mul_f32 v[34:35], v[36:37], v[50:51]
	v_mov_b32_e32 v40, v39
	v_mov_b32_e32 v52, v38
	v_pk_mul_f32 v[34:35], v[40:41], v[34:35]
	v_pk_mul_f32 v[48:49], v[52:53], v[48:49]
	v_cvt_pk_bf16_f32 v36, v49, v35
	v_cvt_pk_bf16_f32 v37, v48, v34
	v_mov_b32_e32 v35, v36
	v_mov_b32_e32 v34, v37
	global_store_dwordx2 v[46:47], v[34:35], off offset:32
	v_mul_f32_e32 v35, 0xbfb8aa3b, v26
	v_exp_f32_e32 v36, v35
	v_mul_f32_e32 v35, 0xbfb8aa3b, v27
	v_mul_f32_e32 v38, 0xbfb8aa3b, v28
	v_exp_f32_e32 v37, v35
	v_exp_f32_e32 v39, v38
	v_mul_f32_e32 v38, 0xbfb8aa3b, v29
	v_exp_f32_e32 v40, v38
	v_add_f32_e32 v37, 1.0, v37
	v_add_f32_e32 v36, 1.0, v36
	v_rcp_f32_e32 v38, v37
	v_add_f32_e32 v37, 1.0, v39
	v_add_f32_e32 v39, 1.0, v40
	v_rcp_f32_e32 v36, v36
	v_rcp_f32_e32 v37, v37
	v_rcp_f32_e32 v39, v39
	v_mov_b32_e32 v40, v26
	v_mov_b32_e32 v41, v28
	v_mov_b32_e32 v28, v27
	v_pk_mul_f32 v[36:37], v[40:41], v[36:37]
	v_mov_b32_e32 v41, v32
	v_pk_mul_f32 v[26:27], v[28:29], v[38:39]
	v_mov_b32_e32 v32, v31
	v_mov_b32_e32 v40, v30
	v_pk_mul_f32 v[26:27], v[32:33], v[26:27]
	v_pk_mul_f32 v[36:37], v[40:41], v[36:37]
	v_cvt_pk_bf16_f32 v28, v37, v27
	v_cvt_pk_bf16_f32 v29, v36, v26
	v_mov_b32_e32 v27, v28
	v_mul_f32_e32 v28, 0xbfb8aa3b, v18
	v_mov_b32_e32 v26, v29
	v_exp_f32_e32 v28, v28
	v_mul_f32_e32 v29, 0xbfb8aa3b, v19
	v_or_b32_e32 v34, 32, v54
	v_exp_f32_e32 v29, v29
	v_mad_i64_i32 v[34:35], s[6:7], v34, s52, v[42:43]
	v_lshl_add_u64 v[34:35], v[34:35], 0, v[44:45]
	global_store_dwordx2 v[34:35], v[26:27], off
	v_add_f32_e32 v26, 1.0, v28
	v_mul_f32_e32 v28, 0xbfb8aa3b, v20
	v_add_f32_e32 v27, 1.0, v29
	v_exp_f32_e32 v29, v28
	v_mul_f32_e32 v28, 0xbfb8aa3b, v21
	v_exp_f32_e32 v30, v28
	v_rcp_f32_e32 v28, v27
	v_add_f32_e32 v27, 1.0, v29
	v_rcp_f32_e32 v26, v26
	v_add_f32_e32 v29, 1.0, v30
	v_rcp_f32_e32 v27, v27
	v_rcp_f32_e32 v29, v29
	v_mov_b32_e32 v30, v18
	v_mov_b32_e32 v31, v20
	v_mov_b32_e32 v20, v19
	v_pk_mul_f32 v[26:27], v[30:31], v[26:27]
	v_mov_b32_e32 v31, v24
	v_pk_mul_f32 v[18:19], v[20:21], v[28:29]
	v_mov_b32_e32 v24, v23
	v_mov_b32_e32 v30, v22
	v_pk_mul_f32 v[18:19], v[24:25], v[18:19]
	v_pk_mul_f32 v[26:27], v[30:31], v[26:27]
	v_cvt_pk_bf16_f32 v20, v27, v19
	v_cvt_pk_bf16_f32 v21, v26, v18
	v_mov_b32_e32 v19, v20
	v_mov_b32_e32 v18, v21
	global_store_dwordx2 v[34:35], v[18:19], off offset:32
	v_mul_f32_e32 v19, 0xbfb8aa3b, v10
	v_exp_f32_e32 v20, v19
	v_mul_f32_e32 v19, 0xbfb8aa3b, v11
	v_mul_f32_e32 v22, 0xbfb8aa3b, v12
	v_exp_f32_e32 v21, v19
	v_exp_f32_e32 v23, v22
	v_mul_f32_e32 v22, 0xbfb8aa3b, v13
	v_exp_f32_e32 v24, v22
	v_add_f32_e32 v21, 1.0, v21
	v_add_f32_e32 v20, 1.0, v20
	v_rcp_f32_e32 v22, v21
	v_add_f32_e32 v21, 1.0, v23
	v_add_f32_e32 v23, 1.0, v24
	v_rcp_f32_e32 v20, v20
	v_rcp_f32_e32 v21, v21
	v_rcp_f32_e32 v23, v23
	v_mov_b32_e32 v24, v10
	v_mov_b32_e32 v25, v12
	v_mov_b32_e32 v12, v11
	v_pk_mul_f32 v[20:21], v[24:25], v[20:21]
	v_mov_b32_e32 v25, v16
	v_pk_mul_f32 v[10:11], v[12:13], v[22:23]
	v_mov_b32_e32 v16, v15
	v_mov_b32_e32 v24, v14
	v_pk_mul_f32 v[10:11], v[16:17], v[10:11]
	v_pk_mul_f32 v[20:21], v[24:25], v[20:21]
	v_cvt_pk_bf16_f32 v12, v21, v11
	v_cvt_pk_bf16_f32 v13, v20, v10
	v_mov_b32_e32 v11, v12
	v_mul_f32_e32 v12, 0xbfb8aa3b, v2
	v_mov_b32_e32 v10, v13
	v_exp_f32_e32 v12, v12
	v_mul_f32_e32 v13, 0xbfb8aa3b, v3
	v_or_b32_e32 v18, 48, v54
	v_exp_f32_e32 v13, v13
	v_mad_i64_i32 v[18:19], s[6:7], v18, s52, v[42:43]
	v_lshl_add_u64 v[18:19], v[18:19], 0, v[44:45]
	global_store_dwordx2 v[18:19], v[10:11], off
	v_add_f32_e32 v10, 1.0, v12
	v_mul_f32_e32 v12, 0xbfb8aa3b, v4
	v_add_f32_e32 v11, 1.0, v13
	v_exp_f32_e32 v13, v12
	v_mul_f32_e32 v12, 0xbfb8aa3b, v5
	v_exp_f32_e32 v14, v12
	v_rcp_f32_e32 v12, v11
	v_add_f32_e32 v11, 1.0, v13
	v_rcp_f32_e32 v10, v10
	v_add_f32_e32 v13, 1.0, v14
	v_rcp_f32_e32 v11, v11
	v_rcp_f32_e32 v13, v13
	v_mov_b32_e32 v14, v2
	v_mov_b32_e32 v15, v4
	v_mov_b32_e32 v4, v3
	v_pk_mul_f32 v[10:11], v[14:15], v[10:11]
	v_mov_b32_e32 v15, v8
	v_pk_mul_f32 v[2:3], v[4:5], v[12:13]
	v_mov_b32_e32 v8, v7
	v_mov_b32_e32 v14, v6
	v_pk_mul_f32 v[2:3], v[8:9], v[2:3]
	v_pk_mul_f32 v[10:11], v[14:15], v[10:11]
	v_and_b32_sdwa v6, v3, v177 dst_sel:DWORD dst_unused:UNUSED_PAD src0_sel:WORD_1 src1_sel:DWORD
	v_and_b32_sdwa v7, v2, v177 dst_sel:DWORD dst_unused:UNUSED_PAD src0_sel:WORD_1 src1_sel:DWORD
	v_and_b32_sdwa v4, v11, v177 dst_sel:DWORD dst_unused:UNUSED_PAD src0_sel:WORD_1 src1_sel:DWORD
	v_and_b32_sdwa v5, v10, v177 dst_sel:DWORD dst_unused:UNUSED_PAD src0_sel:WORD_1 src1_sel:DWORD
	v_add3_u32 v3, v3, v6, s28
	v_add3_u32 v2, v2, v7, s28
	v_add3_u32 v5, v10, v5, s28
	v_add3_u32 v4, v11, v4, s28
	v_and_b32_e32 v3, 0xffff0000, v3
	v_and_b32_e32 v2, 0xffff0000, v2
	v_or_b32_sdwa v3, v3, v4 dst_sel:DWORD dst_unused:UNUSED_PAD src0_sel:DWORD src1_sel:WORD_1
	v_or_b32_sdwa v2, v2, v5 dst_sel:DWORD dst_unused:UNUSED_PAD src0_sel:DWORD src1_sel:WORD_1
	s_mov_b32 s7, 0
	s_mov_b32 s6, s18
	s_mov_b32 s4, s19
	global_store_dwordx2 v[18:19], v[2:3], off offset:32
	s_branch .LBB0_1446

.LBB0_1462:
	s_bitcmp1_b32 s4, 0
	s_cselect_b32 s2, 0x12000, 0
	v_or_b32_e32 v218, s2, v206
	v_add_u32_e32 v214, v218, v0
	v_add_u32_e32 v246, v218, v167
	ds_read_b128 v[184:187], v214
	ds_read_b128 v[218:221], v246 offset:32768
	ds_read_b128 v[198:201], v214 offset:2048
	ds_read_b128 v[210:213], v214 offset:4096
	ds_read_b128 v[214:217], v214 offset:6144
	ds_read_b128 v[222:225], v246 offset:34816
	ds_read_b128 v[226:229], v246 offset:36864
	ds_read_b128 v[230:233], v246 offset:38912
	ds_read_b128 v[234:237], v246 offset:40960
	ds_read_b128 v[238:241], v246 offset:43008
	ds_read_b128 v[242:245], v246 offset:45056
	ds_read_b128 v[246:249], v246 offset:47104
	s_add_i32 s10, s4, 1
	s_bitcmp1_b32 s10, 0
	s_cselect_b32 s3, 0x12000, 0
	v_add_u32_e32 v171, s3, v166
	v_xor_b32_e32 v169, 64, v206
	v_add3_u32 v169, s2, v167, v169
	s_waitcnt lgkmcnt(10)
	v_mfma_f32_16x16x32_bf16 v[158:161], v[218:221], v[184:187], v[158:161]
	s_waitcnt lgkmcnt(9)
	v_mfma_f32_16x16x32_bf16 v[94:97], v[218:221], v[198:201], v[94:97]
	s_waitcnt lgkmcnt(8)
	v_mfma_f32_16x16x32_bf16 v[62:65], v[218:221], v[210:213], v[62:65]
	s_waitcnt lgkmcnt(7)
	v_mfma_f32_16x16x32_bf16 v[30:33], v[218:221], v[214:217], v[30:33]
	ds_read_b128 v[218:221], v169 offset:32768
	s_waitcnt lgkmcnt(7)
	v_mfma_f32_16x16x32_bf16 v[154:157], v[222:225], v[184:187], v[154:157]
	v_mfma_f32_16x16x32_bf16 v[90:93], v[222:225], v[198:201], v[90:93]
	v_mfma_f32_16x16x32_bf16 v[58:61], v[222:225], v[210:213], v[58:61]
	v_mfma_f32_16x16x32_bf16 v[26:29], v[222:225], v[214:217], v[26:29]
	ds_read_b128 v[222:225], v169 offset:34816
	s_waitcnt lgkmcnt(7)
	v_mfma_f32_16x16x32_bf16 v[150:153], v[226:229], v[184:187], v[150:153]
	v_mfma_f32_16x16x32_bf16 v[86:89], v[226:229], v[198:201], v[86:89]
	v_mfma_f32_16x16x32_bf16 v[54:57], v[226:229], v[210:213], v[54:57]
	v_mfma_f32_16x16x32_bf16 v[22:25], v[226:229], v[214:217], v[22:25]
	ds_read_b128 v[226:229], v169 offset:36864
	s_waitcnt lgkmcnt(7)
	v_mfma_f32_16x16x32_bf16 v[146:149], v[230:233], v[184:187], v[146:149]
	v_mfma_f32_16x16x32_bf16 v[82:85], v[230:233], v[198:201], v[82:85]
	v_mfma_f32_16x16x32_bf16 v[50:53], v[230:233], v[210:213], v[50:53]
	v_mfma_f32_16x16x32_bf16 v[18:21], v[230:233], v[214:217], v[18:21]
	ds_read_b128 v[230:233], v169 offset:38912
	s_waitcnt lgkmcnt(7)
	v_mfma_f32_16x16x32_bf16 v[142:145], v[234:237], v[184:187], v[142:145]
	v_mfma_f32_16x16x32_bf16 v[78:81], v[234:237], v[198:201], v[78:81]
	v_mfma_f32_16x16x32_bf16 v[46:49], v[234:237], v[210:213], v[46:49]
	v_mfma_f32_16x16x32_bf16 v[14:17], v[234:237], v[214:217], v[14:17]
	ds_read_b128 v[234:237], v169 offset:40960
	s_waitcnt lgkmcnt(7)
	v_mfma_f32_16x16x32_bf16 v[138:141], v[238:241], v[184:187], v[138:141]
	v_mfma_f32_16x16x32_bf16 v[74:77], v[238:241], v[198:201], v[74:77]
	v_mfma_f32_16x16x32_bf16 v[42:45], v[238:241], v[210:213], v[42:45]
	v_mfma_f32_16x16x32_bf16 v[10:13], v[238:241], v[214:217], v[10:13]
	ds_read_b128 v[238:241], v169 offset:43008
	s_waitcnt lgkmcnt(7)
	v_mfma_f32_16x16x32_bf16 v[102:105], v[242:245], v[184:187], v[102:105]
	v_mfma_f32_16x16x32_bf16 v[70:73], v[242:245], v[198:201], v[70:73]
	v_mfma_f32_16x16x32_bf16 v[38:41], v[242:245], v[210:213], v[38:41]
	v_mfma_f32_16x16x32_bf16 v[6:9], v[242:245], v[214:217], v[6:9]
	ds_read_b128 v[242:245], v169 offset:45056
	s_waitcnt lgkmcnt(7)
	v_mfma_f32_16x16x32_bf16 v[98:101], v[246:249], v[184:187], v[98:101]
	v_mfma_f32_16x16x32_bf16 v[66:69], v[246:249], v[198:201], v[66:69]
	v_xor_b32_e32 v169, 64, v206
	v_add3_u32 v169, s2, v0, v169
	ds_read_b128 v[184:187], v169
	ds_read_b128 v[198:201], v169 offset:2048
	v_mfma_f32_16x16x32_bf16 v[34:37], v[246:249], v[210:213], v[34:37]
	ds_read_b128 v[210:213], v169 offset:4096
	v_mfma_f32_16x16x32_bf16 v[2:5], v[246:249], v[214:217], v[2:5]
	ds_read_b128 v[214:217], v169 offset:6144
	v_xor_b32_e32 v169, 64, v206
	v_add3_u32 v169, s2, v167, v169
	ds_read_b128 v[246:249], v169 offset:47104
	s_waitcnt lgkmcnt(4)
	v_mfma_f32_16x16x32_bf16 v[158:161], v[218:221], v[184:187], v[158:161]
	s_waitcnt lgkmcnt(3)
	v_mfma_f32_16x16x32_bf16 v[94:97], v[218:221], v[198:201], v[94:97]
	s_waitcnt lgkmcnt(2)
	v_mfma_f32_16x16x32_bf16 v[62:65], v[218:221], v[210:213], v[62:65]
	s_waitcnt lgkmcnt(1)
	v_mfma_f32_16x16x32_bf16 v[30:33], v[218:221], v[214:217], v[30:33]
	s_waitcnt vmcnt(7)
	ds_write_b128 v171, v[114:117]
	v_mfma_f32_16x16x32_bf16 v[154:157], v[222:225], v[184:187], v[154:157]
	v_mfma_f32_16x16x32_bf16 v[90:93], v[222:225], v[198:201], v[90:93]
	global_load_dwordx4 v[114:117], v168, vcc offset:256
	v_mfma_f32_16x16x32_bf16 v[58:61], v[222:225], v[210:213], v[58:61]
	v_mfma_f32_16x16x32_bf16 v[26:29], v[222:225], v[214:217], v[26:29]
	s_waitcnt vmcnt(7)
	ds_write_b128 v171, v[106:109] offset:8192
	v_mfma_f32_16x16x32_bf16 v[150:153], v[226:229], v[184:187], v[150:153]
	v_mfma_f32_16x16x32_bf16 v[86:89], v[226:229], v[198:201], v[86:89]
	v_add_u32_e32 v106, s34, v168
	global_load_dwordx4 v[106:109], v106, vcc offset:256
	v_mfma_f32_16x16x32_bf16 v[54:57], v[226:229], v[210:213], v[54:57]
	v_mfma_f32_16x16x32_bf16 v[22:25], v[226:229], v[214:217], v[22:25]
	s_waitcnt vmcnt(7)
	ds_write_b128 v171, v[110:113] offset:16384
	v_mfma_f32_16x16x32_bf16 v[146:149], v[230:233], v[184:187], v[146:149]
	v_mfma_f32_16x16x32_bf16 v[82:85], v[230:233], v[198:201], v[82:85]
	v_add_u32_e32 v110, s35, v168
	global_load_dwordx4 v[110:113], v110, vcc offset:256
	v_mfma_f32_16x16x32_bf16 v[50:53], v[230:233], v[210:213], v[50:53]
	v_mfma_f32_16x16x32_bf16 v[18:21], v[230:233], v[214:217], v[18:21]
	s_waitcnt vmcnt(7)
	ds_write_b128 v171, v[126:129] offset:24576
	v_mfma_f32_16x16x32_bf16 v[142:145], v[234:237], v[184:187], v[142:145]
	v_mfma_f32_16x16x32_bf16 v[78:81], v[234:237], v[198:201], v[78:81]
	v_add_u32_e32 v126, s36, v168
	global_load_dwordx4 v[126:129], v126, vcc offset:256
	v_mfma_f32_16x16x32_bf16 v[46:49], v[234:237], v[210:213], v[46:49]
	v_mfma_f32_16x16x32_bf16 v[14:17], v[234:237], v[214:217], v[14:17]
	s_waitcnt vmcnt(7)
	ds_write_b128 v171, v[122:125] offset:32768
	v_mfma_f32_16x16x32_bf16 v[138:141], v[238:241], v[184:187], v[138:141]
	v_mfma_f32_16x16x32_bf16 v[74:77], v[238:241], v[198:201], v[74:77]
	global_load_dwordx4 v[122:125], v170, s[100:101] offset:256
	v_mfma_f32_16x16x32_bf16 v[42:45], v[238:241], v[210:213], v[42:45]
	v_mfma_f32_16x16x32_bf16 v[10:13], v[238:241], v[214:217], v[10:13]
	s_waitcnt vmcnt(7)
	ds_write_b128 v171, v[118:121] offset:40960
	v_mfma_f32_16x16x32_bf16 v[102:105], v[242:245], v[184:187], v[102:105]
	v_mfma_f32_16x16x32_bf16 v[70:73], v[242:245], v[198:201], v[70:73]
	v_add_u32_e32 v118, s34, v170
	global_load_dwordx4 v[118:121], v118, s[100:101] offset:256
	v_mfma_f32_16x16x32_bf16 v[38:41], v[242:245], v[210:213], v[38:41]
	v_mfma_f32_16x16x32_bf16 v[6:9], v[242:245], v[214:217], v[6:9]
	s_waitcnt vmcnt(7)
	ds_write_b128 v171, v[134:137] offset:49152
	s_waitcnt lgkmcnt(7)
	v_mfma_f32_16x16x32_bf16 v[98:101], v[246:249], v[184:187], v[98:101]
	v_mfma_f32_16x16x32_bf16 v[66:69], v[246:249], v[198:201], v[66:69]
	v_add_u32_e32 v134, s35, v170
	global_load_dwordx4 v[134:137], v134, s[100:101] offset:256
	v_mfma_f32_16x16x32_bf16 v[34:37], v[246:249], v[210:213], v[34:37]
	v_mfma_f32_16x16x32_bf16 v[2:5], v[246:249], v[214:217], v[2:5]
	s_waitcnt vmcnt(7)
	ds_write_b128 v171, v[130:133] offset:57344
	v_add_u32_e32 v130, s36, v170
	global_load_dwordx4 v[130:133], v130, s[100:101] offset:256
	v_add_u32_e32 v168, 0x80, v168
	v_add_u32_e32 v170, 0x80, v170
	s_waitcnt lgkmcnt(0)
	s_barrier
	s_cmp_eq_u32 s10, 16
	s_mov_b32 s4, s10
	s_cbranch_scc0 .LBB0_1462
	s_waitcnt vmcnt(4)
	v_mul_f32_e32 v109, 0xbfb8aa3b, v158
	v_exp_f32_e32 v109, v109
	s_waitcnt vmcnt(3)
	v_mul_f32_e32 v111, 0xbfb8aa3b, v159
	v_exp_f32_e32 v111, v111
	v_mul_f32_e32 v115, 0xbfb8aa3b, v161
	v_add_f32_e32 v109, 1.0, v109
	v_rcp_f32_e32 v114, v109
	v_add_f32_e32 v109, 1.0, v111
	v_mul_f32_e32 v111, 0xbfb8aa3b, v160
	v_exp_f32_e32 v111, v111
	v_exp_f32_e32 v117, v115
	v_rcp_f32_e32 v116, v109
	s_waitcnt vmcnt(2)
	v_mov_b32_e32 v118, v158
	v_add_f32_e32 v109, 1.0, v111
	v_rcp_f32_e32 v115, v109
	v_add_f32_e32 v109, 1.0, v117
	v_rcp_f32_e32 v117, v109
	v_mov_b32_e32 v119, v160
	v_pk_mul_f32 v[114:115], v[118:119], v[114:115]
	v_mov_b32_e32 v118, v154
	v_mov_b32_e32 v119, v156
	v_mov_b32_e32 v160, v159
	v_pk_mul_f32 v[114:115], v[118:119], v[114:115]
	v_pk_mul_f32 v[116:117], v[160:161], v[116:117]
	v_mov_b32_e32 v156, v155
	v_pk_mul_f32 v[116:117], v[156:157], v[116:117]
	v_cvt_pk_bf16_f32 v111, v115, v117
	v_cvt_pk_bf16_f32 v114, v114, v116
	v_or_b32_e32 v106, s7, v207
	v_ashrrev_i32_e32 v106, 1, v106
	v_mov_b32_e32 v115, v111
	v_mul_f32_e32 v111, 0xbfb8aa3b, v150
	v_or_b32_e32 v108, v106, v208
	v_exp_f32_e32 v111, v111
	v_mul_f32_e32 v116, 0xbfb8aa3b, v151
	v_add_u32_e32 v110, s6, v205
	v_mov_b64_e32 v[106:107], s[12:13]
	v_ashrrev_i32_e32 v109, 31, v108
	v_exp_f32_e32 v116, v116
	v_mad_i64_i32 v[112:113], s[6:7], v110, s52, v[106:107]
	v_lshlrev_b64 v[108:109], 1, v[108:109]
	v_lshl_add_u64 v[112:113], v[112:113], 0, v[108:109]
	s_waitcnt vmcnt(0)
	global_store_dwordx2 v[112:113], v[114:115], off
	v_add_f32_e32 v111, 1.0, v111
	v_mul_f32_e32 v115, 0xbfb8aa3b, v152
	v_rcp_f32_e32 v114, v111
	v_add_f32_e32 v111, 1.0, v116
	v_exp_f32_e32 v115, v115
	v_mul_f32_e32 v116, 0xbfb8aa3b, v153
	v_exp_f32_e32 v117, v116
	v_rcp_f32_e32 v116, v111
	v_add_f32_e32 v111, 1.0, v115
	v_rcp_f32_e32 v115, v111
	v_add_f32_e32 v111, 1.0, v117
	v_rcp_f32_e32 v117, v111
	v_mov_b32_e32 v118, v150
	v_mov_b32_e32 v119, v152
	v_pk_mul_f32 v[114:115], v[118:119], v[114:115]
	v_mov_b32_e32 v118, v146
	v_mov_b32_e32 v119, v148
	v_mov_b32_e32 v152, v151
	v_pk_mul_f32 v[114:115], v[118:119], v[114:115]
	v_pk_mul_f32 v[116:117], v[152:153], v[116:117]
	v_mov_b32_e32 v148, v147
	v_pk_mul_f32 v[116:117], v[148:149], v[116:117]
	v_cvt_pk_bf16_f32 v111, v115, v117
	v_cvt_pk_bf16_f32 v114, v114, v116
	v_mov_b32_e32 v115, v111
	v_mul_f32_e32 v111, 0xbfb8aa3b, v142
	v_exp_f32_e32 v111, v111
	v_mul_f32_e32 v116, 0xbfb8aa3b, v143
	v_exp_f32_e32 v116, v116
	global_store_dwordx2 v[112:113], v[114:115], off offset:32
	v_add_f32_e32 v111, 1.0, v111
	v_mul_f32_e32 v115, 0xbfb8aa3b, v144
	v_rcp_f32_e32 v114, v111
	v_add_f32_e32 v111, 1.0, v116
	v_exp_f32_e32 v115, v115
	v_mul_f32_e32 v116, 0xbfb8aa3b, v145
	v_exp_f32_e32 v117, v116
	v_rcp_f32_e32 v116, v111
	v_add_f32_e32 v111, 1.0, v115
	v_rcp_f32_e32 v115, v111
	v_add_f32_e32 v111, 1.0, v117
	v_rcp_f32_e32 v117, v111
	v_mov_b32_e32 v118, v142
	v_mov_b32_e32 v119, v144
	v_pk_mul_f32 v[114:115], v[118:119], v[114:115]
	v_mov_b32_e32 v118, v138
	v_mov_b32_e32 v119, v140
	v_mov_b32_e32 v144, v143
	v_pk_mul_f32 v[114:115], v[118:119], v[114:115]
	v_pk_mul_f32 v[116:117], v[144:145], v[116:117]
	v_mov_b32_e32 v140, v139
	v_pk_mul_f32 v[116:117], v[140:141], v[116:117]
	v_cvt_pk_bf16_f32 v111, v115, v117
	v_cvt_pk_bf16_f32 v114, v114, v116
	v_mov_b32_e32 v115, v111
	v_mul_f32_e32 v111, 0xbfb8aa3b, v102
	v_exp_f32_e32 v111, v111
	v_mul_f32_e32 v116, 0xbfb8aa3b, v103
	v_exp_f32_e32 v116, v116
	global_store_dwordx2 v[112:113], v[114:115], off offset:64
	v_add_f32_e32 v111, 1.0, v111
	v_mul_f32_e32 v115, 0xbfb8aa3b, v104
	v_rcp_f32_e32 v114, v111
	v_add_f32_e32 v111, 1.0, v116
	v_exp_f32_e32 v115, v115
	v_mul_f32_e32 v116, 0xbfb8aa3b, v105
	v_exp_f32_e32 v117, v116
	v_rcp_f32_e32 v116, v111
	v_add_f32_e32 v111, 1.0, v115
	v_rcp_f32_e32 v115, v111
	v_add_f32_e32 v111, 1.0, v117
	v_rcp_f32_e32 v117, v111
	v_mov_b32_e32 v118, v102
	v_mov_b32_e32 v119, v104
	v_mov_b32_e32 v104, v103
	v_pk_mul_f32 v[114:115], v[118:119], v[114:115]
	v_mov_b32_e32 v119, v100
	v_pk_mul_f32 v[102:103], v[104:105], v[116:117]
	v_mov_b32_e32 v100, v99
	v_mov_b32_e32 v118, v98
	v_pk_mul_f32 v[98:99], v[100:101], v[102:103]
	v_pk_mul_f32 v[114:115], v[118:119], v[114:115]
	v_cvt_pk_bf16_f32 v100, v115, v99
	v_cvt_pk_bf16_f32 v101, v114, v98
	v_mov_b32_e32 v99, v100
	v_mov_b32_e32 v98, v101
	global_store_dwordx2 v[112:113], v[98:99], off offset:96
	v_mul_f32_e32 v99, 0xbfb8aa3b, v94
	v_exp_f32_e32 v100, v99
	v_mul_f32_e32 v99, 0xbfb8aa3b, v95
	v_mul_f32_e32 v102, 0xbfb8aa3b, v96
	v_exp_f32_e32 v101, v99
	v_exp_f32_e32 v103, v102
	v_mul_f32_e32 v102, 0xbfb8aa3b, v97
	v_exp_f32_e32 v104, v102
	v_add_f32_e32 v101, 1.0, v101
	v_add_f32_e32 v100, 1.0, v100
	v_rcp_f32_e32 v102, v101
	v_add_f32_e32 v101, 1.0, v103
	v_add_f32_e32 v103, 1.0, v104
	v_rcp_f32_e32 v100, v100
	v_rcp_f32_e32 v101, v101
	v_rcp_f32_e32 v103, v103
	v_mov_b32_e32 v104, v94
	v_mov_b32_e32 v105, v96
	v_mov_b32_e32 v96, v95
	v_pk_mul_f32 v[100:101], v[104:105], v[100:101]
	v_mov_b32_e32 v105, v92
	v_pk_mul_f32 v[94:95], v[96:97], v[102:103]
	v_mov_b32_e32 v92, v91
	v_mov_b32_e32 v104, v90
	v_pk_mul_f32 v[90:91], v[92:93], v[94:95]
	v_pk_mul_f32 v[100:101], v[104:105], v[100:101]
	v_cvt_pk_bf16_f32 v92, v101, v91
	v_cvt_pk_bf16_f32 v93, v100, v90
	v_mov_b32_e32 v91, v92
	v_mul_f32_e32 v92, 0xbfb8aa3b, v86
	v_mov_b32_e32 v90, v93
	v_exp_f32_e32 v92, v92
	v_mul_f32_e32 v93, 0xbfb8aa3b, v87
	v_or_b32_e32 v98, 16, v110
	v_exp_f32_e32 v93, v93
	v_mad_i64_i32 v[98:99], s[6:7], v98, s52, v[106:107]
	v_lshl_add_u64 v[98:99], v[98:99], 0, v[108:109]
	global_store_dwordx2 v[98:99], v[90:91], off
	v_add_f32_e32 v90, 1.0, v92
	v_mul_f32_e32 v92, 0xbfb8aa3b, v88
	v_add_f32_e32 v91, 1.0, v93
	v_exp_f32_e32 v93, v92
	v_mul_f32_e32 v92, 0xbfb8aa3b, v89
	v_exp_f32_e32 v94, v92
	v_rcp_f32_e32 v92, v91
	v_add_f32_e32 v91, 1.0, v93
	v_rcp_f32_e32 v90, v90
	v_add_f32_e32 v93, 1.0, v94
	v_rcp_f32_e32 v91, v91
	v_rcp_f32_e32 v93, v93
	v_mov_b32_e32 v94, v86
	v_mov_b32_e32 v95, v88
	v_mov_b32_e32 v88, v87
	v_pk_mul_f32 v[90:91], v[94:95], v[90:91]
	v_mov_b32_e32 v95, v84
	v_pk_mul_f32 v[86:87], v[88:89], v[92:93]
	v_mov_b32_e32 v84, v83
	v_mov_b32_e32 v94, v82
	v_pk_mul_f32 v[82:83], v[84:85], v[86:87]
	v_pk_mul_f32 v[90:91], v[94:95], v[90:91]
	v_cvt_pk_bf16_f32 v84, v91, v83
	v_cvt_pk_bf16_f32 v85, v90, v82
	v_mov_b32_e32 v83, v84
	v_mul_f32_e32 v84, 0xbfb8aa3b, v78
	v_mov_b32_e32 v82, v85
	v_exp_f32_e32 v84, v84
	v_mul_f32_e32 v85, 0xbfb8aa3b, v79
	v_exp_f32_e32 v85, v85
	global_store_dwordx2 v[98:99], v[82:83], off offset:32
	v_add_f32_e32 v82, 1.0, v84
	v_mul_f32_e32 v84, 0xbfb8aa3b, v80
	v_add_f32_e32 v83, 1.0, v85
	v_exp_f32_e32 v85, v84
	v_mul_f32_e32 v84, 0xbfb8aa3b, v81
	v_exp_f32_e32 v86, v84
	v_rcp_f32_e32 v84, v83
	v_add_f32_e32 v83, 1.0, v85
	v_rcp_f32_e32 v82, v82
	v_add_f32_e32 v85, 1.0, v86
	v_rcp_f32_e32 v83, v83
	v_rcp_f32_e32 v85, v85
	v_mov_b32_e32 v86, v78
	v_mov_b32_e32 v87, v80
	v_mov_b32_e32 v80, v79
	v_pk_mul_f32 v[82:83], v[86:87], v[82:83]
	v_mov_b32_e32 v87, v76
	v_pk_mul_f32 v[78:79], v[80:81], v[84:85]
	v_mov_b32_e32 v76, v75
	v_mov_b32_e32 v86, v74
	v_pk_mul_f32 v[74:75], v[76:77], v[78:79]
	v_pk_mul_f32 v[82:83], v[86:87], v[82:83]
	v_cvt_pk_bf16_f32 v76, v83, v75
	v_cvt_pk_bf16_f32 v77, v82, v74
	v_mov_b32_e32 v75, v76
	v_mul_f32_e32 v76, 0xbfb8aa3b, v70
	v_mov_b32_e32 v74, v77
	v_exp_f32_e32 v76, v76
	v_mul_f32_e32 v77, 0xbfb8aa3b, v71
	v_exp_f32_e32 v77, v77
	global_store_dwordx2 v[98:99], v[74:75], off offset:64
	v_add_f32_e32 v74, 1.0, v76
	v_mul_f32_e32 v76, 0xbfb8aa3b, v72
	v_add_f32_e32 v75, 1.0, v77
	v_exp_f32_e32 v77, v76
	v_mul_f32_e32 v76, 0xbfb8aa3b, v73
	v_exp_f32_e32 v78, v76
	v_rcp_f32_e32 v76, v75
	v_add_f32_e32 v75, 1.0, v77
	v_rcp_f32_e32 v74, v74
	v_add_f32_e32 v77, 1.0, v78
	v_rcp_f32_e32 v75, v75
	v_rcp_f32_e32 v77, v77
	v_mov_b32_e32 v78, v70
	v_mov_b32_e32 v79, v72
	v_mov_b32_e32 v72, v71
	v_pk_mul_f32 v[74:75], v[78:79], v[74:75]
	v_mov_b32_e32 v79, v68
	v_pk_mul_f32 v[70:71], v[72:73], v[76:77]
	v_mov_b32_e32 v68, v67
	v_mov_b32_e32 v78, v66
	v_pk_mul_f32 v[66:67], v[68:69], v[70:71]
	v_pk_mul_f32 v[74:75], v[78:79], v[74:75]
	v_cvt_pk_bf16_f32 v68, v75, v67
	v_cvt_pk_bf16_f32 v69, v74, v66
	v_mov_b32_e32 v67, v68
	v_mov_b32_e32 v66, v69
	global_store_dwordx2 v[98:99], v[66:67], off offset:96
	v_mul_f32_e32 v67, 0xbfb8aa3b, v62
	v_exp_f32_e32 v68, v67
	v_mul_f32_e32 v67, 0xbfb8aa3b, v63
	v_mul_f32_e32 v70, 0xbfb8aa3b, v64
	v_exp_f32_e32 v69, v67
	v_exp_f32_e32 v71, v70
	v_mul_f32_e32 v70, 0xbfb8aa3b, v65
	v_exp_f32_e32 v72, v70
	v_add_f32_e32 v69, 1.0, v69
	v_add_f32_e32 v68, 1.0, v68
	v_rcp_f32_e32 v70, v69
	v_add_f32_e32 v69, 1.0, v71
	v_add_f32_e32 v71, 1.0, v72
	v_rcp_f32_e32 v68, v68
	v_rcp_f32_e32 v69, v69
	v_rcp_f32_e32 v71, v71
	v_mov_b32_e32 v72, v62
	v_mov_b32_e32 v73, v64
	v_mov_b32_e32 v64, v63
	v_pk_mul_f32 v[68:69], v[72:73], v[68:69]
	v_mov_b32_e32 v73, v60
	v_pk_mul_f32 v[62:63], v[64:65], v[70:71]
	v_mov_b32_e32 v60, v59
	v_mov_b32_e32 v72, v58
	v_pk_mul_f32 v[58:59], v[60:61], v[62:63]
	v_pk_mul_f32 v[68:69], v[72:73], v[68:69]
	v_cvt_pk_bf16_f32 v60, v69, v59
	v_cvt_pk_bf16_f32 v61, v68, v58
	v_mov_b32_e32 v59, v60
	v_mul_f32_e32 v60, 0xbfb8aa3b, v54
	v_mov_b32_e32 v58, v61
	v_exp_f32_e32 v60, v60
	v_mul_f32_e32 v61, 0xbfb8aa3b, v55
	v_or_b32_e32 v66, 32, v110
	v_exp_f32_e32 v61, v61
	v_mad_i64_i32 v[66:67], s[6:7], v66, s52, v[106:107]
	v_lshl_add_u64 v[66:67], v[66:67], 0, v[108:109]
	global_store_dwordx2 v[66:67], v[58:59], off
	v_add_f32_e32 v58, 1.0, v60
	v_mul_f32_e32 v60, 0xbfb8aa3b, v56
	v_add_f32_e32 v59, 1.0, v61
	v_exp_f32_e32 v61, v60
	v_mul_f32_e32 v60, 0xbfb8aa3b, v57
	v_exp_f32_e32 v62, v60
	v_rcp_f32_e32 v60, v59
	v_add_f32_e32 v59, 1.0, v61
	v_rcp_f32_e32 v58, v58
	v_add_f32_e32 v61, 1.0, v62
	v_rcp_f32_e32 v59, v59
	v_rcp_f32_e32 v61, v61
	v_mov_b32_e32 v62, v54
	v_mov_b32_e32 v63, v56
	v_mov_b32_e32 v56, v55
	v_pk_mul_f32 v[58:59], v[62:63], v[58:59]
	v_mov_b32_e32 v63, v52
	v_pk_mul_f32 v[54:55], v[56:57], v[60:61]
	v_mov_b32_e32 v52, v51
	v_mov_b32_e32 v62, v50
	v_pk_mul_f32 v[50:51], v[52:53], v[54:55]
	v_pk_mul_f32 v[58:59], v[62:63], v[58:59]
	v_cvt_pk_bf16_f32 v52, v59, v51
	v_cvt_pk_bf16_f32 v53, v58, v50
	v_mov_b32_e32 v51, v52
	v_mul_f32_e32 v52, 0xbfb8aa3b, v46
	v_mov_b32_e32 v50, v53
	v_exp_f32_e32 v52, v52
	v_mul_f32_e32 v53, 0xbfb8aa3b, v47
	v_exp_f32_e32 v53, v53
	global_store_dwordx2 v[66:67], v[50:51], off offset:32
	v_add_f32_e32 v50, 1.0, v52
	v_mul_f32_e32 v52, 0xbfb8aa3b, v48
	v_add_f32_e32 v51, 1.0, v53
	v_exp_f32_e32 v53, v52
	v_mul_f32_e32 v52, 0xbfb8aa3b, v49
	v_exp_f32_e32 v54, v52
	v_rcp_f32_e32 v52, v51
	v_add_f32_e32 v51, 1.0, v53
	v_rcp_f32_e32 v50, v50
	v_add_f32_e32 v53, 1.0, v54
	v_rcp_f32_e32 v51, v51
	v_rcp_f32_e32 v53, v53
	v_mov_b32_e32 v54, v46
	v_mov_b32_e32 v55, v48
	v_mov_b32_e32 v48, v47
	v_pk_mul_f32 v[50:51], v[54:55], v[50:51]
	v_mov_b32_e32 v55, v44
	v_pk_mul_f32 v[46:47], v[48:49], v[52:53]
	v_mov_b32_e32 v44, v43
	v_mov_b32_e32 v54, v42
	v_pk_mul_f32 v[42:43], v[44:45], v[46:47]
	v_pk_mul_f32 v[50:51], v[54:55], v[50:51]
	v_cvt_pk_bf16_f32 v44, v51, v43
	v_cvt_pk_bf16_f32 v45, v50, v42
	v_mov_b32_e32 v43, v44
	v_mul_f32_e32 v44, 0xbfb8aa3b, v38
	v_mov_b32_e32 v42, v45
	v_exp_f32_e32 v44, v44
	v_mul_f32_e32 v45, 0xbfb8aa3b, v39
	v_exp_f32_e32 v45, v45
	global_store_dwordx2 v[66:67], v[42:43], off offset:64
	v_add_f32_e32 v42, 1.0, v44
	v_mul_f32_e32 v44, 0xbfb8aa3b, v40
	v_add_f32_e32 v43, 1.0, v45
	v_exp_f32_e32 v45, v44
	v_mul_f32_e32 v44, 0xbfb8aa3b, v41
	v_exp_f32_e32 v46, v44
	v_rcp_f32_e32 v44, v43
	v_add_f32_e32 v43, 1.0, v45
	v_rcp_f32_e32 v42, v42
	v_add_f32_e32 v45, 1.0, v46
	v_rcp_f32_e32 v43, v43
	v_rcp_f32_e32 v45, v45
	v_mov_b32_e32 v46, v38
	v_mov_b32_e32 v47, v40
	v_mov_b32_e32 v40, v39
	v_pk_mul_f32 v[42:43], v[46:47], v[42:43]
	v_mov_b32_e32 v47, v36
	v_pk_mul_f32 v[38:39], v[40:41], v[44:45]
	v_mov_b32_e32 v36, v35
	v_mov_b32_e32 v46, v34
	v_pk_mul_f32 v[34:35], v[36:37], v[38:39]
	v_pk_mul_f32 v[42:43], v[46:47], v[42:43]
	v_cvt_pk_bf16_f32 v36, v43, v35
	v_cvt_pk_bf16_f32 v37, v42, v34
	v_mov_b32_e32 v35, v36
	v_mov_b32_e32 v34, v37
	global_store_dwordx2 v[66:67], v[34:35], off offset:96
	v_mul_f32_e32 v35, 0xbfb8aa3b, v30
	v_exp_f32_e32 v36, v35
	v_mul_f32_e32 v35, 0xbfb8aa3b, v31
	v_mul_f32_e32 v38, 0xbfb8aa3b, v32
	v_exp_f32_e32 v37, v35
	v_exp_f32_e32 v39, v38
	v_mul_f32_e32 v38, 0xbfb8aa3b, v33
	v_exp_f32_e32 v40, v38
	v_add_f32_e32 v37, 1.0, v37
	v_add_f32_e32 v36, 1.0, v36
	v_rcp_f32_e32 v38, v37
	v_add_f32_e32 v37, 1.0, v39
	v_add_f32_e32 v39, 1.0, v40
	v_rcp_f32_e32 v36, v36
	v_rcp_f32_e32 v37, v37
	v_rcp_f32_e32 v39, v39
	v_mov_b32_e32 v40, v30
	v_mov_b32_e32 v41, v32
	v_mov_b32_e32 v32, v31
	v_pk_mul_f32 v[36:37], v[40:41], v[36:37]
	v_mov_b32_e32 v41, v28
	v_pk_mul_f32 v[30:31], v[32:33], v[38:39]
	v_mov_b32_e32 v28, v27
	v_mov_b32_e32 v40, v26
	v_pk_mul_f32 v[26:27], v[28:29], v[30:31]
	v_pk_mul_f32 v[36:37], v[40:41], v[36:37]
	v_cvt_pk_bf16_f32 v28, v37, v27
	v_cvt_pk_bf16_f32 v29, v36, v26
	v_mov_b32_e32 v27, v28
	v_mul_f32_e32 v28, 0xbfb8aa3b, v22
	v_mov_b32_e32 v26, v29
	v_exp_f32_e32 v28, v28
	v_mul_f32_e32 v29, 0xbfb8aa3b, v23
	v_or_b32_e32 v34, 48, v110
	v_exp_f32_e32 v29, v29
	v_mad_i64_i32 v[34:35], s[6:7], v34, s52, v[106:107]
	v_lshl_add_u64 v[34:35], v[34:35], 0, v[108:109]
	global_store_dwordx2 v[34:35], v[26:27], off
	v_add_f32_e32 v26, 1.0, v28
	v_mul_f32_e32 v28, 0xbfb8aa3b, v24
	v_add_f32_e32 v27, 1.0, v29
	v_exp_f32_e32 v29, v28
	v_mul_f32_e32 v28, 0xbfb8aa3b, v25
	v_exp_f32_e32 v30, v28
	v_rcp_f32_e32 v28, v27
	v_add_f32_e32 v27, 1.0, v29
	v_rcp_f32_e32 v26, v26
	v_add_f32_e32 v29, 1.0, v30
	v_rcp_f32_e32 v27, v27
	v_rcp_f32_e32 v29, v29
	v_mov_b32_e32 v30, v22
	v_mov_b32_e32 v31, v24
	v_mov_b32_e32 v24, v23
	v_pk_mul_f32 v[26:27], v[30:31], v[26:27]
	v_mov_b32_e32 v31, v20
	v_pk_mul_f32 v[22:23], v[24:25], v[28:29]
	v_mov_b32_e32 v20, v19
	v_mov_b32_e32 v30, v18
	v_pk_mul_f32 v[18:19], v[20:21], v[22:23]
	v_pk_mul_f32 v[26:27], v[30:31], v[26:27]
	v_cvt_pk_bf16_f32 v20, v27, v19
	v_cvt_pk_bf16_f32 v21, v26, v18
	v_mov_b32_e32 v19, v20
	v_mul_f32_e32 v20, 0xbfb8aa3b, v14
	v_mov_b32_e32 v18, v21
	v_exp_f32_e32 v20, v20
	v_mul_f32_e32 v21, 0xbfb8aa3b, v15
	v_exp_f32_e32 v21, v21
	global_store_dwordx2 v[34:35], v[18:19], off offset:32
	v_add_f32_e32 v18, 1.0, v20
	v_mul_f32_e32 v20, 0xbfb8aa3b, v16
	v_add_f32_e32 v19, 1.0, v21
	v_exp_f32_e32 v21, v20
	v_mul_f32_e32 v20, 0xbfb8aa3b, v17
	v_exp_f32_e32 v22, v20
	v_rcp_f32_e32 v20, v19
	v_add_f32_e32 v19, 1.0, v21
	v_rcp_f32_e32 v18, v18
	v_add_f32_e32 v21, 1.0, v22
	v_rcp_f32_e32 v19, v19
	v_rcp_f32_e32 v21, v21
	v_mov_b32_e32 v22, v14
	v_mov_b32_e32 v23, v16
	v_mov_b32_e32 v16, v15
	v_pk_mul_f32 v[18:19], v[22:23], v[18:19]
	v_mov_b32_e32 v23, v12
	v_pk_mul_f32 v[14:15], v[16:17], v[20:21]
	v_mov_b32_e32 v12, v11
	v_mov_b32_e32 v22, v10
	v_pk_mul_f32 v[10:11], v[12:13], v[14:15]
	v_pk_mul_f32 v[18:19], v[22:23], v[18:19]
	v_cvt_pk_bf16_f32 v12, v19, v11
	v_cvt_pk_bf16_f32 v13, v18, v10
	v_mov_b32_e32 v11, v12
	v_mul_f32_e32 v12, 0xbfb8aa3b, v6
	v_mov_b32_e32 v10, v13
	v_exp_f32_e32 v12, v12
	v_mul_f32_e32 v13, 0xbfb8aa3b, v7
	v_exp_f32_e32 v13, v13
	global_store_dwordx2 v[34:35], v[10:11], off offset:64
	v_add_f32_e32 v10, 1.0, v12
	v_mul_f32_e32 v12, 0xbfb8aa3b, v8
	v_add_f32_e32 v11, 1.0, v13
	v_exp_f32_e32 v13, v12
	v_mul_f32_e32 v12, 0xbfb8aa3b, v9
	v_exp_f32_e32 v14, v12
	v_rcp_f32_e32 v12, v11
	v_add_f32_e32 v11, 1.0, v13
	v_rcp_f32_e32 v10, v10
	v_add_f32_e32 v13, 1.0, v14
	v_rcp_f32_e32 v11, v11
	v_rcp_f32_e32 v13, v13
	v_mov_b32_e32 v14, v6
	v_mov_b32_e32 v15, v8
	v_mov_b32_e32 v8, v7
	v_pk_mul_f32 v[10:11], v[14:15], v[10:11]
	v_mov_b32_e32 v15, v4
	v_pk_mul_f32 v[6:7], v[8:9], v[12:13]
	v_mov_b32_e32 v4, v3
	v_mov_b32_e32 v14, v2
	v_pk_mul_f32 v[2:3], v[4:5], v[6:7]
	v_pk_mul_f32 v[10:11], v[14:15], v[10:11]
	v_cvt_pk_bf16_f32 v4, v11, v3
	v_cvt_pk_bf16_f32 v5, v10, v2
	s_add_i32 s14, s14, s11
	v_mov_b32_e32 v3, v4
	v_mov_b32_e32 v2, v5
	s_cmpk_gt_i32 s14, 0x5ff
	global_store_dwordx2 v[34:35], v[2:3], off offset:96
	s_cbranch_scc0 .LBB0_1461

.LBB0_1470:
	s_add_i32 s2, s17, 4
	s_min_u32 s2, s2, 15
	s_lshl_b32 s4, s2, 7
	v_lshl_add_u64 v[74:75], v[54:55], 0, s[4:5]
	v_add_co_u32_e32 v78, vcc, s34, v74
	v_lshl_add_u64 v[82:83], v[56:57], 0, s[4:5]
	s_nop 0
	v_addc_co_u32_e32 v79, vcc, 0, v75, vcc
	v_add_co_u32_e32 v86, vcc, s34, v82
	global_load_dwordx4 v[74:77], v[74:75], off
	s_nop 0
	global_load_dwordx4 v[78:81], v[78:79], off
	v_addc_co_u32_e32 v87, vcc, 0, v83, vcc
	global_load_dwordx4 v[82:85], v[82:83], off
	s_nop 0
	global_load_dwordx4 v[86:89], v[86:87], off
	v_add_u32_e32 v73, v61, v64
	ds_read_b128 v[90:93], v65
	ds_read_b128 v[94:97], v65 offset:2304
	ds_read_b128 v[98:101], v73 offset:36864
	ds_read_b128 v[102:105], v73 offset:39168
	ds_read_b128 v[106:109], v73 offset:41472
	ds_read_b128 v[110:113], v73 offset:43776
	s_add_i32 s17, s17, 2
	s_waitcnt lgkmcnt(3)
	v_mfma_f32_16x16x32_bf16 v[42:45], v[98:101], v[90:93], v[42:45]
	s_waitcnt lgkmcnt(2)
	v_mfma_f32_16x16x32_bf16 v[46:49], v[102:105], v[90:93], v[46:49]
	s_waitcnt lgkmcnt(1)
	v_mfma_f32_16x16x32_bf16 v[34:37], v[106:109], v[90:93], v[34:37]
	s_waitcnt lgkmcnt(0)
	v_mfma_f32_16x16x32_bf16 v[38:41], v[110:113], v[90:93], v[38:41]
	v_mfma_f32_16x16x32_bf16 v[10:13], v[98:101], v[94:97], v[10:13]
	ds_read_b128 v[90:93], v65 offset:64
	ds_read_b128 v[98:101], v65 offset:2368
	v_mfma_f32_16x16x32_bf16 v[14:17], v[102:105], v[94:97], v[14:17]
	v_mfma_f32_16x16x32_bf16 v[2:5], v[106:109], v[94:97], v[2:5]
	ds_read_b128 v[102:105], v73 offset:36928
	ds_read_b128 v[106:109], v73 offset:39232
	ds_read_b128 v[114:117], v73 offset:41536
	ds_read_b128 v[118:121], v73 offset:43840
	v_mfma_f32_16x16x32_bf16 v[6:9], v[110:113], v[94:97], v[6:9]
	s_waitcnt lgkmcnt(3)
	v_mfma_f32_16x16x32_bf16 v[42:45], v[102:105], v[90:93], v[42:45]
	s_waitcnt vmcnt(7)
	ds_write_b128 v72, v[18:21] offset:55296
	s_waitcnt vmcnt(6)
	ds_write_b128 v72, v[22:25] offset:64512
	s_waitcnt vmcnt(5)
	ds_write_b128 v66, v[26:29]
	s_waitcnt vmcnt(4)
	ds_write_b128 v66, v[30:33] offset:9216
	s_waitcnt lgkmcnt(6)
	v_mfma_f32_16x16x32_bf16 v[46:49], v[106:109], v[90:93], v[46:49]
	s_waitcnt lgkmcnt(5)
	v_mfma_f32_16x16x32_bf16 v[34:37], v[114:117], v[90:93], v[34:37]
	s_waitcnt lgkmcnt(4)
	v_mfma_f32_16x16x32_bf16 v[38:41], v[118:121], v[90:93], v[38:41]
	v_mfma_f32_16x16x32_bf16 v[10:13], v[102:105], v[98:101], v[10:13]
	v_mfma_f32_16x16x32_bf16 v[14:17], v[106:109], v[98:101], v[14:17]
	v_mfma_f32_16x16x32_bf16 v[2:5], v[114:117], v[98:101], v[2:5]
	v_mfma_f32_16x16x32_bf16 v[6:9], v[118:121], v[98:101], v[6:9]
	s_min_u32 s2, s17, 12
	s_lshl_b32 s4, s2, 7
	v_lshl_add_u64 v[18:19], v[54:55], 0, s[4:5]
	v_add_co_u32_e32 v22, vcc, s34, v18
	v_lshl_add_u64 v[26:27], v[56:57], 0, s[4:5]
	s_nop 0
	v_addc_co_u32_e32 v23, vcc, 0, v19, vcc
	v_add_co_u32_e32 v30, vcc, s34, v26
	s_waitcnt lgkmcnt(0)
	s_barrier
	global_load_dwordx4 v[18:21], v[18:19], off offset:384
	s_nop 0
	global_load_dwordx4 v[22:25], v[22:23], off offset:384
	v_addc_co_u32_e32 v31, vcc, 0, v27, vcc
	global_load_dwordx4 v[26:29], v[26:27], off offset:384
	s_nop 0
	global_load_dwordx4 v[30:33], v[30:31], off offset:384
	ds_read_b128 v[90:93], v65 offset:55296
	ds_read_b128 v[94:97], v65 offset:57600
	ds_read_b128 v[98:101], v67
	ds_read_b128 v[102:105], v67 offset:2304
	ds_read_b128 v[106:109], v67 offset:4608
	ds_read_b128 v[110:113], v67 offset:6912
	s_waitcnt lgkmcnt(3)
	v_mfma_f32_16x16x32_bf16 v[42:45], v[98:101], v[90:93], v[42:45]
	s_waitcnt lgkmcnt(2)
	v_mfma_f32_16x16x32_bf16 v[46:49], v[102:105], v[90:93], v[46:49]
	s_waitcnt lgkmcnt(1)
	v_mfma_f32_16x16x32_bf16 v[34:37], v[106:109], v[90:93], v[34:37]
	s_waitcnt lgkmcnt(0)
	v_mfma_f32_16x16x32_bf16 v[38:41], v[110:113], v[90:93], v[38:41]
	v_mfma_f32_16x16x32_bf16 v[10:13], v[98:101], v[94:97], v[10:13]
	ds_read_b128 v[90:93], v65 offset:55360
	ds_read_b128 v[98:101], v65 offset:57664
	v_mfma_f32_16x16x32_bf16 v[14:17], v[102:105], v[94:97], v[14:17]
	v_mfma_f32_16x16x32_bf16 v[2:5], v[106:109], v[94:97], v[2:5]
	ds_read_b128 v[102:105], v68 offset:64
	ds_read_b128 v[106:109], v69 offset:64
	ds_read_b128 v[114:117], v70 offset:64
	ds_read_b128 v[118:121], v71 offset:64
	v_mfma_f32_16x16x32_bf16 v[6:9], v[110:113], v[94:97], v[6:9]
	s_waitcnt lgkmcnt(3)
	v_mfma_f32_16x16x32_bf16 v[42:45], v[102:105], v[90:93], v[42:45]
	s_waitcnt vmcnt(7)
	ds_write_b128 v72, v[74:77]
	s_waitcnt vmcnt(6)
	ds_write_b128 v72, v[78:81] offset:9216
	s_waitcnt vmcnt(5)
	ds_write_b128 v72, v[82:85] offset:36864
	s_waitcnt vmcnt(4)
	ds_write_b128 v72, v[86:89] offset:46080
	s_waitcnt lgkmcnt(6)
	v_mfma_f32_16x16x32_bf16 v[46:49], v[106:109], v[90:93], v[46:49]
	s_waitcnt lgkmcnt(5)
	v_mfma_f32_16x16x32_bf16 v[34:37], v[114:117], v[90:93], v[34:37]
	s_waitcnt lgkmcnt(4)
	v_mfma_f32_16x16x32_bf16 v[38:41], v[118:121], v[90:93], v[38:41]
	v_mfma_f32_16x16x32_bf16 v[10:13], v[102:105], v[98:101], v[10:13]
	v_mfma_f32_16x16x32_bf16 v[14:17], v[106:109], v[98:101], v[14:17]
	v_mfma_f32_16x16x32_bf16 v[2:5], v[114:117], v[98:101], v[2:5]
	v_mfma_f32_16x16x32_bf16 v[6:9], v[118:121], v[98:101], v[6:9]
	s_waitcnt lgkmcnt(0)
	s_barrier
	s_cmp_gt_u32 s17, 13
	s_cbranch_scc0 .LBB0_1470
	s_waitcnt vmcnt(3)
	v_mul_f32_e32 v19, 0xbfb8aa3b, v42
	v_exp_f32_e32 v19, v19
	s_waitcnt vmcnt(2)
	v_mul_f32_e32 v22, 0xbfb8aa3b, v43
	v_exp_f32_e32 v25, v22
	s_waitcnt vmcnt(1)
	v_mul_f32_e32 v26, 0xbfb8aa3b, v45
	v_add_f32_e32 v19, 1.0, v19
	v_rcp_f32_e32 v24, v19
	v_add_f32_e32 v19, 1.0, v25
	v_mul_f32_e32 v25, 0xbfb8aa3b, v44
	v_exp_f32_e32 v25, v25
	v_exp_f32_e32 v27, v26
	v_rcp_f32_e32 v26, v19
	v_mov_b32_e32 v28, v42
	v_add_f32_e32 v19, 1.0, v25
	v_rcp_f32_e32 v25, v19
	v_add_f32_e32 v19, 1.0, v27
	v_rcp_f32_e32 v27, v19
	v_mov_b32_e32 v29, v44
	v_pk_mul_f32 v[24:25], v[28:29], v[24:25]
	v_mov_b32_e32 v28, v46
	v_mov_b32_e32 v29, v48
	v_mov_b32_e32 v44, v43
	v_pk_mul_f32 v[24:25], v[28:29], v[24:25]
	v_pk_mul_f32 v[26:27], v[44:45], v[26:27]
	v_mov_b32_e32 v48, v47
	v_pk_mul_f32 v[26:27], v[48:49], v[26:27]
	v_cvt_pk_bf16_f32 v24, v24, v26
	v_cvt_pk_bf16_f32 v25, v25, v27
	v_or_b32_e32 v18, s15, v58
	v_ashrrev_i32_e32 v18, 1, v18
	v_mul_f32_e32 v26, 0xbfb8aa3b, v34
	v_or_b32_e32 v18, v18, v62
	v_exp_f32_e32 v26, v26
	v_mul_f32_e32 v27, 0xbfb8aa3b, v35
	s_waitcnt vmcnt(0)
	v_add_u32_e32 v30, s14, v60
	v_mov_b64_e32 v[20:21], s[12:13]
	v_ashrrev_i32_e32 v19, 31, v18
	v_exp_f32_e32 v27, v27
	v_mad_i64_i32 v[22:23], s[14:15], v30, s52, v[20:21]
	v_lshlrev_b64 v[18:19], 1, v[18:19]
	v_lshl_add_u64 v[22:23], v[22:23], 0, v[18:19]
	s_waitcnt vmcnt(0)
	global_store_dwordx2 v[22:23], v[24:25], off
	v_add_f32_e32 v24, 1.0, v26
	v_mul_f32_e32 v26, 0xbfb8aa3b, v36
	v_add_f32_e32 v25, 1.0, v27
	v_exp_f32_e32 v27, v26
	v_mul_f32_e32 v26, 0xbfb8aa3b, v37
	v_exp_f32_e32 v28, v26
	v_rcp_f32_e32 v26, v25
	v_add_f32_e32 v25, 1.0, v27
	v_rcp_f32_e32 v24, v24
	v_rcp_f32_e32 v25, v25
	v_add_f32_e32 v27, 1.0, v28
	v_rcp_f32_e32 v27, v27
	v_mov_b32_e32 v28, v34
	v_mov_b32_e32 v29, v36
	v_pk_mul_f32 v[24:25], v[28:29], v[24:25]
	v_mov_b32_e32 v28, v38
	v_mov_b32_e32 v29, v40
	v_mov_b32_e32 v36, v35
	v_pk_mul_f32 v[24:25], v[28:29], v[24:25]
	v_pk_mul_f32 v[26:27], v[36:37], v[26:27]
	v_mov_b32_e32 v40, v39
	v_pk_mul_f32 v[26:27], v[40:41], v[26:27]
	v_and_b32_sdwa v28, v25, v177 dst_sel:DWORD dst_unused:UNUSED_PAD src0_sel:WORD_1 src1_sel:DWORD
	v_and_b32_sdwa v29, v24, v177 dst_sel:DWORD dst_unused:UNUSED_PAD src0_sel:WORD_1 src1_sel:DWORD
	v_add3_u32 v24, v24, v29, s28
	v_add3_u32 v25, v25, v28, s28
	v_and_b32_sdwa v28, v27, v177 dst_sel:DWORD dst_unused:UNUSED_PAD src0_sel:WORD_1 src1_sel:DWORD
	v_and_b32_sdwa v29, v26, v177 dst_sel:DWORD dst_unused:UNUSED_PAD src0_sel:WORD_1 src1_sel:DWORD
	v_add3_u32 v27, v27, v28, s28
	v_add3_u32 v26, v26, v29, s28
	v_and_b32_e32 v27, 0xffff0000, v27
	v_and_b32_e32 v26, 0xffff0000, v26
	v_or_b32_sdwa v25, v27, v25 dst_sel:DWORD dst_unused:UNUSED_PAD src0_sel:DWORD src1_sel:WORD_1
	v_or_b32_sdwa v24, v26, v24 dst_sel:DWORD dst_unused:UNUSED_PAD src0_sel:DWORD src1_sel:WORD_1
	global_store_dwordx2 v[22:23], v[24:25], off offset:32
	v_mul_f32_e32 v23, 0xbfb8aa3b, v10
	v_mul_f32_e32 v24, 0xbfb8aa3b, v11
	v_exp_f32_e32 v23, v23
	v_exp_f32_e32 v24, v24
	v_or_b32_e32 v22, 16, v30
	v_mad_i64_i32 v[20:21], s[14:15], v22, s52, v[20:21]
	v_add_f32_e32 v22, 1.0, v23
	v_add_f32_e32 v23, 1.0, v24
	v_mul_f32_e32 v24, 0xbfb8aa3b, v12
	v_exp_f32_e32 v25, v24
	v_mul_f32_e32 v24, 0xbfb8aa3b, v13
	v_exp_f32_e32 v26, v24
	v_rcp_f32_e32 v24, v23
	v_add_f32_e32 v23, 1.0, v25
	v_rcp_f32_e32 v22, v22
	v_add_f32_e32 v25, 1.0, v26
	v_rcp_f32_e32 v23, v23
	v_rcp_f32_e32 v25, v25
	v_lshl_add_u64 v[18:19], v[20:21], 0, v[18:19]
	v_mov_b32_e32 v20, v10
	v_mov_b32_e32 v21, v12
	v_mov_b32_e32 v12, v11
	v_pk_mul_f32 v[20:21], v[20:21], v[22:23]
	v_mov_b32_e32 v23, v16
	v_pk_mul_f32 v[10:11], v[12:13], v[24:25]
	v_mov_b32_e32 v16, v15
	v_mov_b32_e32 v22, v14
	v_pk_mul_f32 v[10:11], v[16:17], v[10:11]
	v_pk_mul_f32 v[20:21], v[22:23], v[20:21]
	v_cvt_pk_bf16_f32 v12, v21, v11
	v_cvt_pk_bf16_f32 v13, v20, v10
	v_mov_b32_e32 v11, v12
	v_mul_f32_e32 v12, 0xbfb8aa3b, v2
	v_mov_b32_e32 v10, v13
	v_exp_f32_e32 v12, v12
	v_mul_f32_e32 v13, 0xbfb8aa3b, v3
	v_exp_f32_e32 v13, v13
	global_store_dwordx2 v[18:19], v[10:11], off
	v_add_f32_e32 v10, 1.0, v12
	v_mul_f32_e32 v12, 0xbfb8aa3b, v4
	v_add_f32_e32 v11, 1.0, v13
	v_exp_f32_e32 v13, v12
	v_mul_f32_e32 v12, 0xbfb8aa3b, v5
	v_exp_f32_e32 v14, v12
	v_rcp_f32_e32 v12, v11
	v_add_f32_e32 v11, 1.0, v13
	v_rcp_f32_e32 v10, v10
	v_add_f32_e32 v13, 1.0, v14
	v_rcp_f32_e32 v11, v11
	v_rcp_f32_e32 v13, v13
	v_mov_b32_e32 v14, v2
	v_mov_b32_e32 v15, v4
	v_mov_b32_e32 v4, v3
	v_pk_mul_f32 v[10:11], v[14:15], v[10:11]
	v_mov_b32_e32 v15, v8
	v_pk_mul_f32 v[2:3], v[4:5], v[12:13]
	v_mov_b32_e32 v8, v7
	v_mov_b32_e32 v14, v6
	v_pk_mul_f32 v[2:3], v[8:9], v[2:3]
	v_pk_mul_f32 v[10:11], v[14:15], v[10:11]
	v_and_b32_sdwa v6, v3, v177 dst_sel:DWORD dst_unused:UNUSED_PAD src0_sel:WORD_1 src1_sel:DWORD
	v_and_b32_sdwa v7, v2, v177 dst_sel:DWORD dst_unused:UNUSED_PAD src0_sel:WORD_1 src1_sel:DWORD
	v_and_b32_sdwa v4, v11, v177 dst_sel:DWORD dst_unused:UNUSED_PAD src0_sel:WORD_1 src1_sel:DWORD
	v_and_b32_sdwa v5, v10, v177 dst_sel:DWORD dst_unused:UNUSED_PAD src0_sel:WORD_1 src1_sel:DWORD
	v_add3_u32 v3, v3, v6, s28
	v_add3_u32 v2, v2, v7, s28
	v_add3_u32 v5, v10, v5, s28
	v_add3_u32 v4, v11, v4, s28
	v_and_b32_e32 v3, 0xffff0000, v3
	v_and_b32_e32 v2, 0xffff0000, v2
	v_or_b32_sdwa v3, v3, v4 dst_sel:DWORD dst_unused:UNUSED_PAD src0_sel:DWORD src1_sel:WORD_1
	v_or_b32_sdwa v2, v2, v5 dst_sel:DWORD dst_unused:UNUSED_PAD src0_sel:DWORD src1_sel:WORD_1
	s_mov_b32 s4, 0
	global_store_dwordx2 v[18:19], v[2:3], off offset:32
	s_branch .LBB0_1465
